# dn_chunk: solved rows stored two per global_store_dword (DPP neighbour exchange + v_perm), 32 instead of 64 stores
# baseline (speedup 1.0000x reference)
.LBB0_1308:
	v_mov_b32_e32 v25, s16
	v_and_b32_e32 v24, 64, v86
	v_cmp_eq_u32_e64 s[2:3], 0, v24
	v_mov_b32_e32 v24, s17
	s_movk_i32 s4, 0x80
	v_cndmask_b32_e64 v24, v24, v25, s[2:3]
	v_lshlrev_b32_e32 v25, 1, v86
	v_cmp_gt_u32_e32 vcc, s4, v86
	v_and_b32_e32 v26, 0xffffff00, v25
	v_readlane_b32 s4, v253, 26
	v_add_u32_e32 v84, v24, v26
	v_mov_b32_e32 v26, s15
	v_mov_b32_e32 v24, s4
	v_cndmask_b32_e32 v92, v24, v26, vcc
	v_mov_b32_e32 v24, s33
	v_mov_b32_e32 v26, s14
	v_cndmask_b32_e64 v24, v24, v26, s[2:3]
	v_cndmask_b32_e64 v26, v196, 0, vcc
	v_and_b32_e32 v128, 0x7e, v25
	v_add3_u32 v40, v24, v26, v128
	v_cndmask_b32_e32 v97, v197, v198, vcc
	v_add_u32_e32 v44, v40, v97
	ds_read_b128 v[36:39], v84
	ds_read_b128 v[32:35], v84 offset:16
	ds_read_b128 v[28:31], v84 offset:32
	ds_read_b128 v[24:27], v84 offset:48
	ds_read_u16 v40, v40
	s_brev_b32 s4, 1
	s_waitcnt lgkmcnt(0)
	v_lshlrev_b32_e32 v40, 16, v40
	v_fma_f32 v89, v36, v40, 0
	v_add_u32_e32 v36, v44, v97
	ds_read_b128 v[40:43], v92 offset:256
	ds_read_u16 v44, v44
	s_waitcnt lgkmcnt(1)
	v_mul_f32_e32 v40, v40, v89
	s_waitcnt lgkmcnt(0)
	v_lshlrev_b32_e32 v44, 16, v44
	v_fma_f32 v43, v43, s4, 0
	v_fma_f32 v42, v42, s4, 0
	v_fma_f32 v41, v41, s4, 0
	v_fma_f32 v37, v37, v44, -v40
	v_add_f32_e32 v37, v41, v37
	v_add_f32_e32 v40, v42, v43
	v_add_f32_e32 v90, v40, v37
	v_add_u32_e32 v37, v36, v97
	ds_read_b128 v[40:43], v92 offset:512
	ds_read_u16 v36, v36
	v_add_u32_e32 v44, v37, v97
	ds_read_u16 v37, v37
	v_add_u32_e32 v45, v44, v97
	s_waitcnt lgkmcnt(2)
	v_mul_f32_e32 v40, v40, v89
	s_waitcnt lgkmcnt(1)
	v_lshlrev_b32_e32 v36, 16, v36
	v_fma_f32 v43, v43, s4, 0
	v_fma_f32 v42, v42, s4, 0
	v_fma_f32 v41, -v41, v90, 0
	v_fma_f32 v36, v38, v36, -v40
	v_add_f32_e32 v36, v36, v41
	v_add_f32_e32 v38, v42, v43
	ds_read_b128 v[40:43], v92 offset:768
	v_add_f32_e32 v91, v38, v36
	s_waitcnt lgkmcnt(1)
	v_lshlrev_b32_e32 v37, 16, v37
	s_waitcnt lgkmcnt(0)
	v_mul_f32_e32 v40, v89, v40
	v_fma_f32 v36, v43, s4, 0
	v_fma_f32 v38, -v42, v91, 0
	v_fma_f32 v41, -v41, v90, 0
	v_fma_f32 v37, v39, v37, -v40
	v_add_f32_e32 v37, v41, v37
	v_add_f32_e32 v36, v36, v38
	v_add_f32_e32 v93, v37, v36
	ds_read_b128 v[36:39], v92 offset:1024
	ds_read_u16 v40, v44
	s_waitcnt lgkmcnt(1)
	v_mul_f32_e32 v36, v89, v36
	s_waitcnt lgkmcnt(0)
	v_lshlrev_b32_e32 v40, 16, v40
	v_fma_f32 v39, -v39, v93, 0
	v_fma_f32 v38, -v38, v91, 0
	v_fma_f32 v37, -v90, v37, 0
	v_fma_f32 v32, v32, v40, -v36
	v_add_f32_e32 v32, v37, v32
	v_add_f32_e32 v36, v38, v39
	v_add_f32_e32 v94, v32, v36
	ds_read_b128 v[36:39], v92 offset:1280
	ds_read_b128 v[40:43], v92 offset:1296
	v_add_u32_e32 v32, v45, v97
	s_waitcnt lgkmcnt(1)
	v_fma_f32 v37, -v90, v37, 0
	s_waitcnt lgkmcnt(0)
	v_fmac_f32_e32 v37, 0x80000000, v41
	ds_read_u16 v41, v45
	v_mul_f32_e32 v36, v89, v36
	v_fma_f32 v39, -v39, v93, 0
	v_fma_f32 v38, -v38, v91, 0
	v_fmac_f32_e32 v39, 0x80000000, v43
	s_waitcnt lgkmcnt(0)
	v_lshlrev_b32_e32 v41, 16, v41
	v_fma_f32 v33, v33, v41, -v36
	v_fmac_f32_e32 v38, 0x80000000, v42
	v_fma_f32 v33, -v40, v94, v33
	v_add_f32_e32 v33, v37, v33
	v_add_f32_e32 v36, v38, v39
	v_add_f32_e32 v95, v36, v33
	v_add_u32_e32 v33, v32, v97
	ds_read_b128 v[36:39], v92 offset:1536
	ds_read_u16 v32, v32
	ds_read_b128 v[40:43], v92 offset:1552
	v_add_u32_e32 v44, v33, v97
	ds_read_u16 v33, v33
	s_waitcnt lgkmcnt(3)
	v_mul_f32_e32 v36, v89, v36
	s_waitcnt lgkmcnt(2)
	v_lshlrev_b32_e32 v32, 16, v32
	v_fma_f32 v39, -v39, v93, 0
	v_fma_f32 v38, -v91, v38, 0
	v_fma_f32 v37, -v90, v37, 0
	v_fma_f32 v32, v34, v32, -v36
	s_waitcnt lgkmcnt(1)
	v_fmac_f32_e32 v39, 0x80000000, v43
	v_fmac_f32_e32 v38, 0x80000000, v42
	v_fma_f32 v37, -v41, v95, v37
	v_fma_f32 v32, -v40, v94, v32
	v_add_f32_e32 v32, v32, v37
	v_add_f32_e32 v34, v38, v39
	ds_read_b128 v[36:39], v92 offset:1792
	ds_read_b128 v[40:43], v92 offset:1808
	s_waitcnt lgkmcnt(2)
	v_lshlrev_b32_e32 v33, 16, v33
	v_add_f32_e32 v96, v34, v32
	v_add_u32_e32 v45, v44, v97
	s_waitcnt lgkmcnt(1)
	v_mul_f32_e32 v36, v89, v36
	v_fma_f32 v32, -v93, v39, 0
	v_fma_f32 v34, -v91, v38, 0
	v_fma_f32 v37, -v90, v37, 0
	v_fma_f32 v33, v35, v33, -v36
	s_waitcnt lgkmcnt(0)
	v_fmac_f32_e32 v32, 0x80000000, v43
	v_fma_f32 v34, -v42, v96, v34
	v_fma_f32 v37, -v41, v95, v37
	v_fma_f32 v33, -v94, v40, v33
	v_add_f32_e32 v33, v37, v33
	v_add_f32_e32 v32, v32, v34
	v_add_f32_e32 v98, v33, v32
	ds_read_b128 v[32:35], v92 offset:2048
	ds_read_b128 v[36:39], v92 offset:2064
	ds_read_b128 v[40:43], v92 offset:2336
	s_waitcnt lgkmcnt(2)
	v_fma_f32 v33, -v90, v33, 0
	s_waitcnt lgkmcnt(1)
	v_fma_f32 v33, -v95, v37, v33
	ds_read_u16 v37, v44
	v_mul_f32_e32 v32, v89, v32
	v_fma_f32 v35, -v93, v35, 0
	v_fma_f32 v34, -v91, v34, 0
	v_fma_f32 v35, -v39, v98, v35
	s_waitcnt lgkmcnt(0)
	v_lshlrev_b32_e32 v37, 16, v37
	v_fma_f32 v28, v28, v37, -v32
	v_fma_f32 v34, -v38, v96, v34
	v_fma_f32 v28, -v94, v36, v28
	v_add_f32_e32 v28, v33, v28
	v_add_f32_e32 v32, v34, v35
	v_add_f32_e32 v99, v28, v32
	ds_read_b128 v[32:35], v92 offset:2304
	ds_read_b128 v[36:39], v92 offset:2320
	v_add_u32_e32 v28, v45, v97
	s_waitcnt lgkmcnt(1)
	v_fma_f32 v33, -v90, v33, 0
	s_waitcnt lgkmcnt(0)
	v_fma_f32 v33, -v95, v37, v33
	ds_read_u16 v37, v45
	v_mul_f32_e32 v32, v89, v32
	v_fma_f32 v35, -v93, v35, 0
	v_fma_f32 v34, -v91, v34, 0
	v_fma_f32 v35, -v39, v98, v35
	s_waitcnt lgkmcnt(0)
	v_lshlrev_b32_e32 v37, 16, v37
	v_fma_f32 v29, v29, v37, -v32
	v_fma_f32 v34, -v96, v38, v34
	v_fma_f32 v29, -v94, v36, v29
	v_fmac_f32_e32 v35, 0x80000000, v43
	v_fmac_f32_e32 v34, 0x80000000, v42
	v_fmac_f32_e32 v33, 0x80000000, v41
	v_fma_f32 v29, -v40, v99, v29
	v_add_f32_e32 v29, v33, v29
	v_add_f32_e32 v32, v34, v35
	v_add_f32_e32 v100, v32, v29
	v_add_u32_e32 v29, v28, v97
	ds_read_b128 v[32:35], v92 offset:2560
	ds_read_u16 v28, v28
	ds_read_b128 v[36:39], v92 offset:2576
	ds_read_b128 v[40:43], v92 offset:2592
	v_add_u32_e32 v44, v29, v97
	s_waitcnt lgkmcnt(3)
	v_mul_f32_e32 v32, v89, v32
	s_waitcnt lgkmcnt(2)
	v_lshlrev_b32_e32 v28, 16, v28
	v_fma_f32 v35, -v93, v35, 0
	v_fma_f32 v34, -v91, v34, 0
	v_fma_f32 v33, -v90, v33, 0
	v_fma_f32 v28, v30, v28, -v32
	s_waitcnt lgkmcnt(1)
	v_fma_f32 v35, -v98, v39, v35
	v_fma_f32 v34, -v96, v38, v34
	v_fma_f32 v33, -v95, v37, v33
	v_fma_f32 v28, -v94, v36, v28
	s_waitcnt lgkmcnt(0)
	v_fmac_f32_e32 v35, 0x80000000, v43
	v_fmac_f32_e32 v34, 0x80000000, v42
	v_fma_f32 v33, -v41, v100, v33
	v_fma_f32 v28, -v40, v99, v28
	v_add_f32_e32 v28, v33, v28
	v_add_f32_e32 v30, v34, v35
	ds_read_b128 v[32:35], v92 offset:2816
	ds_read_u16 v29, v29
	ds_read_b128 v[36:39], v92 offset:2832
	ds_read_b128 v[40:43], v92 offset:2848
	v_add_f32_e32 v101, v30, v28
	s_waitcnt lgkmcnt(3)
	v_mul_f32_e32 v32, v89, v32
	s_waitcnt lgkmcnt(2)
	v_lshlrev_b32_e32 v29, 16, v29
	v_fma_f32 v28, -v93, v35, 0
	v_fma_f32 v30, -v91, v34, 0
	v_fma_f32 v33, -v90, v33, 0
	v_fma_f32 v29, v31, v29, -v32
	s_waitcnt lgkmcnt(1)
	v_fma_f32 v28, -v98, v39, v28
	v_fma_f32 v30, -v96, v38, v30
	v_fma_f32 v33, -v95, v37, v33
	v_fma_f32 v29, -v94, v36, v29
	s_waitcnt lgkmcnt(0)
	v_fmac_f32_e32 v28, 0x80000000, v43
	v_fma_f32 v30, -v42, v101, v30
	v_fma_f32 v33, -v41, v100, v33
	v_fma_f32 v29, -v99, v40, v29
	v_add_f32_e32 v29, v33, v29
	v_add_f32_e32 v28, v28, v30
	v_add_f32_e32 v102, v28, v29
	ds_read_b128 v[28:31], v92 offset:3072
	ds_read_b128 v[32:35], v92 offset:3088
	ds_read_b128 v[36:39], v92 offset:3104
	v_add_u32_e32 v45, v44, v97
	ds_read_b128 v[40:43], v92 offset:3376
	s_waitcnt lgkmcnt(3)
	v_fma_f32 v29, -v90, v29, 0
	s_waitcnt lgkmcnt(2)
	v_fma_f32 v29, -v95, v33, v29
	ds_read_u16 v33, v44
	v_mul_f32_e32 v28, v89, v28
	v_fma_f32 v31, -v93, v31, 0
	v_fma_f32 v30, -v91, v30, 0
	v_fma_f32 v31, -v98, v35, v31
	s_waitcnt lgkmcnt(0)
	v_lshlrev_b32_e32 v33, 16, v33
	v_fma_f32 v24, v24, v33, -v28
	v_fma_f32 v30, -v96, v34, v30
	v_fma_f32 v24, -v94, v32, v24
	v_fma_f32 v31, -v39, v102, v31
	v_fma_f32 v30, -v38, v101, v30
	v_fma_f32 v29, -v100, v37, v29
	v_fma_f32 v24, -v99, v36, v24
	v_add_f32_e32 v24, v29, v24
	v_add_f32_e32 v28, v30, v31
	v_add_f32_e32 v103, v28, v24
	ds_read_b128 v[28:31], v92 offset:3328
	ds_read_b128 v[32:35], v92 offset:3344
	ds_read_b128 v[36:39], v92 offset:3360
	v_add_u32_e32 v24, v45, v97
	s_waitcnt lgkmcnt(2)
	v_fma_f32 v29, -v90, v29, 0
	s_waitcnt lgkmcnt(1)
	v_fma_f32 v29, -v95, v33, v29
	ds_read_u16 v33, v45
	v_mul_f32_e32 v28, v89, v28
	v_fma_f32 v31, -v93, v31, 0
	v_fma_f32 v30, -v91, v30, 0
	v_fma_f32 v31, -v98, v35, v31
	s_waitcnt lgkmcnt(0)
	v_lshlrev_b32_e32 v33, 16, v33
	v_fma_f32 v25, v25, v33, -v28
	v_fma_f32 v30, -v96, v34, v30
	v_fma_f32 v25, -v94, v32, v25
	v_fma_f32 v31, -v39, v102, v31
	v_fma_f32 v30, -v101, v38, v30
	v_fma_f32 v29, -v100, v37, v29
	v_fma_f32 v25, -v99, v36, v25
	v_fmac_f32_e32 v31, 0x80000000, v43
	v_fmac_f32_e32 v30, 0x80000000, v42
	v_fmac_f32_e32 v29, 0x80000000, v41
	v_fma_f32 v25, -v40, v103, v25
	v_add_f32_e32 v25, v29, v25
	v_add_f32_e32 v28, v30, v31
	v_add_f32_e32 v104, v28, v25
	v_add_u32_e32 v25, v24, v97
	ds_read_b128 v[28:31], v92 offset:3584
	ds_read_u16 v24, v24
	ds_read_b128 v[32:35], v92 offset:3600
	ds_read_b128 v[36:39], v92 offset:3616
	ds_read_b128 v[40:43], v92 offset:3632
	s_waitcnt lgkmcnt(4)
	v_mul_f32_e32 v28, v89, v28
	s_waitcnt lgkmcnt(3)
	v_lshlrev_b32_e32 v24, 16, v24
	v_fma_f32 v31, -v93, v31, 0
	v_fma_f32 v30, -v91, v30, 0
	v_fma_f32 v29, -v90, v29, 0
	v_fma_f32 v24, v26, v24, -v28
	s_waitcnt lgkmcnt(2)
	v_fma_f32 v31, -v98, v35, v31
	v_fma_f32 v30, -v96, v34, v30
	v_fma_f32 v29, -v95, v33, v29
	v_fma_f32 v24, -v94, v32, v24
	s_waitcnt lgkmcnt(1)
	v_fma_f32 v31, -v102, v39, v31
	v_fma_f32 v30, -v101, v38, v30
	v_fma_f32 v29, -v100, v37, v29
	v_fma_f32 v24, -v99, v36, v24
	s_waitcnt lgkmcnt(0)
	v_fmac_f32_e32 v31, 0x80000000, v43
	v_fmac_f32_e32 v30, 0x80000000, v42
	v_fma_f32 v29, -v41, v104, v29
	v_fma_f32 v24, -v103, v40, v24
	v_add_f32_e32 v24, v29, v24
	v_add_f32_e32 v26, v30, v31
	v_add_u32_e32 v44, v25, v97
	ds_read_b128 v[28:31], v92 offset:3840
	ds_read_u16 v25, v25
	ds_read_b128 v[32:35], v92 offset:3856
	ds_read_b128 v[36:39], v92 offset:3872
	ds_read_b128 v[40:43], v92 offset:3888
	s_waitcnt lgkmcnt(4)
	v_mul_f32_e32 v28, v89, v28
	s_waitcnt lgkmcnt(3)
	v_lshlrev_b32_e32 v25, 16, v25
	v_add_f32_e32 v105, v26, v24
	v_fma_f32 v24, -v93, v31, 0
	v_fma_f32 v26, -v91, v30, 0
	v_fma_f32 v29, -v90, v29, 0
	v_fma_f32 v25, v27, v25, -v28
	s_waitcnt lgkmcnt(2)
	v_fma_f32 v24, -v98, v35, v24
	v_fma_f32 v26, -v96, v34, v26
	v_fma_f32 v29, -v95, v33, v29
	v_fma_f32 v25, -v94, v32, v25
	s_waitcnt lgkmcnt(1)
	v_fma_f32 v24, -v102, v39, v24
	v_fma_f32 v26, -v101, v38, v26
	v_fma_f32 v29, -v100, v37, v29
	v_fma_f32 v25, -v99, v36, v25
	s_waitcnt lgkmcnt(0)
	v_fmac_f32_e32 v24, 0x80000000, v43
	v_fma_f32 v26, -v42, v105, v26
	v_fma_f32 v29, -v104, v41, v29
	v_fma_f32 v25, -v103, v40, v25
	v_add_f32_e32 v25, v29, v25
	v_add_f32_e32 v24, v24, v26
	v_add_f32_e32 v106, v24, v25
	ds_read_b128 v[24:27], v92 offset:4096
	ds_read_b128 v[28:31], v92 offset:4112
	ds_read_b128 v[32:35], v92 offset:4128
	ds_read_b128 v[36:39], v92 offset:4144
	v_add_u32_e32 v50, v44, v97
	s_waitcnt lgkmcnt(3)
	v_fma_f32 v27, -v93, v27, 0
	v_fma_f32 v26, -v91, v26, 0
	s_waitcnt lgkmcnt(2)
	v_fma_f32 v27, -v98, v31, v27
	v_fma_f32 v26, -v96, v30, v26
	s_waitcnt lgkmcnt(1)
	v_fma_f32 v27, -v102, v35, v27
	v_fma_f32 v26, -v101, v34, v26
	v_fma_f32 v25, -v90, v25, 0
	s_waitcnt lgkmcnt(0)
	v_fma_f32 v27, -v39, v106, v27
	v_fma_f32 v26, -v105, v38, v26
	v_fma_f32 v25, -v95, v29, v25
	ds_read_b128 v[38:41], v84 offset:64
	ds_read_u16 v29, v44
	v_mul_f32_e32 v24, v89, v24
	v_fma_f32 v25, -v100, v33, v25
	v_fma_f32 v25, -v104, v37, v25
	ds_read_b128 v[42:45], v92 offset:4400
	ds_read_b128 v[46:49], v92 offset:4416
	s_waitcnt lgkmcnt(2)
	v_lshlrev_b32_e32 v29, 16, v29
	v_fma_f32 v24, v38, v29, -v24
	v_fma_f32 v24, -v94, v28, v24
	v_fma_f32 v24, -v99, v32, v24
	v_fma_f32 v24, -v103, v36, v24
	v_add_f32_e32 v24, v25, v24
	v_add_f32_e32 v25, v26, v27
	v_add_f32_e32 v107, v25, v24
	ds_read_b128 v[24:27], v92 offset:4352
	ds_read_b128 v[28:31], v92 offset:4368
	ds_read_b128 v[32:35], v92 offset:4384
	v_add_u32_e32 v51, v50, v97
	s_waitcnt lgkmcnt(2)
	v_fma_f32 v25, -v90, v25, 0
	s_waitcnt lgkmcnt(1)
	v_fma_f32 v25, -v95, v29, v25
	ds_read_u16 v29, v50
	v_mul_f32_e32 v24, v89, v24
	v_fma_f32 v27, -v93, v27, 0
	v_fma_f32 v26, -v91, v26, 0
	v_fma_f32 v27, -v98, v31, v27
	s_waitcnt lgkmcnt(0)
	v_lshlrev_b32_e32 v29, 16, v29
	v_fma_f32 v24, v39, v29, -v24
	v_fma_f32 v26, -v96, v30, v26
	v_fma_f32 v24, -v94, v28, v24
	v_fma_f32 v27, -v102, v35, v27
	v_fma_f32 v26, -v101, v34, v26
	v_fma_f32 v25, -v100, v33, v25
	v_fma_f32 v24, -v99, v32, v24
	v_fma_f32 v27, -v106, v45, v27
	v_fma_f32 v26, -v105, v44, v26
	v_fma_f32 v25, -v104, v43, v25
	v_fma_f32 v24, -v103, v42, v24
	v_fmac_f32_e32 v27, 0x80000000, v49
	v_fmac_f32_e32 v26, 0x80000000, v48
	v_fmac_f32_e32 v25, 0x80000000, v47
	v_fma_f32 v24, -v46, v107, v24
	v_add_f32_e32 v24, v25, v24
	v_add_f32_e32 v25, v26, v27
	v_add_f32_e32 v108, v25, v24
	ds_read_b128 v[24:27], v92 offset:4608
	ds_read_b128 v[28:31], v92 offset:4624
	ds_read_b128 v[32:35], v92 offset:4640
	ds_read_b128 v[36:39], v92 offset:4656
	ds_read_b128 v[42:45], v92 offset:4672
	s_waitcnt lgkmcnt(4)
	v_fma_f32 v25, -v90, v25, 0
	s_waitcnt lgkmcnt(3)
	v_fma_f32 v25, -v95, v29, v25
	ds_read_u16 v29, v51
	v_mul_f32_e32 v24, v89, v24
	v_fma_f32 v27, -v93, v27, 0
	v_fma_f32 v26, -v91, v26, 0
	v_fma_f32 v27, -v98, v31, v27
	s_waitcnt lgkmcnt(0)
	v_lshlrev_b32_e32 v29, 16, v29
	v_fma_f32 v24, v40, v29, -v24
	v_fma_f32 v26, -v96, v30, v26
	v_fma_f32 v24, -v94, v28, v24
	v_fma_f32 v27, -v102, v35, v27
	v_fma_f32 v26, -v101, v34, v26
	v_fma_f32 v25, -v100, v33, v25
	v_fma_f32 v24, -v99, v32, v24
	v_fma_f32 v27, -v106, v39, v27
	v_fma_f32 v26, -v105, v38, v26
	v_fma_f32 v25, -v104, v37, v25
	v_fma_f32 v24, -v103, v36, v24
	v_fmac_f32_e32 v27, 0x80000000, v45
	v_fmac_f32_e32 v26, 0x80000000, v44
	v_fma_f32 v25, -v43, v108, v25
	v_fma_f32 v24, -v107, v42, v24
	v_add_f32_e32 v24, v25, v24
	v_add_f32_e32 v25, v26, v27
	v_add_f32_e32 v109, v25, v24
	ds_read_b128 v[24:27], v92 offset:4864
	ds_read_b128 v[28:31], v92 offset:4880
	v_add_u32_e32 v46, v51, v97
	ds_read_b128 v[32:35], v92 offset:4896
	ds_read_b128 v[36:39], v92 offset:4912
	s_waitcnt lgkmcnt(3)
	v_fma_f32 v25, -v90, v25, 0
	s_waitcnt lgkmcnt(2)
	v_fma_f32 v25, -v95, v29, v25
	ds_read_u16 v29, v46
	ds_read_b128 v[42:45], v92 offset:4928
	v_mul_f32_e32 v24, v89, v24
	v_fma_f32 v27, -v93, v27, 0
	v_fma_f32 v26, -v91, v26, 0
	s_waitcnt lgkmcnt(1)
	v_lshlrev_b32_e32 v29, 16, v29
	v_fma_f32 v24, v41, v29, -v24
	v_fma_f32 v27, -v98, v31, v27
	v_fma_f32 v26, -v96, v30, v26
	v_fma_f32 v24, -v94, v28, v24
	ds_read_b128 v[28:31], v92 offset:5120
	v_fma_f32 v27, -v102, v35, v27
	v_fma_f32 v26, -v101, v34, v26
	v_fma_f32 v25, -v100, v33, v25
	v_fma_f32 v24, -v99, v32, v24
	ds_read_b128 v[32:35], v92 offset:5136
	v_fma_f32 v27, -v106, v39, v27
	v_fma_f32 v26, -v105, v38, v26
	v_fma_f32 v25, -v104, v37, v25
	v_fma_f32 v24, -v103, v36, v24
	ds_read_b128 v[36:39], v92 offset:5152
	s_waitcnt lgkmcnt(3)
	v_fmac_f32_e32 v27, 0x80000000, v45
	v_fma_f32 v26, -v44, v109, v26
	v_fma_f32 v25, -v108, v43, v25
	v_fma_f32 v24, -v107, v42, v24
	ds_read_b128 v[40:43], v92 offset:5168
	v_add_u32_e32 v49, v46, v97
	v_add_f32_e32 v24, v25, v24
	v_add_f32_e32 v25, v27, v26
	ds_read_b128 v[44:47], v92 offset:5184
	v_add_f32_e32 v110, v25, v24
	s_waitcnt lgkmcnt(4)
	v_fma_f32 v24, -v93, v31, 0
	s_waitcnt lgkmcnt(3)
	v_fma_f32 v24, -v98, v35, v24
	s_waitcnt lgkmcnt(2)
	v_fma_f32 v24, -v102, v39, v24
	s_waitcnt lgkmcnt(1)
	v_fma_f32 v24, -v106, v43, v24
	s_waitcnt lgkmcnt(0)
	v_fma_f32 v31, -v47, v110, v24
	v_fma_f32 v24, -v91, v30, 0
	v_fma_f32 v24, -v96, v34, v24
	v_fma_f32 v24, -v101, v38, v24
	v_fma_f32 v24, -v105, v42, v24
	v_fma_f32 v30, -v109, v46, v24
	v_fma_f32 v24, -v90, v29, 0
	v_fma_f32 v24, -v95, v33, v24
	v_fma_f32 v24, -v100, v37, v24
	v_fma_f32 v24, -v104, v41, v24
	v_fma_f32 v29, -v108, v45, v24
	ds_read_b128 v[24:27], v84 offset:80
	ds_read_u16 v33, v49
	v_mul_f32_e32 v28, v89, v28
	v_add_u32_e32 v48, v49, v97
	ds_read_b128 v[50:53], v92 offset:5456
	s_waitcnt lgkmcnt(1)
	v_lshlrev_b32_e32 v33, 16, v33
	v_fma_f32 v24, v24, v33, -v28
	v_fma_f32 v24, -v94, v32, v24
	v_fma_f32 v24, -v99, v36, v24
	v_fma_f32 v24, -v103, v40, v24
	v_fma_f32 v24, -v107, v44, v24
	v_add_f32_e32 v24, v29, v24
	v_add_f32_e32 v28, v30, v31
	v_add_f32_e32 v111, v28, v24
	ds_read_b128 v[28:31], v92 offset:5376
	ds_read_b128 v[32:35], v92 offset:5392
	ds_read_b128 v[36:39], v92 offset:5408
	ds_read_b128 v[40:43], v92 offset:5424
	ds_read_b128 v[44:47], v92 offset:5440
	s_waitcnt lgkmcnt(4)
	v_fma_f32 v29, -v90, v29, 0
	s_waitcnt lgkmcnt(3)
	v_fma_f32 v29, -v95, v33, v29
	ds_read_u16 v33, v48
	v_mul_f32_e32 v28, v89, v28
	v_fma_f32 v31, -v93, v31, 0
	v_fma_f32 v30, -v91, v30, 0
	v_fma_f32 v31, -v98, v35, v31
	s_waitcnt lgkmcnt(0)
	v_lshlrev_b32_e32 v33, 16, v33
	v_fma_f32 v25, v25, v33, -v28
	v_fma_f32 v30, -v96, v34, v30
	v_fma_f32 v25, -v94, v32, v25
	v_fma_f32 v31, -v102, v39, v31
	v_fma_f32 v30, -v101, v38, v30
	v_fma_f32 v29, -v100, v37, v29
	v_fma_f32 v25, -v99, v36, v25
	v_fma_f32 v31, -v106, v43, v31
	v_fma_f32 v30, -v105, v42, v30
	v_fma_f32 v29, -v104, v41, v29
	v_fma_f32 v25, -v103, v40, v25
	v_fma_f32 v31, -v110, v47, v31
	v_fma_f32 v30, -v109, v46, v30
	v_fma_f32 v29, -v108, v45, v29
	v_fma_f32 v25, -v107, v44, v25
	v_fmac_f32_e32 v31, 0x80000000, v53
	v_fmac_f32_e32 v30, 0x80000000, v52
	v_fmac_f32_e32 v29, 0x80000000, v51
	v_fma_f32 v25, -v50, v111, v25
	v_add_u32_e32 v24, v48, v97
	v_add_f32_e32 v25, v29, v25
	v_add_f32_e32 v28, v30, v31
	v_add_f32_e32 v112, v28, v25
	v_add_u32_e32 v25, v24, v97
	ds_read_b128 v[28:31], v92 offset:5632
	ds_read_u16 v24, v24
	ds_read_b128 v[32:35], v92 offset:5648
	ds_read_b128 v[36:39], v92 offset:5664
	ds_read_b128 v[40:43], v92 offset:5680
	ds_read_b128 v[44:47], v92 offset:5696
	s_waitcnt lgkmcnt(4)
	v_lshlrev_b32_e32 v24, 16, v24
	v_mul_f32_e32 v28, v89, v28
	v_fma_f32 v31, -v93, v31, 0
	ds_read_b128 v[48:51], v92 offset:5712
	v_fma_f32 v30, -v91, v30, 0
	v_fma_f32 v29, -v90, v29, 0
	v_fma_f32 v24, v26, v24, -v28
	s_waitcnt lgkmcnt(4)
	v_fma_f32 v31, -v98, v35, v31
	v_fma_f32 v30, -v96, v34, v30
	v_fma_f32 v29, -v95, v33, v29
	v_fma_f32 v24, -v94, v32, v24
	s_waitcnt lgkmcnt(3)
	v_fma_f32 v31, -v102, v39, v31
	v_fma_f32 v30, -v101, v38, v30
	v_fma_f32 v29, -v100, v37, v29
	v_fma_f32 v24, -v99, v36, v24
	s_waitcnt lgkmcnt(2)
	v_fma_f32 v31, -v106, v43, v31
	v_fma_f32 v30, -v105, v42, v30
	v_fma_f32 v29, -v104, v41, v29
	v_fma_f32 v24, -v103, v40, v24
	s_waitcnt lgkmcnt(1)
	v_fma_f32 v31, -v110, v47, v31
	v_fma_f32 v30, -v109, v46, v30
	v_fma_f32 v29, -v108, v45, v29
	v_fma_f32 v24, -v107, v44, v24
	s_waitcnt lgkmcnt(0)
	v_fmac_f32_e32 v31, 0x80000000, v51
	v_fmac_f32_e32 v30, 0x80000000, v50
	v_fma_f32 v29, -v49, v112, v29
	v_fma_f32 v24, -v111, v48, v24
	v_add_f32_e32 v24, v29, v24
	v_add_f32_e32 v26, v30, v31
	v_add_u32_e32 v52, v25, v97
	ds_read_b128 v[28:31], v92 offset:5888
	ds_read_u16 v25, v25
	ds_read_b128 v[32:35], v92 offset:5904
	ds_read_b128 v[36:39], v92 offset:5920
	ds_read_b128 v[40:43], v92 offset:5936
	ds_read_b128 v[44:47], v92 offset:5952
	s_waitcnt lgkmcnt(4)
	v_lshlrev_b32_e32 v25, 16, v25
	v_mul_f32_e32 v28, v89, v28
	v_add_f32_e32 v113, v26, v24
	v_fma_f32 v24, -v93, v31, 0
	ds_read_b128 v[48:51], v92 offset:5968
	v_fma_f32 v26, -v91, v30, 0
	v_fma_f32 v29, -v90, v29, 0
	v_fma_f32 v25, v27, v25, -v28
	s_waitcnt lgkmcnt(4)
	v_fma_f32 v24, -v98, v35, v24
	v_fma_f32 v26, -v96, v34, v26
	v_fma_f32 v29, -v95, v33, v29
	v_fma_f32 v25, -v94, v32, v25
	s_waitcnt lgkmcnt(3)
	v_fma_f32 v24, -v102, v39, v24
	v_fma_f32 v26, -v101, v38, v26
	v_fma_f32 v29, -v100, v37, v29
	v_fma_f32 v25, -v99, v36, v25
	s_waitcnt lgkmcnt(2)
	v_fma_f32 v24, -v106, v43, v24
	v_fma_f32 v26, -v105, v42, v26
	v_fma_f32 v29, -v104, v41, v29
	v_fma_f32 v25, -v103, v40, v25
	s_waitcnt lgkmcnt(1)
	v_fma_f32 v24, -v110, v47, v24
	v_fma_f32 v26, -v109, v46, v26
	v_fma_f32 v29, -v108, v45, v29
	v_fma_f32 v25, -v107, v44, v25
	s_waitcnt lgkmcnt(0)
	v_fmac_f32_e32 v24, 0x80000000, v51
	v_fma_f32 v26, -v50, v113, v26
	v_fma_f32 v29, -v112, v49, v29
	v_fma_f32 v25, -v111, v48, v25
	v_add_f32_e32 v25, v29, v25
	v_add_f32_e32 v24, v24, v26
	v_add_f32_e32 v114, v24, v25
	ds_read_b128 v[24:27], v92 offset:6144
	ds_read_b128 v[28:31], v92 offset:6160
	ds_read_b128 v[32:35], v92 offset:6176
	ds_read_b128 v[36:39], v92 offset:6192
	ds_read_b128 v[40:43], v92 offset:6208
	s_waitcnt lgkmcnt(4)
	v_fma_f32 v27, -v93, v27, 0
	ds_read_b128 v[44:47], v92 offset:6224
	v_fma_f32 v26, -v91, v26, 0
	s_waitcnt lgkmcnt(4)
	v_fma_f32 v27, -v98, v31, v27
	v_fma_f32 v26, -v96, v30, v26
	s_waitcnt lgkmcnt(3)
	v_fma_f32 v27, -v102, v35, v27
	v_fma_f32 v26, -v101, v34, v26
	s_waitcnt lgkmcnt(2)
	v_fma_f32 v27, -v106, v39, v27
	v_fma_f32 v26, -v105, v38, v26
	s_waitcnt lgkmcnt(1)
	v_fma_f32 v27, -v110, v43, v27
	v_fma_f32 v26, -v109, v42, v26
	v_fma_f32 v25, -v90, v25, 0
	s_waitcnt lgkmcnt(0)
	v_fma_f32 v27, -v47, v114, v27
	v_fma_f32 v26, -v113, v46, v26
	v_fma_f32 v25, -v95, v29, v25
	ds_read_b128 v[46:49], v84 offset:96
	ds_read_u16 v29, v52
	v_mul_f32_e32 v24, v89, v24
	v_fma_f32 v25, -v100, v33, v25
	v_fma_f32 v25, -v104, v37, v25
	v_fma_f32 v25, -v108, v41, v25
	s_waitcnt lgkmcnt(0)
	v_lshlrev_b32_e32 v29, 16, v29
	v_fma_f32 v24, v46, v29, -v24
	v_fma_f32 v24, -v94, v28, v24
	v_fma_f32 v24, -v99, v32, v24
	v_fma_f32 v24, -v103, v36, v24
	v_fma_f32 v24, -v107, v40, v24
	v_fma_f32 v25, -v112, v45, v25
	v_fma_f32 v24, -v111, v44, v24
	v_add_f32_e32 v24, v25, v24
	v_add_f32_e32 v25, v26, v27
	v_add_f32_e32 v115, v25, v24
	ds_read_b128 v[24:27], v92 offset:6400
	ds_read_b128 v[28:31], v92 offset:6416
	v_add_u32_e32 v58, v52, v97
	ds_read_b128 v[32:35], v92 offset:6432
	ds_read_b128 v[36:39], v92 offset:6448
	s_waitcnt lgkmcnt(3)
	v_fma_f32 v25, -v90, v25, 0
	s_waitcnt lgkmcnt(2)
	v_fma_f32 v25, -v95, v29, v25
	ds_read_u16 v29, v58
	ds_read_b128 v[40:43], v92 offset:6464
	v_mul_f32_e32 v24, v89, v24
	v_fma_f32 v27, -v93, v27, 0
	ds_read_b128 v[50:53], v92 offset:6480
	ds_read_b128 v[54:57], v92 offset:6496
	s_waitcnt lgkmcnt(3)
	v_lshlrev_b32_e32 v29, 16, v29
	v_fma_f32 v26, -v91, v26, 0
	v_fma_f32 v24, v47, v29, -v24
	v_fma_f32 v27, -v98, v31, v27
	v_fma_f32 v26, -v96, v30, v26
	v_fma_f32 v24, -v94, v28, v24
	v_fma_f32 v27, -v102, v35, v27
	v_fma_f32 v26, -v101, v34, v26
	v_fma_f32 v25, -v100, v33, v25
	v_fma_f32 v24, -v99, v32, v24
	v_fma_f32 v27, -v106, v39, v27
	v_fma_f32 v26, -v105, v38, v26
	v_fma_f32 v25, -v104, v37, v25
	v_fma_f32 v24, -v103, v36, v24
	s_waitcnt lgkmcnt(2)
	v_fma_f32 v27, -v110, v43, v27
	v_fma_f32 v26, -v109, v42, v26
	v_fma_f32 v25, -v108, v41, v25
	v_fma_f32 v24, -v107, v40, v24
	s_waitcnt lgkmcnt(1)
	v_fma_f32 v27, -v114, v53, v27
	v_fma_f32 v26, -v113, v52, v26
	v_fma_f32 v25, -v112, v51, v25
	v_fma_f32 v24, -v111, v50, v24
	s_waitcnt lgkmcnt(0)
	v_fmac_f32_e32 v27, 0x80000000, v57
	v_fmac_f32_e32 v26, 0x80000000, v56
	v_fmac_f32_e32 v25, 0x80000000, v55
	v_fma_f32 v24, -v54, v115, v24
	v_add_f32_e32 v24, v25, v24
	v_add_f32_e32 v25, v26, v27
	v_add_f32_e32 v116, v25, v24
	ds_read_b128 v[24:27], v92 offset:6656
	ds_read_b128 v[28:31], v92 offset:6672
	v_add_u32_e32 v59, v58, v97
	ds_read_b128 v[32:35], v92 offset:6688
	ds_read_b128 v[36:39], v92 offset:6704
	s_waitcnt lgkmcnt(3)
	v_fma_f32 v25, -v90, v25, 0
	s_waitcnt lgkmcnt(2)
	v_fma_f32 v25, -v95, v29, v25
	ds_read_u16 v29, v59
	ds_read_b128 v[40:43], v92 offset:6720
	v_mul_f32_e32 v24, v89, v24
	v_fma_f32 v27, -v93, v27, 0
	ds_read_b128 v[44:47], v92 offset:6736
	s_waitcnt lgkmcnt(2)
	v_lshlrev_b32_e32 v29, 16, v29
	v_fma_f32 v26, -v91, v26, 0
	v_fma_f32 v24, v48, v29, -v24
	v_fma_f32 v27, -v98, v31, v27
	ds_read_b128 v[50:53], v92 offset:6752
	v_fma_f32 v26, -v96, v30, v26
	v_fma_f32 v24, -v94, v28, v24
	v_fma_f32 v27, -v102, v35, v27
	v_fma_f32 v26, -v101, v34, v26
	v_fma_f32 v25, -v100, v33, v25
	v_fma_f32 v24, -v99, v32, v24
	v_fma_f32 v27, -v106, v39, v27
	v_fma_f32 v26, -v105, v38, v26
	v_fma_f32 v25, -v104, v37, v25
	v_fma_f32 v24, -v103, v36, v24
	s_waitcnt lgkmcnt(2)
	v_fma_f32 v27, -v110, v43, v27
	v_fma_f32 v26, -v109, v42, v26
	v_fma_f32 v25, -v108, v41, v25
	v_fma_f32 v24, -v107, v40, v24
	s_waitcnt lgkmcnt(1)
	v_fma_f32 v27, -v114, v47, v27
	v_fma_f32 v26, -v113, v46, v26
	v_fma_f32 v25, -v112, v45, v25
	v_fma_f32 v24, -v111, v44, v24
	s_waitcnt lgkmcnt(0)
	v_fmac_f32_e32 v27, 0x80000000, v53
	v_fmac_f32_e32 v26, 0x80000000, v52
	v_fma_f32 v25, -v51, v116, v25
	v_fma_f32 v24, -v115, v50, v24
	v_add_f32_e32 v24, v25, v24
	v_add_f32_e32 v25, v26, v27
	v_add_f32_e32 v117, v25, v24
	ds_read_b128 v[24:27], v92 offset:6912
	ds_read_b128 v[28:31], v92 offset:6928
	v_add_u32_e32 v54, v59, v97
	ds_read_b128 v[32:35], v92 offset:6944
	ds_read_b128 v[36:39], v92 offset:6960
	s_waitcnt lgkmcnt(3)
	v_fma_f32 v25, -v90, v25, 0
	s_waitcnt lgkmcnt(2)
	v_fma_f32 v25, -v95, v29, v25
	ds_read_u16 v29, v54
	ds_read_b128 v[40:43], v92 offset:6976
	v_mul_f32_e32 v24, v89, v24
	v_fma_f32 v27, -v93, v27, 0
	ds_read_b128 v[44:47], v92 offset:6992
	s_waitcnt lgkmcnt(2)
	v_lshlrev_b32_e32 v29, 16, v29
	v_fma_f32 v26, -v91, v26, 0
	v_fma_f32 v24, v49, v29, -v24
	v_fma_f32 v27, -v98, v31, v27
	ds_read_b128 v[50:53], v92 offset:7008
	v_fma_f32 v26, -v96, v30, v26
	v_fma_f32 v24, -v94, v28, v24
	v_fma_f32 v27, -v102, v35, v27
	v_fma_f32 v26, -v101, v34, v26
	v_fma_f32 v25, -v100, v33, v25
	v_fma_f32 v24, -v99, v32, v24
	v_fma_f32 v27, -v106, v39, v27
	v_fma_f32 v26, -v105, v38, v26
	v_fma_f32 v25, -v104, v37, v25
	v_fma_f32 v24, -v103, v36, v24
	ds_read_b128 v[28:31], v92 offset:7168
	s_waitcnt lgkmcnt(3)
	v_fma_f32 v27, -v110, v43, v27
	v_fma_f32 v26, -v109, v42, v26
	v_fma_f32 v25, -v108, v41, v25
	v_fma_f32 v24, -v107, v40, v24
	ds_read_b128 v[32:35], v92 offset:7184
	s_waitcnt lgkmcnt(3)
	v_fma_f32 v27, -v114, v47, v27
	v_fma_f32 v26, -v113, v46, v26
	v_fma_f32 v25, -v112, v45, v25
	v_fma_f32 v24, -v111, v44, v24
	ds_read_b128 v[36:39], v92 offset:7200
	s_waitcnt lgkmcnt(3)
	v_fmac_f32_e32 v27, 0x80000000, v53
	v_fma_f32 v26, -v52, v117, v26
	v_fma_f32 v25, -v116, v51, v25
	v_fma_f32 v24, -v115, v50, v24
	ds_read_b128 v[40:43], v92 offset:7216
	v_add_f32_e32 v24, v25, v24
	v_add_f32_e32 v25, v27, v26
	ds_read_b128 v[44:47], v92 offset:7232
	v_add_f32_e32 v118, v25, v24
	s_waitcnt lgkmcnt(4)
	v_fma_f32 v24, -v93, v31, 0
	ds_read_b128 v[48:51], v92 offset:7248
	v_add_u32_e32 v57, v54, v97
	s_waitcnt lgkmcnt(4)
	v_fma_f32 v24, -v98, v35, v24
	ds_read_b128 v[52:55], v92 offset:7264
	s_waitcnt lgkmcnt(4)
	v_fma_f32 v24, -v102, v39, v24
	s_waitcnt lgkmcnt(3)
	v_fma_f32 v24, -v106, v43, v24
	s_waitcnt lgkmcnt(2)
	v_fma_f32 v24, -v110, v47, v24
	s_waitcnt lgkmcnt(1)
	v_fma_f32 v24, -v114, v51, v24
	s_waitcnt lgkmcnt(0)
	v_fma_f32 v31, -v55, v118, v24
	v_fma_f32 v24, -v91, v30, 0
	v_fma_f32 v24, -v96, v34, v24
	v_fma_f32 v24, -v101, v38, v24
	v_fma_f32 v24, -v105, v42, v24
	v_fma_f32 v24, -v109, v46, v24
	v_fma_f32 v24, -v113, v50, v24
	v_fma_f32 v30, -v117, v54, v24
	v_fma_f32 v24, -v90, v29, 0
	v_fma_f32 v24, -v95, v33, v24
	v_fma_f32 v24, -v100, v37, v24
	v_fma_f32 v24, -v104, v41, v24
	v_fma_f32 v24, -v108, v45, v24
	v_fma_f32 v24, -v112, v49, v24
	v_fma_f32 v29, -v116, v53, v24
	ds_read_b128 v[24:27], v84 offset:112
	ds_read_u16 v33, v57
	v_mul_f32_e32 v28, v89, v28
	v_add_u32_e32 v56, v57, v97
	ds_read_b128 v[58:61], v92 offset:7536
	s_waitcnt lgkmcnt(1)
	v_lshlrev_b32_e32 v33, 16, v33
	v_fma_f32 v24, v24, v33, -v28
	v_fma_f32 v24, -v94, v32, v24
	v_fma_f32 v24, -v99, v36, v24
	v_fma_f32 v24, -v103, v40, v24
	v_fma_f32 v24, -v107, v44, v24
	v_fma_f32 v24, -v111, v48, v24
	v_fma_f32 v24, -v115, v52, v24
	v_add_f32_e32 v24, v29, v24
	v_add_f32_e32 v28, v30, v31
	v_add_f32_e32 v119, v28, v24
	ds_read_b128 v[28:31], v92 offset:7424
	ds_read_b128 v[32:35], v92 offset:7440
	ds_read_b128 v[36:39], v92 offset:7456
	ds_read_b128 v[40:43], v92 offset:7472
	ds_read_b128 v[44:47], v92 offset:7488
	s_waitcnt lgkmcnt(4)
	v_fma_f32 v29, -v90, v29, 0
	s_waitcnt lgkmcnt(3)
	v_fma_f32 v29, -v95, v33, v29
	ds_read_u16 v33, v56
	v_mul_f32_e32 v28, v89, v28
	v_fma_f32 v31, -v93, v31, 0
	ds_read_b128 v[48:51], v92 offset:7504
	v_fma_f32 v30, -v91, v30, 0
	s_waitcnt lgkmcnt(1)
	v_lshlrev_b32_e32 v33, 16, v33
	v_fma_f32 v25, v25, v33, -v28
	v_fma_f32 v31, -v98, v35, v31
	ds_read_b128 v[52:55], v92 offset:7520
	v_fma_f32 v30, -v96, v34, v30
	v_fma_f32 v25, -v94, v32, v25
	v_fma_f32 v31, -v102, v39, v31
	v_fma_f32 v30, -v101, v38, v30
	v_fma_f32 v29, -v100, v37, v29
	v_fma_f32 v25, -v99, v36, v25
	v_fma_f32 v31, -v106, v43, v31
	v_fma_f32 v30, -v105, v42, v30
	v_fma_f32 v29, -v104, v41, v29
	v_fma_f32 v25, -v103, v40, v25
	v_fma_f32 v31, -v110, v47, v31
	v_fma_f32 v30, -v109, v46, v30
	v_fma_f32 v29, -v108, v45, v29
	v_fma_f32 v25, -v107, v44, v25
	s_waitcnt lgkmcnt(1)
	v_fma_f32 v31, -v114, v51, v31
	v_fma_f32 v30, -v113, v50, v30
	v_fma_f32 v29, -v112, v49, v29
	v_fma_f32 v25, -v111, v48, v25
	s_waitcnt lgkmcnt(0)
	v_fma_f32 v31, -v118, v55, v31
	v_fma_f32 v30, -v117, v54, v30
	v_fma_f32 v29, -v116, v53, v29
	v_fma_f32 v25, -v115, v52, v25
	v_fmac_f32_e32 v31, 0x80000000, v61
	v_fmac_f32_e32 v30, 0x80000000, v60
	v_fmac_f32_e32 v29, 0x80000000, v59
	v_fma_f32 v25, -v58, v119, v25
	v_add_u32_e32 v24, v56, v97
	v_add_f32_e32 v25, v29, v25
	v_add_f32_e32 v28, v30, v31
	v_add_f32_e32 v120, v28, v25
	v_add_u32_e32 v25, v24, v97
	ds_read_b128 v[28:31], v92 offset:7680
	ds_read_u16 v24, v24
	ds_read_b128 v[32:35], v92 offset:7696
	ds_read_b128 v[36:39], v92 offset:7712
	ds_read_b128 v[40:43], v92 offset:7728
	ds_read_b128 v[44:47], v92 offset:7744
	s_waitcnt lgkmcnt(4)
	v_lshlrev_b32_e32 v24, 16, v24
	v_mul_f32_e32 v28, v89, v28
	v_fma_f32 v31, -v93, v31, 0
	ds_read_b128 v[48:51], v92 offset:7760
	v_fma_f32 v30, -v91, v30, 0
	v_fma_f32 v29, -v90, v29, 0
	v_fma_f32 v24, v26, v24, -v28
	s_waitcnt lgkmcnt(4)
	v_fma_f32 v31, -v98, v35, v31
	ds_read_b128 v[52:55], v92 offset:7776
	v_fma_f32 v30, -v96, v34, v30
	v_fma_f32 v29, -v95, v33, v29
	v_fma_f32 v24, -v94, v32, v24
	s_waitcnt lgkmcnt(4)
	v_fma_f32 v31, -v102, v39, v31
	ds_read_b128 v[56:59], v92 offset:7792
	v_fma_f32 v30, -v101, v38, v30
	v_fma_f32 v29, -v100, v37, v29
	v_fma_f32 v24, -v99, v36, v24
	s_waitcnt lgkmcnt(4)
	v_fma_f32 v31, -v106, v43, v31
	v_fma_f32 v30, -v105, v42, v30
	v_fma_f32 v29, -v104, v41, v29
	v_fma_f32 v24, -v103, v40, v24
	s_waitcnt lgkmcnt(3)
	v_fma_f32 v31, -v110, v47, v31
	v_fma_f32 v30, -v109, v46, v30
	v_fma_f32 v29, -v108, v45, v29
	v_fma_f32 v24, -v107, v44, v24
	s_waitcnt lgkmcnt(2)
	v_fma_f32 v31, -v114, v51, v31
	v_fma_f32 v30, -v113, v50, v30
	v_fma_f32 v29, -v112, v49, v29
	v_fma_f32 v24, -v111, v48, v24
	s_waitcnt lgkmcnt(1)
	v_fma_f32 v31, -v118, v55, v31
	v_fma_f32 v30, -v117, v54, v30
	v_fma_f32 v29, -v116, v53, v29
	v_fma_f32 v24, -v115, v52, v24
	s_waitcnt lgkmcnt(0)
	v_fmac_f32_e32 v31, 0x80000000, v59
	v_fmac_f32_e32 v30, 0x80000000, v58
	v_fma_f32 v29, -v57, v120, v29
	v_fma_f32 v24, -v119, v56, v24
	v_add_f32_e32 v24, v29, v24
	v_add_f32_e32 v26, v30, v31
	v_add_u32_e32 v60, v25, v97
	ds_read_b128 v[28:31], v92 offset:7936
	ds_read_u16 v25, v25
	ds_read_b128 v[32:35], v92 offset:7952
	ds_read_b128 v[36:39], v92 offset:7968
	ds_read_b128 v[40:43], v92 offset:7984
	ds_read_b128 v[44:47], v92 offset:8000
	s_waitcnt lgkmcnt(4)
	v_lshlrev_b32_e32 v25, 16, v25
	v_mul_f32_e32 v28, v89, v28
	v_add_f32_e32 v121, v26, v24
	v_fma_f32 v24, -v93, v31, 0
	ds_read_b128 v[48:51], v92 offset:8016
	v_fma_f32 v26, -v91, v30, 0
	v_fma_f32 v29, -v90, v29, 0
	v_fma_f32 v25, v27, v25, -v28
	s_waitcnt lgkmcnt(4)
	v_fma_f32 v24, -v98, v35, v24
	ds_read_b128 v[52:55], v92 offset:8032
	v_fma_f32 v26, -v96, v34, v26
	v_fma_f32 v29, -v95, v33, v29
	v_fma_f32 v25, -v94, v32, v25
	s_waitcnt lgkmcnt(4)
	v_fma_f32 v24, -v102, v39, v24
	ds_read_b128 v[56:59], v92 offset:8048
	v_fma_f32 v26, -v101, v38, v26
	v_fma_f32 v29, -v100, v37, v29
	v_fma_f32 v25, -v99, v36, v25
	s_waitcnt lgkmcnt(4)
	v_fma_f32 v24, -v106, v43, v24
	v_fma_f32 v26, -v105, v42, v26
	v_fma_f32 v29, -v104, v41, v29
	v_fma_f32 v25, -v103, v40, v25
	s_waitcnt lgkmcnt(3)
	v_fma_f32 v24, -v110, v47, v24
	v_fma_f32 v26, -v109, v46, v26
	v_fma_f32 v29, -v108, v45, v29
	v_fma_f32 v25, -v107, v44, v25
	s_waitcnt lgkmcnt(2)
	v_fma_f32 v24, -v114, v51, v24
	v_fma_f32 v26, -v113, v50, v26
	v_fma_f32 v29, -v112, v49, v29
	v_fma_f32 v25, -v111, v48, v25
	s_waitcnt lgkmcnt(1)
	v_fma_f32 v24, -v118, v55, v24
	v_fma_f32 v26, -v117, v54, v26
	v_fma_f32 v29, -v116, v53, v29
	v_fma_f32 v25, -v115, v52, v25
	s_waitcnt lgkmcnt(0)
	v_fmac_f32_e32 v24, 0x80000000, v59
	v_fma_f32 v26, -v58, v121, v26
	v_fma_f32 v29, -v120, v57, v29
	v_fma_f32 v25, -v119, v56, v25
	v_add_f32_e32 v25, v29, v25
	v_add_f32_e32 v24, v24, v26
	v_add_f32_e32 v122, v24, v25
	ds_read_b128 v[24:27], v92 offset:8192
	ds_read_b128 v[28:31], v92 offset:8208
	ds_read_b128 v[32:35], v92 offset:8224
	ds_read_b128 v[36:39], v92 offset:8240
	ds_read_b128 v[40:43], v92 offset:8256
	s_waitcnt lgkmcnt(4)
	v_fma_f32 v27, -v93, v27, 0
	ds_read_b128 v[44:47], v92 offset:8272
	v_fma_f32 v26, -v91, v26, 0
	s_waitcnt lgkmcnt(4)
	v_fma_f32 v27, -v98, v31, v27
	ds_read_b128 v[48:51], v92 offset:8288
	v_fma_f32 v26, -v96, v30, v26
	s_waitcnt lgkmcnt(4)
	v_fma_f32 v27, -v102, v35, v27
	ds_read_b128 v[52:55], v92 offset:8304
	v_fma_f32 v26, -v101, v34, v26
	s_waitcnt lgkmcnt(4)
	v_fma_f32 v27, -v106, v39, v27
	v_fma_f32 v26, -v105, v38, v26
	s_waitcnt lgkmcnt(3)
	v_fma_f32 v27, -v110, v43, v27
	v_fma_f32 v26, -v109, v42, v26
	s_waitcnt lgkmcnt(2)
	v_fma_f32 v27, -v114, v47, v27
	v_fma_f32 v26, -v113, v46, v26
	s_waitcnt lgkmcnt(1)
	v_fma_f32 v27, -v118, v51, v27
	v_fma_f32 v26, -v117, v50, v26
	v_fma_f32 v25, -v90, v25, 0
	s_waitcnt lgkmcnt(0)
	v_fma_f32 v27, -v55, v122, v27
	v_fma_f32 v26, -v121, v54, v26
	v_fma_f32 v25, -v95, v29, v25
	ds_read_b128 v[54:57], v84 offset:128
	ds_read_u16 v29, v60
	v_mul_f32_e32 v24, v89, v24
	v_fma_f32 v25, -v100, v33, v25
	v_fma_f32 v25, -v104, v37, v25
	v_fma_f32 v25, -v108, v41, v25
	s_waitcnt lgkmcnt(0)
	v_lshlrev_b32_e32 v29, 16, v29
	v_fma_f32 v24, v54, v29, -v24
	v_fma_f32 v24, -v94, v28, v24
	v_fma_f32 v24, -v99, v32, v24
	v_fma_f32 v24, -v103, v36, v24
	v_fma_f32 v24, -v107, v40, v24
	v_fma_f32 v25, -v112, v45, v25
	v_fma_f32 v24, -v111, v44, v24
	v_fma_f32 v25, -v116, v49, v25
	v_fma_f32 v24, -v115, v48, v24
	v_fma_f32 v25, -v120, v53, v25
	v_fma_f32 v24, -v119, v52, v24
	v_add_f32_e32 v24, v25, v24
	v_add_f32_e32 v25, v26, v27
	v_add_f32_e32 v123, v25, v24
	ds_read_b128 v[24:27], v92 offset:8448
	ds_read_b128 v[28:31], v92 offset:8464
	v_add_u32_e32 v66, v60, v97
	ds_read_b128 v[32:35], v92 offset:8480
	ds_read_b128 v[36:39], v92 offset:8496
	s_waitcnt lgkmcnt(3)
	v_fma_f32 v25, -v90, v25, 0
	s_waitcnt lgkmcnt(2)
	v_fma_f32 v25, -v95, v29, v25
	ds_read_u16 v29, v66
	ds_read_b128 v[40:43], v92 offset:8512
	v_mul_f32_e32 v24, v89, v24
	v_fma_f32 v27, -v93, v27, 0
	ds_read_b128 v[44:47], v92 offset:8528
	s_waitcnt lgkmcnt(2)
	v_lshlrev_b32_e32 v29, 16, v29
	v_fma_f32 v26, -v91, v26, 0
	v_fma_f32 v24, v55, v29, -v24
	v_fma_f32 v27, -v98, v31, v27
	ds_read_b128 v[48:51], v92 offset:8544
	v_fma_f32 v26, -v96, v30, v26
	v_fma_f32 v24, -v94, v28, v24
	v_fma_f32 v27, -v102, v35, v27
	ds_read_b128 v[58:61], v92 offset:8560
	ds_read_b128 v[62:65], v92 offset:8576
	v_fma_f32 v26, -v101, v34, v26
	v_fma_f32 v25, -v100, v33, v25
	v_fma_f32 v24, -v99, v32, v24
	v_fma_f32 v27, -v106, v39, v27
	v_fma_f32 v26, -v105, v38, v26
	v_fma_f32 v25, -v104, v37, v25
	v_fma_f32 v24, -v103, v36, v24
	s_waitcnt lgkmcnt(4)
	v_fma_f32 v27, -v110, v43, v27
	v_fma_f32 v26, -v109, v42, v26
	v_fma_f32 v25, -v108, v41, v25
	v_fma_f32 v24, -v107, v40, v24
	s_waitcnt lgkmcnt(3)
	v_fma_f32 v27, -v114, v47, v27
	v_fma_f32 v26, -v113, v46, v26
	v_fma_f32 v25, -v112, v45, v25
	v_fma_f32 v24, -v111, v44, v24
	s_waitcnt lgkmcnt(2)
	v_fma_f32 v27, -v118, v51, v27
	v_fma_f32 v26, -v117, v50, v26
	v_fma_f32 v25, -v116, v49, v25
	v_fma_f32 v24, -v115, v48, v24
	s_waitcnt lgkmcnt(1)
	v_fma_f32 v27, -v122, v61, v27
	v_fma_f32 v26, -v121, v60, v26
	v_fma_f32 v25, -v120, v59, v25
	v_fma_f32 v24, -v119, v58, v24
	s_waitcnt lgkmcnt(0)
	v_fmac_f32_e32 v27, 0x80000000, v65
	v_fmac_f32_e32 v26, 0x80000000, v64
	v_fmac_f32_e32 v25, 0x80000000, v63
	v_fma_f32 v24, -v62, v123, v24
	v_add_f32_e32 v24, v25, v24
	v_add_f32_e32 v25, v26, v27
	v_add_f32_e32 v124, v25, v24
	ds_read_b128 v[24:27], v92 offset:8704
	ds_read_b128 v[28:31], v92 offset:8720
	v_add_u32_e32 v67, v66, v97
	ds_read_b128 v[32:35], v92 offset:8736
	ds_read_b128 v[36:39], v92 offset:8752
	s_waitcnt lgkmcnt(3)
	v_fma_f32 v25, -v90, v25, 0
	s_waitcnt lgkmcnt(2)
	v_fma_f32 v25, -v95, v29, v25
	ds_read_u16 v29, v67
	ds_read_b128 v[40:43], v92 offset:8768
	v_mul_f32_e32 v24, v89, v24
	v_fma_f32 v27, -v93, v27, 0
	ds_read_b128 v[44:47], v92 offset:8784
	s_waitcnt lgkmcnt(2)
	v_lshlrev_b32_e32 v29, 16, v29
	v_fma_f32 v26, -v91, v26, 0
	v_fma_f32 v24, v56, v29, -v24
	v_fma_f32 v27, -v98, v31, v27
	ds_read_b128 v[48:51], v92 offset:8800
	v_fma_f32 v26, -v96, v30, v26
	v_fma_f32 v24, -v94, v28, v24
	v_fma_f32 v27, -v102, v35, v27
	ds_read_b128 v[52:55], v92 offset:8816
	v_fma_f32 v26, -v101, v34, v26
	v_fma_f32 v25, -v100, v33, v25
	v_fma_f32 v24, -v99, v32, v24
	v_fma_f32 v27, -v106, v39, v27
	ds_read_b128 v[58:61], v92 offset:8832
	v_fma_f32 v26, -v105, v38, v26
	v_fma_f32 v25, -v104, v37, v25
	v_fma_f32 v24, -v103, v36, v24
	s_waitcnt lgkmcnt(4)
	v_fma_f32 v27, -v110, v43, v27
	v_fma_f32 v26, -v109, v42, v26
	v_fma_f32 v25, -v108, v41, v25
	v_fma_f32 v24, -v107, v40, v24
	s_waitcnt lgkmcnt(3)
	v_fma_f32 v27, -v114, v47, v27
	v_fma_f32 v26, -v113, v46, v26
	v_fma_f32 v25, -v112, v45, v25
	v_fma_f32 v24, -v111, v44, v24
	s_waitcnt lgkmcnt(2)
	v_fma_f32 v27, -v118, v51, v27
	v_fma_f32 v26, -v117, v50, v26
	v_fma_f32 v25, -v116, v49, v25
	v_fma_f32 v24, -v115, v48, v24
	s_waitcnt lgkmcnt(1)
	v_fma_f32 v27, -v122, v55, v27
	v_fma_f32 v26, -v121, v54, v26
	v_fma_f32 v25, -v120, v53, v25
	v_fma_f32 v24, -v119, v52, v24
	s_waitcnt lgkmcnt(0)
	v_fmac_f32_e32 v27, 0x80000000, v61
	v_fmac_f32_e32 v26, 0x80000000, v60
	v_fma_f32 v25, -v59, v124, v25
	v_fma_f32 v24, -v123, v58, v24
	v_add_f32_e32 v24, v25, v24
	v_add_f32_e32 v25, v26, v27
	v_add_f32_e32 v125, v25, v24
	ds_read_b128 v[24:27], v92 offset:8960
	ds_read_b128 v[28:31], v92 offset:8976
	v_add_u32_e32 v62, v67, v97
	ds_read_b128 v[32:35], v92 offset:8992
	ds_read_b128 v[36:39], v92 offset:9008
	s_waitcnt lgkmcnt(3)
	v_fma_f32 v25, -v90, v25, 0
	s_waitcnt lgkmcnt(2)
	v_fma_f32 v25, -v95, v29, v25
	ds_read_u16 v29, v62
	ds_read_b128 v[40:43], v92 offset:9024
	v_mul_f32_e32 v24, v89, v24
	v_fma_f32 v27, -v93, v27, 0
	ds_read_b128 v[44:47], v92 offset:9040
	s_waitcnt lgkmcnt(2)
	v_lshlrev_b32_e32 v29, 16, v29
	v_fma_f32 v26, -v91, v26, 0
	v_fma_f32 v24, v57, v29, -v24
	v_fma_f32 v27, -v98, v31, v27
	ds_read_b128 v[48:51], v92 offset:9056
	v_fma_f32 v26, -v96, v30, v26
	v_fma_f32 v24, -v94, v28, v24
	v_fma_f32 v27, -v102, v35, v27
	ds_read_b128 v[52:55], v92 offset:9072
	v_fma_f32 v26, -v101, v34, v26
	v_fma_f32 v25, -v100, v33, v25
	v_fma_f32 v24, -v99, v32, v24
	v_fma_f32 v27, -v106, v39, v27
	ds_read_b128 v[58:61], v92 offset:9088
	v_fma_f32 v26, -v105, v38, v26
	v_fma_f32 v25, -v104, v37, v25
	v_fma_f32 v24, -v103, v36, v24
	s_waitcnt lgkmcnt(4)
	v_fma_f32 v27, -v110, v43, v27
	v_fma_f32 v26, -v109, v42, v26
	v_fma_f32 v25, -v108, v41, v25
	v_fma_f32 v24, -v107, v40, v24
	s_waitcnt lgkmcnt(3)
	v_fma_f32 v27, -v114, v47, v27
	v_fma_f32 v26, -v113, v46, v26
	v_fma_f32 v25, -v112, v45, v25
	v_fma_f32 v24, -v111, v44, v24
	s_waitcnt lgkmcnt(2)
	v_fma_f32 v27, -v118, v51, v27
	v_fma_f32 v26, -v117, v50, v26
	v_fma_f32 v25, -v116, v49, v25
	v_fma_f32 v24, -v115, v48, v24
	s_waitcnt lgkmcnt(1)
	v_fma_f32 v27, -v122, v55, v27
	v_fma_f32 v26, -v121, v54, v26
	v_fma_f32 v25, -v120, v53, v25
	v_fma_f32 v24, -v119, v52, v24
	s_waitcnt lgkmcnt(0)
	v_fmac_f32_e32 v27, 0x80000000, v61
	v_fma_f32 v26, -v60, v125, v26
	v_fma_f32 v25, -v124, v59, v25
	v_fma_f32 v24, -v123, v58, v24
	v_add_f32_e32 v24, v25, v24
	v_add_f32_e32 v25, v27, v26
	v_add_f32_e32 v126, v25, v24
	ds_read_b128 v[24:27], v92 offset:9216
	ds_read_b128 v[28:31], v92 offset:9232
	ds_read_b128 v[32:35], v92 offset:9248
	ds_read_b128 v[36:39], v92 offset:9264
	ds_read_b128 v[40:43], v92 offset:9280
	s_waitcnt lgkmcnt(4)
	v_fma_f32 v27, -v93, v27, 0
	ds_read_b128 v[44:47], v92 offset:9296
	v_fma_f32 v26, -v91, v26, 0
	s_waitcnt lgkmcnt(4)
	v_fma_f32 v27, -v98, v31, v27
	ds_read_b128 v[48:51], v92 offset:9312
	v_fma_f32 v26, -v96, v30, v26
	s_waitcnt lgkmcnt(4)
	v_fma_f32 v27, -v102, v35, v27
	ds_read_b128 v[52:55], v92 offset:9328
	v_fma_f32 v26, -v101, v34, v26
	s_waitcnt lgkmcnt(4)
	v_fma_f32 v27, -v106, v39, v27
	ds_read_b128 v[56:59], v92 offset:9344
	v_fma_f32 v26, -v105, v38, v26
	s_waitcnt lgkmcnt(4)
	v_fma_f32 v27, -v110, v43, v27
	v_fma_f32 v26, -v109, v42, v26
	s_waitcnt lgkmcnt(3)
	v_fma_f32 v27, -v114, v47, v27
	v_fma_f32 v26, -v113, v46, v26
	s_waitcnt lgkmcnt(2)
	v_fma_f32 v27, -v118, v51, v27
	v_fma_f32 v26, -v117, v50, v26
	s_waitcnt lgkmcnt(1)
	v_fma_f32 v27, -v122, v55, v27
	v_fma_f32 v26, -v121, v54, v26
	v_fma_f32 v25, -v90, v25, 0
	v_add_u32_e32 v63, v62, v97
	s_waitcnt lgkmcnt(0)
	v_fma_f32 v27, -v59, v126, v27
	v_fma_f32 v26, -v125, v58, v26
	v_fma_f32 v25, -v95, v29, v25
	ds_read_b128 v[58:61], v84 offset:144
	ds_read_u16 v29, v63
	v_mul_f32_e32 v24, v89, v24
	v_fma_f32 v25, -v100, v33, v25
	v_fma_f32 v25, -v104, v37, v25
	v_fma_f32 v25, -v108, v41, v25
	s_waitcnt lgkmcnt(0)
	v_lshlrev_b32_e32 v29, 16, v29
	v_fma_f32 v24, v58, v29, -v24
	v_fma_f32 v24, -v94, v28, v24
	v_fma_f32 v24, -v99, v32, v24
	v_fma_f32 v24, -v103, v36, v24
	v_fma_f32 v24, -v107, v40, v24
	v_fma_f32 v25, -v112, v45, v25
	v_fma_f32 v24, -v111, v44, v24
	v_fma_f32 v25, -v116, v49, v25
	v_fma_f32 v24, -v115, v48, v24
	v_fma_f32 v25, -v120, v53, v25
	v_fma_f32 v24, -v119, v52, v24
	v_fma_f32 v25, -v124, v57, v25
	v_fma_f32 v24, -v123, v56, v24
	v_add_f32_e32 v24, v25, v24
	v_add_f32_e32 v25, v26, v27
	v_add_f32_e32 v127, v25, v24
	ds_read_b128 v[24:27], v92 offset:9472
	ds_read_b128 v[28:31], v92 offset:9488
	v_add_u32_e32 v62, v63, v97
	ds_read_b128 v[32:35], v92 offset:9504
	ds_read_b128 v[36:39], v92 offset:9520
	s_waitcnt lgkmcnt(3)
	v_fma_f32 v25, -v90, v25, 0
	s_waitcnt lgkmcnt(2)
	v_fma_f32 v25, -v95, v29, v25
	ds_read_u16 v29, v62
	ds_read_b128 v[40:43], v92 offset:9536
	v_mul_f32_e32 v24, v89, v24
	v_fma_f32 v27, -v93, v27, 0
	ds_read_b128 v[44:47], v92 offset:9552
	s_waitcnt lgkmcnt(2)
	v_lshlrev_b32_e32 v29, 16, v29
	v_fma_f32 v26, -v91, v26, 0
	v_fma_f32 v24, v59, v29, -v24
	v_fma_f32 v27, -v98, v31, v27
	ds_read_b128 v[48:51], v92 offset:9568
	v_fma_f32 v26, -v96, v30, v26
	v_fma_f32 v24, -v94, v28, v24
	v_fma_f32 v27, -v102, v35, v27
	ds_read_b128 v[52:55], v92 offset:9584
	v_fma_f32 v26, -v101, v34, v26
	v_fma_f32 v25, -v100, v33, v25
	v_fma_f32 v24, -v99, v32, v24
	v_fma_f32 v27, -v106, v39, v27
	ds_read_b128 v[64:67], v92 offset:9600
	ds_read_b128 v[68:71], v92 offset:9616
	v_fma_f32 v26, -v105, v38, v26
	v_fma_f32 v25, -v104, v37, v25
	v_fma_f32 v24, -v103, v36, v24
	s_waitcnt lgkmcnt(5)
	v_fma_f32 v27, -v110, v43, v27
	v_fma_f32 v26, -v109, v42, v26
	v_fma_f32 v25, -v108, v41, v25
	v_fma_f32 v24, -v107, v40, v24
	s_waitcnt lgkmcnt(4)
	v_fma_f32 v27, -v114, v47, v27
	v_fma_f32 v26, -v113, v46, v26
	v_fma_f32 v25, -v112, v45, v25
	v_fma_f32 v24, -v111, v44, v24
	s_waitcnt lgkmcnt(3)
	v_fma_f32 v27, -v118, v51, v27
	v_fma_f32 v26, -v117, v50, v26
	v_fma_f32 v25, -v116, v49, v25
	v_fma_f32 v24, -v115, v48, v24
	s_waitcnt lgkmcnt(2)
	v_fma_f32 v27, -v122, v55, v27
	v_fma_f32 v26, -v121, v54, v26
	v_fma_f32 v25, -v120, v53, v25
	v_fma_f32 v24, -v119, v52, v24
	s_waitcnt lgkmcnt(1)
	v_fma_f32 v27, -v126, v67, v27
	v_fma_f32 v26, -v125, v66, v26
	v_fma_f32 v25, -v124, v65, v25
	v_fma_f32 v24, -v123, v64, v24
	s_waitcnt lgkmcnt(0)
	v_fmac_f32_e32 v27, 0x80000000, v71
	v_fmac_f32_e32 v26, 0x80000000, v70
	v_fmac_f32_e32 v25, 0x80000000, v69
	v_fma_f32 v24, -v68, v127, v24
	v_add_f32_e32 v24, v25, v24
	v_add_f32_e32 v25, v26, v27
	v_add_f32_e32 v133, v25, v24
	ds_read_b128 v[24:27], v92 offset:9728
	ds_read_b128 v[28:31], v92 offset:9744
	v_add_u32_e32 v72, v62, v97
	ds_read_b128 v[32:35], v92 offset:9760
	ds_read_b128 v[36:39], v92 offset:9776
	s_waitcnt lgkmcnt(3)
	v_fma_f32 v25, -v90, v25, 0
	s_waitcnt lgkmcnt(2)
	v_fma_f32 v25, -v95, v29, v25
	ds_read_u16 v29, v72
	ds_read_b128 v[40:43], v92 offset:9792
	v_mul_f32_e32 v24, v89, v24
	v_fma_f32 v27, -v93, v27, 0
	ds_read_b128 v[44:47], v92 offset:9808
	s_waitcnt lgkmcnt(2)
	v_lshlrev_b32_e32 v29, 16, v29
	v_fma_f32 v26, -v91, v26, 0
	v_fma_f32 v24, v60, v29, -v24
	v_fma_f32 v27, -v98, v31, v27
	ds_read_b128 v[48:51], v92 offset:9824
	v_fma_f32 v26, -v96, v30, v26
	v_fma_f32 v24, -v94, v28, v24
	v_fma_f32 v27, -v102, v35, v27
	ds_read_b128 v[52:55], v92 offset:9840
	v_fma_f32 v26, -v101, v34, v26
	v_fma_f32 v25, -v100, v33, v25
	v_fma_f32 v24, -v99, v32, v24
	v_fma_f32 v27, -v106, v39, v27
	ds_read_b128 v[56:59], v92 offset:9856
	v_fma_f32 v26, -v105, v38, v26
	v_fma_f32 v25, -v104, v37, v25
	v_fma_f32 v24, -v103, v36, v24
	s_waitcnt lgkmcnt(4)
	v_fma_f32 v27, -v110, v43, v27
	ds_read_b128 v[62:65], v92 offset:9872
	v_fma_f32 v26, -v109, v42, v26
	v_fma_f32 v25, -v108, v41, v25
	v_fma_f32 v24, -v107, v40, v24
	s_waitcnt lgkmcnt(4)
	v_fma_f32 v27, -v114, v47, v27
	v_fma_f32 v26, -v113, v46, v26
	v_fma_f32 v25, -v112, v45, v25
	v_fma_f32 v24, -v111, v44, v24
	s_waitcnt lgkmcnt(3)
	v_fma_f32 v27, -v118, v51, v27
	v_fma_f32 v26, -v117, v50, v26
	v_fma_f32 v25, -v116, v49, v25
	v_fma_f32 v24, -v115, v48, v24
	s_waitcnt lgkmcnt(2)
	v_fma_f32 v27, -v122, v55, v27
	v_fma_f32 v26, -v121, v54, v26
	v_fma_f32 v25, -v120, v53, v25
	v_fma_f32 v24, -v119, v52, v24
	s_waitcnt lgkmcnt(1)
	v_fma_f32 v27, -v126, v59, v27
	v_fma_f32 v26, -v125, v58, v26
	v_fma_f32 v25, -v124, v57, v25
	v_fma_f32 v24, -v123, v56, v24
	s_waitcnt lgkmcnt(0)
	v_fmac_f32_e32 v27, 0x80000000, v65
	v_fmac_f32_e32 v26, 0x80000000, v64
	v_fma_f32 v25, -v63, v133, v25
	v_fma_f32 v24, -v127, v62, v24
	v_add_f32_e32 v24, v25, v24
	v_add_f32_e32 v25, v26, v27
	v_add_f32_e32 v134, v25, v24
	ds_read_b128 v[24:27], v92 offset:9984
	ds_read_b128 v[28:31], v92 offset:10000
	v_add_u32_e32 v66, v72, v97
	ds_read_b128 v[32:35], v92 offset:10016
	ds_read_b128 v[36:39], v92 offset:10032
	s_waitcnt lgkmcnt(3)
	v_fma_f32 v25, -v90, v25, 0
	s_waitcnt lgkmcnt(2)
	v_fma_f32 v25, -v95, v29, v25
	ds_read_u16 v29, v66
	ds_read_b128 v[40:43], v92 offset:10048
	v_mul_f32_e32 v24, v89, v24
	v_fma_f32 v27, -v93, v27, 0
	ds_read_b128 v[44:47], v92 offset:10064
	s_waitcnt lgkmcnt(2)
	v_lshlrev_b32_e32 v29, 16, v29
	v_fma_f32 v26, -v91, v26, 0
	v_fma_f32 v24, v61, v29, -v24
	v_fma_f32 v27, -v98, v31, v27
	ds_read_b128 v[48:51], v92 offset:10080
	v_fma_f32 v26, -v96, v30, v26
	v_fma_f32 v24, -v94, v28, v24
	v_fma_f32 v27, -v102, v35, v27
	ds_read_b128 v[52:55], v92 offset:10096
	v_fma_f32 v26, -v101, v34, v26
	v_fma_f32 v25, -v100, v33, v25
	v_fma_f32 v24, -v99, v32, v24
	v_fma_f32 v27, -v106, v39, v27
	ds_read_b128 v[56:59], v92 offset:10112
	v_fma_f32 v26, -v105, v38, v26
	v_fma_f32 v25, -v104, v37, v25
	v_fma_f32 v24, -v103, v36, v24
	s_waitcnt lgkmcnt(4)
	v_fma_f32 v27, -v110, v43, v27
	ds_read_b128 v[62:65], v92 offset:10128
	v_fma_f32 v26, -v109, v42, v26
	v_fma_f32 v25, -v108, v41, v25
	v_fma_f32 v24, -v107, v40, v24
	s_waitcnt lgkmcnt(4)
	v_fma_f32 v27, -v114, v47, v27
	v_fma_f32 v26, -v113, v46, v26
	v_fma_f32 v25, -v112, v45, v25
	v_fma_f32 v24, -v111, v44, v24
	s_waitcnt lgkmcnt(3)
	v_fma_f32 v27, -v118, v51, v27
	v_fma_f32 v26, -v117, v50, v26
	v_fma_f32 v25, -v116, v49, v25
	v_fma_f32 v24, -v115, v48, v24
	s_waitcnt lgkmcnt(2)
	v_fma_f32 v27, -v122, v55, v27
	v_fma_f32 v26, -v121, v54, v26
	v_fma_f32 v25, -v120, v53, v25
	v_fma_f32 v24, -v119, v52, v24
	s_waitcnt lgkmcnt(1)
	v_fma_f32 v27, -v126, v59, v27
	v_fma_f32 v26, -v125, v58, v26
	v_fma_f32 v25, -v124, v57, v25
	v_fma_f32 v24, -v123, v56, v24
	s_waitcnt lgkmcnt(0)
	v_fmac_f32_e32 v27, 0x80000000, v65
	v_fma_f32 v26, -v64, v134, v26
	v_fma_f32 v25, -v133, v63, v25
	v_fma_f32 v24, -v127, v62, v24
	v_add_f32_e32 v24, v25, v24
	v_add_f32_e32 v25, v27, v26
	v_add_f32_e32 v135, v25, v24
	ds_read_b128 v[24:27], v92 offset:10240
	ds_read_b128 v[28:31], v92 offset:10256
	ds_read_b128 v[32:35], v92 offset:10272
	ds_read_b128 v[36:39], v92 offset:10288
	ds_read_b128 v[40:43], v92 offset:10304
	s_waitcnt lgkmcnt(4)
	v_fma_f32 v27, -v93, v27, 0
	ds_read_b128 v[44:47], v92 offset:10320
	v_fma_f32 v26, -v91, v26, 0
	s_waitcnt lgkmcnt(4)
	v_fma_f32 v27, -v98, v31, v27
	ds_read_b128 v[48:51], v92 offset:10336
	v_fma_f32 v26, -v96, v30, v26
	s_waitcnt lgkmcnt(4)
	v_fma_f32 v27, -v102, v35, v27
	ds_read_b128 v[52:55], v92 offset:10352
	v_fma_f32 v26, -v101, v34, v26
	s_waitcnt lgkmcnt(4)
	v_fma_f32 v27, -v106, v39, v27
	ds_read_b128 v[56:59], v92 offset:10368
	v_fma_f32 v26, -v105, v38, v26
	s_waitcnt lgkmcnt(4)
	v_fma_f32 v27, -v110, v43, v27
	ds_read_b128 v[60:63], v92 offset:10384
	v_fma_f32 v26, -v109, v42, v26
	s_waitcnt lgkmcnt(4)
	v_fma_f32 v27, -v114, v47, v27
	v_fma_f32 v26, -v113, v46, v26
	s_waitcnt lgkmcnt(3)
	v_fma_f32 v27, -v118, v51, v27
	v_fma_f32 v26, -v117, v50, v26
	s_waitcnt lgkmcnt(2)
	v_fma_f32 v27, -v122, v55, v27
	v_fma_f32 v26, -v121, v54, v26
	s_waitcnt lgkmcnt(1)
	v_fma_f32 v27, -v126, v59, v27
	v_fma_f32 v26, -v125, v58, v26
	v_fma_f32 v25, -v90, v25, 0
	v_add_u32_e32 v67, v66, v97
	s_waitcnt lgkmcnt(0)
	v_fma_f32 v27, -v63, v135, v27
	v_fma_f32 v26, -v134, v62, v26
	v_fma_f32 v25, -v95, v29, v25
	ds_read_b128 v[62:65], v84 offset:160
	ds_read_u16 v29, v67
	v_mul_f32_e32 v24, v89, v24
	v_fma_f32 v25, -v100, v33, v25
	v_fma_f32 v25, -v104, v37, v25
	v_fma_f32 v25, -v108, v41, v25
	s_waitcnt lgkmcnt(0)
	v_lshlrev_b32_e32 v29, 16, v29
	v_fma_f32 v24, v62, v29, -v24
	v_fma_f32 v24, -v94, v28, v24
	v_fma_f32 v24, -v99, v32, v24
	v_fma_f32 v24, -v103, v36, v24
	v_fma_f32 v24, -v107, v40, v24
	v_fma_f32 v25, -v112, v45, v25
	v_fma_f32 v24, -v111, v44, v24
	v_fma_f32 v25, -v116, v49, v25
	v_fma_f32 v24, -v115, v48, v24
	v_fma_f32 v25, -v120, v53, v25
	v_fma_f32 v24, -v119, v52, v24
	v_fma_f32 v25, -v124, v57, v25
	v_fma_f32 v24, -v123, v56, v24
	v_fma_f32 v25, -v133, v61, v25
	v_fma_f32 v24, -v127, v60, v24
	v_add_f32_e32 v24, v25, v24
	v_add_f32_e32 v25, v26, v27
	v_add_f32_e32 v136, v25, v24
	ds_read_b128 v[24:27], v92 offset:10496
	ds_read_b128 v[28:31], v92 offset:10512
	v_add_u32_e32 v74, v67, v97
	ds_read_b128 v[32:35], v92 offset:10528
	ds_read_b128 v[36:39], v92 offset:10544
	s_waitcnt lgkmcnt(3)
	v_fma_f32 v25, -v90, v25, 0
	s_waitcnt lgkmcnt(2)
	v_fma_f32 v25, -v95, v29, v25
	ds_read_u16 v29, v74
	ds_read_b128 v[40:43], v92 offset:10560
	v_mul_f32_e32 v24, v89, v24
	v_fma_f32 v27, -v93, v27, 0
	ds_read_b128 v[44:47], v92 offset:10576
	s_waitcnt lgkmcnt(2)
	v_lshlrev_b32_e32 v29, 16, v29
	v_fma_f32 v26, -v91, v26, 0
	v_fma_f32 v24, v63, v29, -v24
	v_fma_f32 v27, -v98, v31, v27
	ds_read_b128 v[48:51], v92 offset:10592
	v_fma_f32 v26, -v96, v30, v26
	v_fma_f32 v24, -v94, v28, v24
	v_fma_f32 v27, -v102, v35, v27
	ds_read_b128 v[52:55], v92 offset:10608
	v_fma_f32 v26, -v101, v34, v26
	v_fma_f32 v25, -v100, v33, v25
	v_fma_f32 v24, -v99, v32, v24
	v_fma_f32 v27, -v106, v39, v27
	ds_read_b128 v[56:59], v92 offset:10624
	v_fma_f32 v26, -v105, v38, v26
	v_fma_f32 v25, -v104, v37, v25
	v_fma_f32 v24, -v103, v36, v24
	s_waitcnt lgkmcnt(4)
	v_fma_f32 v27, -v110, v43, v27
	ds_read_b128 v[66:69], v92 offset:10640
	ds_read_b128 v[70:73], v92 offset:10656
	v_fma_f32 v26, -v109, v42, v26
	v_fma_f32 v25, -v108, v41, v25
	v_fma_f32 v24, -v107, v40, v24
	s_waitcnt lgkmcnt(5)
	v_fma_f32 v27, -v114, v47, v27
	v_fma_f32 v26, -v113, v46, v26
	v_fma_f32 v25, -v112, v45, v25
	v_fma_f32 v24, -v111, v44, v24
	s_waitcnt lgkmcnt(4)
	v_fma_f32 v27, -v118, v51, v27
	v_fma_f32 v26, -v117, v50, v26
	v_fma_f32 v25, -v116, v49, v25
	v_fma_f32 v24, -v115, v48, v24
	s_waitcnt lgkmcnt(3)
	v_fma_f32 v27, -v122, v55, v27
	v_fma_f32 v26, -v121, v54, v26
	v_fma_f32 v25, -v120, v53, v25
	v_fma_f32 v24, -v119, v52, v24
	s_waitcnt lgkmcnt(2)
	v_fma_f32 v27, -v126, v59, v27
	v_fma_f32 v26, -v125, v58, v26
	v_fma_f32 v25, -v124, v57, v25
	v_fma_f32 v24, -v123, v56, v24
	s_waitcnt lgkmcnt(1)
	v_fma_f32 v27, -v135, v69, v27
	v_fma_f32 v26, -v134, v68, v26
	v_fma_f32 v25, -v133, v67, v25
	v_fma_f32 v24, -v127, v66, v24
	s_waitcnt lgkmcnt(0)
	v_fmac_f32_e32 v27, 0x80000000, v73
	v_fmac_f32_e32 v26, 0x80000000, v72
	v_fmac_f32_e32 v25, 0x80000000, v71
	v_fma_f32 v24, -v70, v136, v24
	v_add_f32_e32 v24, v25, v24
	v_add_f32_e32 v25, v26, v27
	v_add_f32_e32 v137, v25, v24
	ds_read_b128 v[24:27], v92 offset:10752
	ds_read_b128 v[28:31], v92 offset:10768
	v_add_u32_e32 v75, v74, v97
	ds_read_b128 v[32:35], v92 offset:10784
	ds_read_b128 v[36:39], v92 offset:10800
	s_waitcnt lgkmcnt(3)
	v_fma_f32 v25, -v90, v25, 0
	s_waitcnt lgkmcnt(2)
	v_fma_f32 v25, -v95, v29, v25
	ds_read_u16 v29, v75
	ds_read_b128 v[40:43], v92 offset:10816
	v_mul_f32_e32 v24, v89, v24
	v_fma_f32 v27, -v93, v27, 0
	ds_read_b128 v[44:47], v92 offset:10832
	s_waitcnt lgkmcnt(2)
	v_lshlrev_b32_e32 v29, 16, v29
	v_fma_f32 v26, -v91, v26, 0
	v_fma_f32 v24, v64, v29, -v24
	v_fma_f32 v27, -v98, v31, v27
	ds_read_b128 v[48:51], v92 offset:10848
	v_fma_f32 v26, -v96, v30, v26
	v_fma_f32 v24, -v94, v28, v24
	v_fma_f32 v27, -v102, v35, v27
	ds_read_b128 v[52:55], v92 offset:10864
	v_fma_f32 v26, -v101, v34, v26
	v_fma_f32 v25, -v100, v33, v25
	v_fma_f32 v24, -v99, v32, v24
	v_fma_f32 v27, -v106, v39, v27
	ds_read_b128 v[56:59], v92 offset:10880
	v_fma_f32 v26, -v105, v38, v26
	v_fma_f32 v25, -v104, v37, v25
	v_fma_f32 v24, -v103, v36, v24
	s_waitcnt lgkmcnt(4)
	v_fma_f32 v27, -v110, v43, v27
	ds_read_b128 v[60:63], v92 offset:10896
	v_fma_f32 v26, -v109, v42, v26
	v_fma_f32 v25, -v108, v41, v25
	v_fma_f32 v24, -v107, v40, v24
	s_waitcnt lgkmcnt(4)
	v_fma_f32 v27, -v114, v47, v27
	ds_read_b128 v[66:69], v92 offset:10912
	v_fma_f32 v26, -v113, v46, v26
	v_fma_f32 v25, -v112, v45, v25
	v_fma_f32 v24, -v111, v44, v24
	s_waitcnt lgkmcnt(4)
	v_fma_f32 v27, -v118, v51, v27
	v_fma_f32 v26, -v117, v50, v26
	v_fma_f32 v25, -v116, v49, v25
	v_fma_f32 v24, -v115, v48, v24
	s_waitcnt lgkmcnt(3)
	v_fma_f32 v27, -v122, v55, v27
	v_fma_f32 v26, -v121, v54, v26
	v_fma_f32 v25, -v120, v53, v25
	v_fma_f32 v24, -v119, v52, v24
	s_waitcnt lgkmcnt(2)
	v_fma_f32 v27, -v126, v59, v27
	v_fma_f32 v26, -v125, v58, v26
	v_fma_f32 v25, -v124, v57, v25
	v_fma_f32 v24, -v123, v56, v24
	s_waitcnt lgkmcnt(1)
	v_fma_f32 v27, -v135, v63, v27
	v_fma_f32 v26, -v134, v62, v26
	v_fma_f32 v25, -v133, v61, v25
	v_fma_f32 v24, -v127, v60, v24
	s_waitcnt lgkmcnt(0)
	v_fmac_f32_e32 v27, 0x80000000, v69
	v_fmac_f32_e32 v26, 0x80000000, v68
	v_fma_f32 v25, -v67, v137, v25
	v_fma_f32 v24, -v136, v66, v24
	v_add_f32_e32 v24, v25, v24
	v_add_f32_e32 v25, v26, v27
	v_add_f32_e32 v138, v25, v24
	ds_read_b128 v[24:27], v92 offset:11008
	ds_read_b128 v[28:31], v92 offset:11024
	v_add_u32_e32 v70, v75, v97
	ds_read_b128 v[32:35], v92 offset:11040
	ds_read_b128 v[36:39], v92 offset:11056
	s_waitcnt lgkmcnt(3)
	v_fma_f32 v25, -v90, v25, 0
	s_waitcnt lgkmcnt(2)
	v_fma_f32 v25, -v95, v29, v25
	ds_read_u16 v29, v70
	ds_read_b128 v[40:43], v92 offset:11072
	v_mul_f32_e32 v24, v89, v24
	v_fma_f32 v27, -v93, v27, 0
	ds_read_b128 v[44:47], v92 offset:11088
	s_waitcnt lgkmcnt(2)
	v_lshlrev_b32_e32 v29, 16, v29
	v_fma_f32 v26, -v91, v26, 0
	v_fma_f32 v24, v65, v29, -v24
	v_fma_f32 v27, -v98, v31, v27
	ds_read_b128 v[48:51], v92 offset:11104
	v_fma_f32 v26, -v96, v30, v26
	v_fma_f32 v24, -v94, v28, v24
	v_fma_f32 v27, -v102, v35, v27
	ds_read_b128 v[52:55], v92 offset:11120
	v_fma_f32 v26, -v101, v34, v26
	v_fma_f32 v25, -v100, v33, v25
	v_fma_f32 v24, -v99, v32, v24
	v_fma_f32 v27, -v106, v39, v27
	ds_read_b128 v[56:59], v92 offset:11136
	v_fma_f32 v26, -v105, v38, v26
	v_fma_f32 v25, -v104, v37, v25
	v_fma_f32 v24, -v103, v36, v24
	s_waitcnt lgkmcnt(4)
	v_fma_f32 v27, -v110, v43, v27
	ds_read_b128 v[60:63], v92 offset:11152
	v_fma_f32 v26, -v109, v42, v26
	v_fma_f32 v25, -v108, v41, v25
	v_fma_f32 v24, -v107, v40, v24
	s_waitcnt lgkmcnt(4)
	v_fma_f32 v27, -v114, v47, v27
	ds_read_b128 v[66:69], v92 offset:11168
	v_fma_f32 v26, -v113, v46, v26
	v_fma_f32 v25, -v112, v45, v25
	v_fma_f32 v24, -v111, v44, v24
	s_waitcnt lgkmcnt(4)
	v_fma_f32 v27, -v118, v51, v27
	v_fma_f32 v26, -v117, v50, v26
	v_fma_f32 v25, -v116, v49, v25
	v_fma_f32 v24, -v115, v48, v24
	s_waitcnt lgkmcnt(3)
	v_fma_f32 v27, -v122, v55, v27
	v_fma_f32 v26, -v121, v54, v26
	v_fma_f32 v25, -v120, v53, v25
	v_fma_f32 v24, -v119, v52, v24
	s_waitcnt lgkmcnt(2)
	v_fma_f32 v27, -v126, v59, v27
	v_fma_f32 v26, -v125, v58, v26
	v_fma_f32 v25, -v124, v57, v25
	v_fma_f32 v24, -v123, v56, v24
	s_waitcnt lgkmcnt(1)
	v_fma_f32 v27, -v135, v63, v27
	v_fma_f32 v26, -v134, v62, v26
	v_fma_f32 v25, -v133, v61, v25
	v_fma_f32 v24, -v127, v60, v24
	s_waitcnt lgkmcnt(0)
	v_fmac_f32_e32 v27, 0x80000000, v69
	v_fma_f32 v26, -v68, v138, v26
	v_fma_f32 v25, -v137, v67, v25
	v_fma_f32 v24, -v136, v66, v24
	v_add_f32_e32 v24, v25, v24
	v_add_f32_e32 v25, v27, v26
	v_add_f32_e32 v139, v25, v24
	ds_read_b128 v[24:27], v92 offset:11264
	ds_read_b128 v[28:31], v92 offset:11280
	ds_read_b128 v[32:35], v92 offset:11296
	ds_read_b128 v[36:39], v92 offset:11312
	ds_read_b128 v[40:43], v92 offset:11328
	s_waitcnt lgkmcnt(4)
	v_fma_f32 v27, -v93, v27, 0
	ds_read_b128 v[44:47], v92 offset:11344
	v_fma_f32 v26, -v91, v26, 0
	s_waitcnt lgkmcnt(4)
	v_fma_f32 v27, -v98, v31, v27
	ds_read_b128 v[48:51], v92 offset:11360
	v_fma_f32 v26, -v96, v30, v26
	s_waitcnt lgkmcnt(4)
	v_fma_f32 v27, -v102, v35, v27
	ds_read_b128 v[52:55], v92 offset:11376
	v_fma_f32 v26, -v101, v34, v26
	s_waitcnt lgkmcnt(4)
	v_fma_f32 v27, -v106, v39, v27
	ds_read_b128 v[56:59], v92 offset:11392
	v_fma_f32 v26, -v105, v38, v26
	s_waitcnt lgkmcnt(4)
	v_fma_f32 v27, -v110, v43, v27
	ds_read_b128 v[60:63], v92 offset:11408
	v_fma_f32 v26, -v109, v42, v26
	s_waitcnt lgkmcnt(4)
	v_fma_f32 v27, -v114, v47, v27
	ds_read_b128 v[64:67], v92 offset:11424
	v_fma_f32 v26, -v113, v46, v26
	s_waitcnt lgkmcnt(4)
	v_fma_f32 v27, -v118, v51, v27
	v_fma_f32 v26, -v117, v50, v26
	s_waitcnt lgkmcnt(3)
	v_fma_f32 v27, -v122, v55, v27
	v_fma_f32 v26, -v121, v54, v26
	s_waitcnt lgkmcnt(2)
	v_fma_f32 v27, -v126, v59, v27
	v_fma_f32 v26, -v125, v58, v26
	s_waitcnt lgkmcnt(1)
	v_fma_f32 v27, -v135, v63, v27
	v_fma_f32 v26, -v134, v62, v26
	v_fma_f32 v25, -v90, v25, 0
	v_add_u32_e32 v71, v70, v97
	s_waitcnt lgkmcnt(0)
	v_fma_f32 v27, -v67, v139, v27
	v_fma_f32 v26, -v138, v66, v26
	v_fma_f32 v25, -v95, v29, v25
	ds_read_b128 v[66:69], v84 offset:176
	ds_read_u16 v29, v71
	v_mul_f32_e32 v24, v89, v24
	v_fma_f32 v25, -v100, v33, v25
	v_fma_f32 v25, -v104, v37, v25
	v_fma_f32 v25, -v108, v41, v25
	s_waitcnt lgkmcnt(0)
	v_lshlrev_b32_e32 v29, 16, v29
	v_fma_f32 v24, v66, v29, -v24
	v_fma_f32 v24, -v94, v28, v24
	v_fma_f32 v24, -v99, v32, v24
	v_fma_f32 v24, -v103, v36, v24
	v_fma_f32 v24, -v107, v40, v24
	v_fma_f32 v25, -v112, v45, v25
	v_fma_f32 v24, -v111, v44, v24
	v_fma_f32 v25, -v116, v49, v25
	v_fma_f32 v24, -v115, v48, v24
	v_fma_f32 v25, -v120, v53, v25
	v_fma_f32 v24, -v119, v52, v24
	v_fma_f32 v25, -v124, v57, v25
	v_fma_f32 v24, -v123, v56, v24
	v_fma_f32 v25, -v133, v61, v25
	v_fma_f32 v24, -v127, v60, v24
	v_fma_f32 v25, -v137, v65, v25
	v_fma_f32 v24, -v136, v64, v24
	v_add_f32_e32 v24, v25, v24
	v_add_f32_e32 v25, v26, v27
	v_add_f32_e32 v140, v25, v24
	ds_read_b128 v[24:27], v92 offset:11520
	ds_read_b128 v[28:31], v92 offset:11536
	v_add_u32_e32 v70, v71, v97
	ds_read_b128 v[32:35], v92 offset:11552
	ds_read_b128 v[36:39], v92 offset:11568
	s_waitcnt lgkmcnt(3)
	v_fma_f32 v25, -v90, v25, 0
	s_waitcnt lgkmcnt(2)
	v_fma_f32 v25, -v95, v29, v25
	ds_read_u16 v29, v70
	ds_read_b128 v[40:43], v92 offset:11584
	v_mul_f32_e32 v24, v89, v24
	v_fma_f32 v27, -v93, v27, 0
	ds_read_b128 v[44:47], v92 offset:11600
	s_waitcnt lgkmcnt(2)
	v_lshlrev_b32_e32 v29, 16, v29
	v_fma_f32 v26, -v91, v26, 0
	v_fma_f32 v24, v67, v29, -v24
	v_fma_f32 v27, -v98, v31, v27
	ds_read_b128 v[48:51], v92 offset:11616
	v_fma_f32 v26, -v96, v30, v26
	v_fma_f32 v24, -v94, v28, v24
	v_fma_f32 v27, -v102, v35, v27
	ds_read_b128 v[52:55], v92 offset:11632
	v_fma_f32 v26, -v101, v34, v26
	v_fma_f32 v25, -v100, v33, v25
	v_fma_f32 v24, -v99, v32, v24
	v_fma_f32 v27, -v106, v39, v27
	ds_read_b128 v[56:59], v92 offset:11648
	v_fma_f32 v26, -v105, v38, v26
	v_fma_f32 v25, -v104, v37, v25
	v_fma_f32 v24, -v103, v36, v24
	s_waitcnt lgkmcnt(4)
	v_fma_f32 v27, -v110, v43, v27
	ds_read_b128 v[60:63], v92 offset:11664
	v_fma_f32 v26, -v109, v42, v26
	v_fma_f32 v25, -v108, v41, v25
	v_fma_f32 v24, -v107, v40, v24
	s_waitcnt lgkmcnt(4)
	v_fma_f32 v27, -v114, v47, v27
	ds_read_b128 v[72:75], v92 offset:11680
	ds_read_b128 v[76:79], v92 offset:11696
	v_fma_f32 v26, -v113, v46, v26
	v_fma_f32 v25, -v112, v45, v25
	v_fma_f32 v24, -v111, v44, v24
	s_waitcnt lgkmcnt(5)
	v_fma_f32 v27, -v118, v51, v27
	v_fma_f32 v26, -v117, v50, v26
	v_fma_f32 v25, -v116, v49, v25
	v_fma_f32 v24, -v115, v48, v24
	s_waitcnt lgkmcnt(4)
	v_fma_f32 v27, -v122, v55, v27
	v_fma_f32 v26, -v121, v54, v26
	v_fma_f32 v25, -v120, v53, v25
	v_fma_f32 v24, -v119, v52, v24
	s_waitcnt lgkmcnt(3)
	v_fma_f32 v27, -v126, v59, v27
	v_fma_f32 v26, -v125, v58, v26
	v_fma_f32 v25, -v124, v57, v25
	v_fma_f32 v24, -v123, v56, v24
	s_waitcnt lgkmcnt(2)
	v_fma_f32 v27, -v135, v63, v27
	v_fma_f32 v26, -v134, v62, v26
	v_fma_f32 v25, -v133, v61, v25
	v_fma_f32 v24, -v127, v60, v24
	s_waitcnt lgkmcnt(1)
	v_fma_f32 v27, -v139, v75, v27
	v_fma_f32 v26, -v138, v74, v26
	v_fma_f32 v25, -v137, v73, v25
	v_fma_f32 v24, -v136, v72, v24
	s_waitcnt lgkmcnt(0)
	v_fmac_f32_e32 v27, 0x80000000, v79
	v_fmac_f32_e32 v26, 0x80000000, v78
	v_fmac_f32_e32 v25, 0x80000000, v77
	v_fma_f32 v24, -v76, v140, v24
	v_add_f32_e32 v24, v25, v24
	v_add_f32_e32 v25, v26, v27
	v_add_f32_e32 v141, v25, v24
	ds_read_b128 v[24:27], v92 offset:11776
	ds_read_b128 v[28:31], v92 offset:11792
	v_add_u32_e32 v80, v70, v97
	ds_read_b128 v[32:35], v92 offset:11808
	ds_read_b128 v[36:39], v92 offset:11824
	s_waitcnt lgkmcnt(3)
	v_fma_f32 v25, -v90, v25, 0
	s_waitcnt lgkmcnt(2)
	v_fma_f32 v25, -v95, v29, v25
	ds_read_u16 v29, v80
	ds_read_b128 v[40:43], v92 offset:11840
	v_mul_f32_e32 v24, v89, v24
	v_fma_f32 v27, -v93, v27, 0
	ds_read_b128 v[44:47], v92 offset:11856
	s_waitcnt lgkmcnt(2)
	v_lshlrev_b32_e32 v29, 16, v29
	v_fma_f32 v26, -v91, v26, 0
	v_fma_f32 v24, v68, v29, -v24
	v_fma_f32 v27, -v98, v31, v27
	ds_read_b128 v[48:51], v92 offset:11872
	v_fma_f32 v26, -v96, v30, v26
	v_fma_f32 v24, -v94, v28, v24
	v_fma_f32 v27, -v102, v35, v27
	ds_read_b128 v[52:55], v92 offset:11888
	v_fma_f32 v26, -v101, v34, v26
	v_fma_f32 v25, -v100, v33, v25
	v_fma_f32 v24, -v99, v32, v24
	v_fma_f32 v27, -v106, v39, v27
	ds_read_b128 v[56:59], v92 offset:11904
	v_fma_f32 v26, -v105, v38, v26
	v_fma_f32 v25, -v104, v37, v25
	v_fma_f32 v24, -v103, v36, v24
	s_waitcnt lgkmcnt(4)
	v_fma_f32 v27, -v110, v43, v27
	ds_read_b128 v[60:63], v92 offset:11920
	v_fma_f32 v26, -v109, v42, v26
	v_fma_f32 v25, -v108, v41, v25
	v_fma_f32 v24, -v107, v40, v24
	s_waitcnt lgkmcnt(4)
	v_fma_f32 v27, -v114, v47, v27
	ds_read_b128 v[64:67], v92 offset:11936
	v_fma_f32 v26, -v113, v46, v26
	v_fma_f32 v25, -v112, v45, v25
	v_fma_f32 v24, -v111, v44, v24
	s_waitcnt lgkmcnt(4)
	v_fma_f32 v27, -v118, v51, v27
	ds_read_b128 v[70:73], v92 offset:11952
	v_fma_f32 v26, -v117, v50, v26
	v_fma_f32 v25, -v116, v49, v25
	v_fma_f32 v24, -v115, v48, v24
	s_waitcnt lgkmcnt(4)
	v_fma_f32 v27, -v122, v55, v27
	v_fma_f32 v26, -v121, v54, v26
	v_fma_f32 v25, -v120, v53, v25
	v_fma_f32 v24, -v119, v52, v24
	s_waitcnt lgkmcnt(3)
	v_fma_f32 v27, -v126, v59, v27
	v_fma_f32 v26, -v125, v58, v26
	v_fma_f32 v25, -v124, v57, v25
	v_fma_f32 v24, -v123, v56, v24
	s_waitcnt lgkmcnt(2)
	v_fma_f32 v27, -v135, v63, v27
	v_fma_f32 v26, -v134, v62, v26
	v_fma_f32 v25, -v133, v61, v25
	v_fma_f32 v24, -v127, v60, v24
	s_waitcnt lgkmcnt(1)
	v_fma_f32 v27, -v139, v67, v27
	v_fma_f32 v26, -v138, v66, v26
	v_fma_f32 v25, -v137, v65, v25
	v_fma_f32 v24, -v136, v64, v24
	s_waitcnt lgkmcnt(0)
	v_fmac_f32_e32 v27, 0x80000000, v73
	v_fmac_f32_e32 v26, 0x80000000, v72
	v_fma_f32 v25, -v71, v141, v25
	v_fma_f32 v24, -v140, v70, v24
	v_add_f32_e32 v24, v25, v24
	v_add_f32_e32 v25, v26, v27
	v_add_f32_e32 v142, v25, v24
	ds_read_b128 v[24:27], v92 offset:12032
	ds_read_b128 v[28:31], v92 offset:12048
	v_add_u32_e32 v74, v80, v97
	ds_read_b128 v[32:35], v92 offset:12064
	ds_read_b128 v[36:39], v92 offset:12080
	s_waitcnt lgkmcnt(3)
	v_fma_f32 v25, -v90, v25, 0
	s_waitcnt lgkmcnt(2)
	v_fma_f32 v25, -v95, v29, v25
	ds_read_u16 v29, v74
	ds_read_b128 v[40:43], v92 offset:12096
	v_mul_f32_e32 v24, v89, v24
	v_fma_f32 v27, -v93, v27, 0
	ds_read_b128 v[44:47], v92 offset:12112
	s_waitcnt lgkmcnt(2)
	v_lshlrev_b32_e32 v29, 16, v29
	v_fma_f32 v26, -v91, v26, 0
	v_fma_f32 v24, v69, v29, -v24
	v_fma_f32 v27, -v98, v31, v27
	ds_read_b128 v[48:51], v92 offset:12128
	v_fma_f32 v26, -v96, v30, v26
	v_fma_f32 v24, -v94, v28, v24
	v_fma_f32 v27, -v102, v35, v27
	ds_read_b128 v[52:55], v92 offset:12144
	v_fma_f32 v26, -v101, v34, v26
	v_fma_f32 v25, -v100, v33, v25
	v_fma_f32 v24, -v99, v32, v24
	v_fma_f32 v27, -v106, v39, v27
	ds_read_b128 v[56:59], v92 offset:12160
	v_fma_f32 v26, -v105, v38, v26
	v_fma_f32 v25, -v104, v37, v25
	v_fma_f32 v24, -v103, v36, v24
	s_waitcnt lgkmcnt(4)
	v_fma_f32 v27, -v110, v43, v27
	ds_read_b128 v[60:63], v92 offset:12176
	v_fma_f32 v26, -v109, v42, v26
	v_fma_f32 v25, -v108, v41, v25
	v_fma_f32 v24, -v107, v40, v24
	s_waitcnt lgkmcnt(4)
	v_fma_f32 v27, -v114, v47, v27
	ds_read_b128 v[64:67], v92 offset:12192
	v_fma_f32 v26, -v113, v46, v26
	v_fma_f32 v25, -v112, v45, v25
	v_fma_f32 v24, -v111, v44, v24
	s_waitcnt lgkmcnt(4)
	v_fma_f32 v27, -v118, v51, v27
	ds_read_b128 v[70:73], v92 offset:12208
	v_fma_f32 v26, -v117, v50, v26
	v_fma_f32 v25, -v116, v49, v25
	v_fma_f32 v24, -v115, v48, v24
	s_waitcnt lgkmcnt(4)
	v_fma_f32 v27, -v122, v55, v27
	v_fma_f32 v26, -v121, v54, v26
	v_fma_f32 v25, -v120, v53, v25
	v_fma_f32 v24, -v119, v52, v24
	s_waitcnt lgkmcnt(3)
	v_fma_f32 v27, -v126, v59, v27
	v_fma_f32 v26, -v125, v58, v26
	v_fma_f32 v25, -v124, v57, v25
	v_fma_f32 v24, -v123, v56, v24
	ds_read_b128 v[28:31], v92 offset:12288
	s_waitcnt lgkmcnt(3)
	v_fma_f32 v27, -v135, v63, v27
	v_fma_f32 v26, -v134, v62, v26
	v_fma_f32 v25, -v133, v61, v25
	v_fma_f32 v24, -v127, v60, v24
	ds_read_b128 v[32:35], v92 offset:12304
	s_waitcnt lgkmcnt(3)
	v_fma_f32 v27, -v139, v67, v27
	v_fma_f32 v26, -v138, v66, v26
	v_fma_f32 v25, -v137, v65, v25
	v_fma_f32 v24, -v136, v64, v24
	ds_read_b128 v[36:39], v92 offset:12320
	s_waitcnt lgkmcnt(3)
	v_fmac_f32_e32 v27, 0x80000000, v73
	v_fma_f32 v26, -v72, v142, v26
	v_fma_f32 v25, -v141, v71, v25
	v_fma_f32 v24, -v140, v70, v24
	ds_read_b128 v[40:43], v92 offset:12336
	v_add_f32_e32 v24, v25, v24
	v_add_f32_e32 v25, v27, v26
	ds_read_b128 v[44:47], v92 offset:12352
	v_add_f32_e32 v143, v25, v24
	s_waitcnt lgkmcnt(4)
	v_fma_f32 v24, -v93, v31, 0
	ds_read_b128 v[48:51], v92 offset:12368
	s_waitcnt lgkmcnt(4)
	v_fma_f32 v24, -v98, v35, v24
	ds_read_b128 v[52:55], v92 offset:12384
	s_waitcnt lgkmcnt(4)
	v_fma_f32 v24, -v102, v39, v24
	ds_read_b128 v[56:59], v92 offset:12400
	s_waitcnt lgkmcnt(4)
	v_fma_f32 v24, -v106, v43, v24
	ds_read_b128 v[60:63], v92 offset:12416
	s_waitcnt lgkmcnt(4)
	v_fma_f32 v24, -v110, v47, v24
	ds_read_b128 v[64:67], v92 offset:12432
	s_waitcnt lgkmcnt(4)
	v_fma_f32 v24, -v114, v51, v24
	ds_read_b128 v[68:71], v92 offset:12448
	v_add_u32_e32 v76, v74, v97
	s_waitcnt lgkmcnt(4)
	v_fma_f32 v24, -v118, v55, v24
	ds_read_b128 v[72:75], v92 offset:12464
	s_waitcnt lgkmcnt(4)
	v_fma_f32 v24, -v122, v59, v24
	s_waitcnt lgkmcnt(3)
	v_fma_f32 v24, -v126, v63, v24
	s_waitcnt lgkmcnt(2)
	v_fma_f32 v24, -v135, v67, v24
	s_waitcnt lgkmcnt(1)
	v_fma_f32 v24, -v139, v71, v24
	s_waitcnt lgkmcnt(0)
	v_fma_f32 v31, -v75, v143, v24
	v_fma_f32 v24, -v91, v30, 0
	v_fma_f32 v24, -v96, v34, v24
	v_fma_f32 v24, -v101, v38, v24
	v_fma_f32 v24, -v105, v42, v24
	v_fma_f32 v24, -v109, v46, v24
	v_fma_f32 v24, -v113, v50, v24
	v_fma_f32 v24, -v117, v54, v24
	v_fma_f32 v24, -v121, v58, v24
	v_fma_f32 v24, -v125, v62, v24
	v_fma_f32 v24, -v134, v66, v24
	v_fma_f32 v24, -v138, v70, v24
	v_fma_f32 v30, -v142, v74, v24
	v_fma_f32 v24, -v90, v29, 0
	v_fma_f32 v24, -v95, v33, v24
	v_fma_f32 v24, -v100, v37, v24
	v_fma_f32 v24, -v104, v41, v24
	v_fma_f32 v24, -v108, v45, v24
	v_fma_f32 v24, -v112, v49, v24
	v_fma_f32 v24, -v116, v53, v24
	v_fma_f32 v24, -v120, v57, v24
	v_fma_f32 v24, -v124, v61, v24
	v_fma_f32 v24, -v133, v65, v24
	v_fma_f32 v24, -v137, v69, v24
	v_fma_f32 v29, -v141, v73, v24
	ds_read_b128 v[24:27], v84 offset:192
	ds_read_u16 v33, v76
	v_mul_f32_e32 v28, v89, v28
	v_add_u32_e32 v80, v76, v97
	ds_read_b128 v[76:79], v92 offset:12736
	s_waitcnt lgkmcnt(1)
	v_lshlrev_b32_e32 v33, 16, v33
	v_fma_f32 v24, v24, v33, -v28
	v_fma_f32 v24, -v94, v32, v24
	v_fma_f32 v24, -v99, v36, v24
	v_fma_f32 v24, -v103, v40, v24
	v_fma_f32 v24, -v107, v44, v24
	v_fma_f32 v24, -v111, v48, v24
	v_fma_f32 v24, -v115, v52, v24
	v_fma_f32 v24, -v119, v56, v24
	v_fma_f32 v24, -v123, v60, v24
	v_fma_f32 v24, -v127, v64, v24
	v_fma_f32 v24, -v136, v68, v24
	v_fma_f32 v24, -v140, v72, v24
	v_add_f32_e32 v24, v29, v24
	v_add_f32_e32 v28, v30, v31
	v_add_f32_e32 v144, v28, v24
	ds_read_b128 v[28:31], v92 offset:12544
	ds_read_b128 v[32:35], v92 offset:12560
	ds_read_b128 v[36:39], v92 offset:12576
	ds_read_b128 v[40:43], v92 offset:12592
	ds_read_b128 v[44:47], v92 offset:12608
	s_waitcnt lgkmcnt(4)
	v_fma_f32 v29, -v90, v29, 0
	s_waitcnt lgkmcnt(3)
	v_fma_f32 v29, -v95, v33, v29
	ds_read_u16 v33, v80
	v_mul_f32_e32 v28, v89, v28
	v_fma_f32 v31, -v93, v31, 0
	ds_read_b128 v[48:51], v92 offset:12624
	v_fma_f32 v30, -v91, v30, 0
	s_waitcnt lgkmcnt(1)
	v_lshlrev_b32_e32 v33, 16, v33
	v_fma_f32 v25, v25, v33, -v28
	v_fma_f32 v31, -v98, v35, v31
	ds_read_b128 v[52:55], v92 offset:12640
	v_fma_f32 v30, -v96, v34, v30
	v_fma_f32 v25, -v94, v32, v25
	v_fma_f32 v31, -v102, v39, v31
	ds_read_b128 v[56:59], v92 offset:12656
	v_fma_f32 v30, -v101, v38, v30
	v_fma_f32 v29, -v100, v37, v29
	v_fma_f32 v25, -v99, v36, v25
	v_fma_f32 v31, -v106, v43, v31
	ds_read_b128 v[60:63], v92 offset:12672
	v_fma_f32 v30, -v105, v42, v30
	v_fma_f32 v29, -v104, v41, v29
	v_fma_f32 v25, -v103, v40, v25
	v_fma_f32 v31, -v110, v47, v31
	ds_read_b128 v[64:67], v92 offset:12688
	v_fma_f32 v30, -v109, v46, v30
	v_fma_f32 v29, -v108, v45, v29
	v_fma_f32 v25, -v107, v44, v25
	s_waitcnt lgkmcnt(4)
	v_fma_f32 v31, -v114, v51, v31
	ds_read_b128 v[68:71], v92 offset:12704
	v_fma_f32 v30, -v113, v50, v30
	v_fma_f32 v29, -v112, v49, v29
	v_fma_f32 v25, -v111, v48, v25
	s_waitcnt lgkmcnt(4)
	v_fma_f32 v31, -v118, v55, v31
	ds_read_b128 v[72:75], v92 offset:12720
	v_fma_f32 v30, -v117, v54, v30
	v_fma_f32 v29, -v116, v53, v29
	v_fma_f32 v25, -v115, v52, v25
	s_waitcnt lgkmcnt(4)
	v_fma_f32 v31, -v122, v59, v31
	v_fma_f32 v30, -v121, v58, v30
	v_fma_f32 v29, -v120, v57, v29
	v_fma_f32 v25, -v119, v56, v25
	s_waitcnt lgkmcnt(3)
	v_fma_f32 v31, -v126, v63, v31
	v_fma_f32 v30, -v125, v62, v30
	v_fma_f32 v29, -v124, v61, v29
	v_fma_f32 v25, -v123, v60, v25
	s_waitcnt lgkmcnt(2)
	v_fma_f32 v31, -v135, v67, v31
	v_fma_f32 v30, -v134, v66, v30
	v_fma_f32 v29, -v133, v65, v29
	v_fma_f32 v25, -v127, v64, v25
	s_waitcnt lgkmcnt(1)
	v_fma_f32 v31, -v139, v71, v31
	v_fma_f32 v30, -v138, v70, v30
	v_fma_f32 v29, -v137, v69, v29
	v_fma_f32 v25, -v136, v68, v25
	s_waitcnt lgkmcnt(0)
	v_fma_f32 v31, -v143, v75, v31
	v_fma_f32 v30, -v142, v74, v30
	v_fma_f32 v29, -v141, v73, v29
	v_fma_f32 v25, -v140, v72, v25
	v_fmac_f32_e32 v31, 0x80000000, v79
	v_fmac_f32_e32 v30, 0x80000000, v78
	v_fmac_f32_e32 v29, 0x80000000, v77
	v_fma_f32 v25, -v76, v144, v25
	v_add_u32_e32 v24, v80, v97
	v_add_f32_e32 v25, v29, v25
	v_add_f32_e32 v28, v30, v31
	v_add_f32_e32 v145, v28, v25
	v_add_u32_e32 v25, v24, v97
	ds_read_b128 v[28:31], v92 offset:12800
	ds_read_u16 v24, v24
	ds_read_b128 v[32:35], v92 offset:12816
	ds_read_b128 v[36:39], v92 offset:12832
	ds_read_b128 v[40:43], v92 offset:12848
	ds_read_b128 v[44:47], v92 offset:12864
	s_waitcnt lgkmcnt(4)
	v_lshlrev_b32_e32 v24, 16, v24
	v_mul_f32_e32 v28, v89, v28
	v_fma_f32 v31, -v93, v31, 0
	ds_read_b128 v[48:51], v92 offset:12880
	v_fma_f32 v30, -v91, v30, 0
	v_fma_f32 v29, -v90, v29, 0
	v_fma_f32 v24, v26, v24, -v28
	s_waitcnt lgkmcnt(4)
	v_fma_f32 v31, -v98, v35, v31
	ds_read_b128 v[52:55], v92 offset:12896
	v_fma_f32 v30, -v96, v34, v30
	v_fma_f32 v29, -v95, v33, v29
	v_fma_f32 v24, -v94, v32, v24
	s_waitcnt lgkmcnt(4)
	v_fma_f32 v31, -v102, v39, v31
	ds_read_b128 v[56:59], v92 offset:12912
	v_fma_f32 v30, -v101, v38, v30
	v_fma_f32 v29, -v100, v37, v29
	v_fma_f32 v24, -v99, v36, v24
	s_waitcnt lgkmcnt(4)
	v_fma_f32 v31, -v106, v43, v31
	ds_read_b128 v[60:63], v92 offset:12928
	v_fma_f32 v30, -v105, v42, v30
	v_fma_f32 v29, -v104, v41, v29
	v_fma_f32 v24, -v103, v40, v24
	s_waitcnt lgkmcnt(4)
	v_fma_f32 v31, -v110, v47, v31
	ds_read_b128 v[64:67], v92 offset:12944
	v_fma_f32 v30, -v109, v46, v30
	v_fma_f32 v29, -v108, v45, v29
	v_fma_f32 v24, -v107, v44, v24
	s_waitcnt lgkmcnt(4)
	v_fma_f32 v31, -v114, v51, v31
	ds_read_b128 v[68:71], v92 offset:12960
	v_fma_f32 v30, -v113, v50, v30
	v_fma_f32 v29, -v112, v49, v29
	v_fma_f32 v24, -v111, v48, v24
	s_waitcnt lgkmcnt(4)
	v_fma_f32 v31, -v118, v55, v31
	ds_read_b128 v[72:75], v92 offset:12976
	v_fma_f32 v30, -v117, v54, v30
	v_fma_f32 v29, -v116, v53, v29
	v_fma_f32 v24, -v115, v52, v24
	s_waitcnt lgkmcnt(4)
	v_fma_f32 v31, -v122, v59, v31
	ds_read_b128 v[76:79], v92 offset:12992
	v_fma_f32 v30, -v121, v58, v30
	v_fma_f32 v29, -v120, v57, v29
	v_fma_f32 v24, -v119, v56, v24
	s_waitcnt lgkmcnt(4)
	v_fma_f32 v31, -v126, v63, v31
	v_fma_f32 v30, -v125, v62, v30
	v_fma_f32 v29, -v124, v61, v29
	v_fma_f32 v24, -v123, v60, v24
	s_waitcnt lgkmcnt(3)
	v_fma_f32 v31, -v135, v67, v31
	v_fma_f32 v30, -v134, v66, v30
	v_fma_f32 v29, -v133, v65, v29
	v_fma_f32 v24, -v127, v64, v24
	s_waitcnt lgkmcnt(2)
	v_fma_f32 v31, -v139, v71, v31
	v_fma_f32 v30, -v138, v70, v30
	v_fma_f32 v29, -v137, v69, v29
	v_fma_f32 v24, -v136, v68, v24
	s_waitcnt lgkmcnt(1)
	v_fma_f32 v31, -v143, v75, v31
	v_fma_f32 v30, -v142, v74, v30
	v_fma_f32 v29, -v141, v73, v29
	v_fma_f32 v24, -v140, v72, v24
	s_waitcnt lgkmcnt(0)
	v_fmac_f32_e32 v31, 0x80000000, v79
	v_fmac_f32_e32 v30, 0x80000000, v78
	v_fma_f32 v29, -v77, v145, v29
	v_fma_f32 v24, -v144, v76, v24
	v_add_f32_e32 v24, v29, v24
	v_add_f32_e32 v26, v30, v31
	v_add_u32_e32 v79, v25, v97
	ds_read_b128 v[28:31], v92 offset:13056
	ds_read_u16 v25, v25
	ds_read_b128 v[32:35], v92 offset:13072
	ds_read_b128 v[36:39], v92 offset:13088
	ds_read_b128 v[40:43], v92 offset:13104
	ds_read_b128 v[44:47], v92 offset:13120
	s_waitcnt lgkmcnt(4)
	v_lshlrev_b32_e32 v25, 16, v25
	v_mul_f32_e32 v28, v89, v28
	v_add_f32_e32 v146, v26, v24
	v_fma_f32 v24, -v93, v31, 0
	ds_read_b128 v[48:51], v92 offset:13136
	v_fma_f32 v26, -v91, v30, 0
	v_fma_f32 v29, -v90, v29, 0
	v_fma_f32 v25, v27, v25, -v28
	s_waitcnt lgkmcnt(4)
	v_fma_f32 v24, -v98, v35, v24
	ds_read_b128 v[52:55], v92 offset:13152
	v_fma_f32 v26, -v96, v34, v26
	v_fma_f32 v29, -v95, v33, v29
	v_fma_f32 v25, -v94, v32, v25
	s_waitcnt lgkmcnt(4)
	v_fma_f32 v24, -v102, v39, v24
	ds_read_b128 v[56:59], v92 offset:13168
	v_fma_f32 v26, -v101, v38, v26
	v_fma_f32 v29, -v100, v37, v29
	v_fma_f32 v25, -v99, v36, v25
	s_waitcnt lgkmcnt(4)
	v_fma_f32 v24, -v106, v43, v24
	ds_read_b128 v[60:63], v92 offset:13184
	v_fma_f32 v26, -v105, v42, v26
	v_fma_f32 v29, -v104, v41, v29
	v_fma_f32 v25, -v103, v40, v25
	s_waitcnt lgkmcnt(4)
	v_fma_f32 v24, -v110, v47, v24
	ds_read_b128 v[64:67], v92 offset:13200
	v_fma_f32 v26, -v109, v46, v26
	v_fma_f32 v29, -v108, v45, v29
	v_fma_f32 v25, -v107, v44, v25
	s_waitcnt lgkmcnt(4)
	v_fma_f32 v24, -v114, v51, v24
	ds_read_b128 v[68:71], v92 offset:13216
	v_fma_f32 v26, -v113, v50, v26
	v_fma_f32 v29, -v112, v49, v29
	v_fma_f32 v25, -v111, v48, v25
	s_waitcnt lgkmcnt(4)
	v_fma_f32 v24, -v118, v55, v24
	ds_read_b128 v[72:75], v92 offset:13232
	v_fma_f32 v26, -v117, v54, v26
	v_fma_f32 v29, -v116, v53, v29
	v_fma_f32 v25, -v115, v52, v25
	s_waitcnt lgkmcnt(4)
	v_fma_f32 v24, -v122, v59, v24
	ds_read_b128 v[80:83], v92 offset:13248
	v_fma_f32 v26, -v121, v58, v26
	v_fma_f32 v29, -v120, v57, v29
	v_fma_f32 v25, -v119, v56, v25
	s_waitcnt lgkmcnt(4)
	v_fma_f32 v24, -v126, v63, v24
	v_fma_f32 v26, -v125, v62, v26
	v_fma_f32 v29, -v124, v61, v29
	v_fma_f32 v25, -v123, v60, v25
	s_waitcnt lgkmcnt(3)
	v_fma_f32 v24, -v135, v67, v24
	v_fma_f32 v26, -v134, v66, v26
	v_fma_f32 v29, -v133, v65, v29
	v_fma_f32 v25, -v127, v64, v25
	s_waitcnt lgkmcnt(2)
	v_fma_f32 v24, -v139, v71, v24
	v_fma_f32 v26, -v138, v70, v26
	v_fma_f32 v29, -v137, v69, v29
	v_fma_f32 v25, -v136, v68, v25
	s_waitcnt lgkmcnt(1)
	v_fma_f32 v24, -v143, v75, v24
	v_fma_f32 v26, -v142, v74, v26
	v_fma_f32 v29, -v141, v73, v29
	v_fma_f32 v25, -v140, v72, v25
	s_waitcnt lgkmcnt(0)
	v_fmac_f32_e32 v24, 0x80000000, v83
	v_fma_f32 v26, -v82, v146, v26
	v_fma_f32 v29, -v145, v81, v29
	v_fma_f32 v25, -v144, v80, v25
	v_add_f32_e32 v25, v29, v25
	v_add_f32_e32 v24, v24, v26
	v_add_f32_e32 v147, v24, v25
	ds_read_b128 v[24:27], v92 offset:13312
	ds_read_b128 v[28:31], v92 offset:13328
	ds_read_b128 v[32:35], v92 offset:13344
	ds_read_b128 v[36:39], v92 offset:13360
	ds_read_b128 v[40:43], v92 offset:13376
	s_waitcnt lgkmcnt(4)
	v_fma_f32 v27, -v93, v27, 0
	ds_read_b128 v[44:47], v92 offset:13392
	v_fma_f32 v26, -v91, v26, 0
	s_waitcnt lgkmcnt(4)
	v_fma_f32 v27, -v98, v31, v27
	ds_read_b128 v[48:51], v92 offset:13408
	v_fma_f32 v26, -v96, v30, v26
	s_waitcnt lgkmcnt(4)
	v_fma_f32 v27, -v102, v35, v27
	ds_read_b128 v[52:55], v92 offset:13424
	v_fma_f32 v26, -v101, v34, v26
	s_waitcnt lgkmcnt(4)
	v_fma_f32 v27, -v106, v39, v27
	ds_read_b128 v[56:59], v92 offset:13440
	v_fma_f32 v26, -v105, v38, v26
	s_waitcnt lgkmcnt(4)
	v_fma_f32 v27, -v110, v43, v27
	ds_read_b128 v[60:63], v92 offset:13456
	v_fma_f32 v26, -v109, v42, v26
	s_waitcnt lgkmcnt(4)
	v_fma_f32 v27, -v114, v47, v27
	ds_read_b128 v[64:67], v92 offset:13472
	v_fma_f32 v26, -v113, v46, v26
	s_waitcnt lgkmcnt(4)
	v_fma_f32 v27, -v118, v51, v27
	ds_read_b128 v[68:71], v92 offset:13488
	v_fma_f32 v26, -v117, v50, v26
	s_waitcnt lgkmcnt(4)
	v_fma_f32 v27, -v122, v55, v27
	ds_read_b128 v[72:75], v92 offset:13504
	v_fma_f32 v26, -v121, v54, v26
	s_waitcnt lgkmcnt(4)
	v_fma_f32 v27, -v126, v59, v27
	v_fma_f32 v26, -v125, v58, v26
	s_waitcnt lgkmcnt(3)
	v_fma_f32 v27, -v135, v63, v27
	v_fma_f32 v26, -v134, v62, v26
	s_waitcnt lgkmcnt(2)
	v_fma_f32 v27, -v139, v67, v27
	v_fma_f32 v26, -v138, v66, v26
	s_waitcnt lgkmcnt(1)
	v_fma_f32 v27, -v143, v71, v27
	v_fma_f32 v26, -v142, v70, v26
	v_fma_f32 v25, -v90, v25, 0
	s_waitcnt lgkmcnt(0)
	v_fma_f32 v27, -v75, v147, v27
	v_fma_f32 v26, -v146, v74, v26
	v_fma_f32 v25, -v95, v29, v25
	ds_read_b128 v[74:77], v84 offset:208
	ds_read_u16 v29, v79
	v_mul_f32_e32 v24, v89, v24
	v_fma_f32 v25, -v100, v33, v25
	v_fma_f32 v25, -v104, v37, v25
	v_fma_f32 v25, -v108, v41, v25
	s_waitcnt lgkmcnt(0)
	v_lshlrev_b32_e32 v29, 16, v29
	v_fma_f32 v24, v74, v29, -v24
	v_fma_f32 v24, -v94, v28, v24
	v_fma_f32 v24, -v99, v32, v24
	v_fma_f32 v24, -v103, v36, v24
	v_fma_f32 v24, -v107, v40, v24
	v_fma_f32 v25, -v112, v45, v25
	v_fma_f32 v24, -v111, v44, v24
	v_fma_f32 v25, -v116, v49, v25
	v_fma_f32 v24, -v115, v48, v24
	v_fma_f32 v25, -v120, v53, v25
	v_fma_f32 v24, -v119, v52, v24
	v_fma_f32 v25, -v124, v57, v25
	v_fma_f32 v24, -v123, v56, v24
	v_fma_f32 v25, -v133, v61, v25
	v_fma_f32 v24, -v127, v60, v24
	v_fma_f32 v25, -v137, v65, v25
	v_fma_f32 v24, -v136, v64, v24
	v_fma_f32 v25, -v141, v69, v25
	v_fma_f32 v24, -v140, v68, v24
	v_fma_f32 v25, -v145, v73, v25
	v_fma_f32 v24, -v144, v72, v24
	v_add_f32_e32 v24, v25, v24
	v_add_f32_e32 v25, v26, v27
	v_add_f32_e32 v148, v25, v24
	ds_read_b128 v[24:27], v92 offset:13568
	ds_read_b128 v[28:31], v92 offset:13584
	v_add_u32_e32 v78, v79, v97
	ds_read_b128 v[32:35], v92 offset:13600
	ds_read_b128 v[36:39], v92 offset:13616
	s_waitcnt lgkmcnt(3)
	v_fma_f32 v25, -v90, v25, 0
	s_waitcnt lgkmcnt(2)
	v_fma_f32 v25, -v95, v29, v25
	ds_read_u16 v29, v78
	ds_read_b128 v[40:43], v92 offset:13632
	v_mul_f32_e32 v24, v89, v24
	v_fma_f32 v27, -v93, v27, 0
	ds_read_b128 v[44:47], v92 offset:13648
	s_waitcnt lgkmcnt(2)
	v_lshlrev_b32_e32 v29, 16, v29
	v_fma_f32 v26, -v91, v26, 0
	v_fma_f32 v24, v75, v29, -v24
	v_fma_f32 v27, -v98, v31, v27
	ds_read_b128 v[48:51], v92 offset:13664
	v_fma_f32 v26, -v96, v30, v26
	v_fma_f32 v24, -v94, v28, v24
	v_fma_f32 v27, -v102, v35, v27
	ds_read_b128 v[52:55], v92 offset:13680
	v_fma_f32 v26, -v101, v34, v26
	v_fma_f32 v25, -v100, v33, v25
	v_fma_f32 v24, -v99, v32, v24
	v_fma_f32 v27, -v106, v39, v27
	ds_read_b128 v[56:59], v92 offset:13696
	v_fma_f32 v26, -v105, v38, v26
	v_fma_f32 v25, -v104, v37, v25
	v_fma_f32 v24, -v103, v36, v24
	s_waitcnt lgkmcnt(4)
	v_fma_f32 v27, -v110, v43, v27
	ds_read_b128 v[60:63], v92 offset:13712
	v_fma_f32 v26, -v109, v42, v26
	v_fma_f32 v25, -v108, v41, v25
	v_fma_f32 v24, -v107, v40, v24
	s_waitcnt lgkmcnt(4)
	v_fma_f32 v27, -v114, v47, v27
	ds_read_b128 v[64:67], v92 offset:13728
	v_fma_f32 v26, -v113, v46, v26
	v_fma_f32 v25, -v112, v45, v25
	v_fma_f32 v24, -v111, v44, v24
	s_waitcnt lgkmcnt(4)
	v_fma_f32 v27, -v118, v51, v27
	ds_read_b128 v[68:71], v92 offset:13744
	v_fma_f32 v26, -v117, v50, v26
	v_fma_f32 v25, -v116, v49, v25
	v_fma_f32 v24, -v115, v48, v24
	s_waitcnt lgkmcnt(4)
	v_fma_f32 v27, -v122, v55, v27
	ds_read_b128 v[80:83], v92 offset:13760
	ds_read_b128 v[150:153], v92 offset:13776
	v_fma_f32 v26, -v121, v54, v26
	v_fma_f32 v25, -v120, v53, v25
	v_fma_f32 v24, -v119, v52, v24
	s_waitcnt lgkmcnt(5)
	v_fma_f32 v27, -v126, v59, v27
	v_fma_f32 v26, -v125, v58, v26
	v_fma_f32 v25, -v124, v57, v25
	v_fma_f32 v24, -v123, v56, v24
	s_waitcnt lgkmcnt(4)
	v_fma_f32 v27, -v135, v63, v27
	v_fma_f32 v26, -v134, v62, v26
	v_fma_f32 v25, -v133, v61, v25
	v_fma_f32 v24, -v127, v60, v24
	s_waitcnt lgkmcnt(3)
	v_fma_f32 v27, -v139, v67, v27
	v_fma_f32 v26, -v138, v66, v26
	v_fma_f32 v25, -v137, v65, v25
	v_fma_f32 v24, -v136, v64, v24
	s_waitcnt lgkmcnt(2)
	v_fma_f32 v27, -v143, v71, v27
	v_fma_f32 v26, -v142, v70, v26
	v_fma_f32 v25, -v141, v69, v25
	v_fma_f32 v24, -v140, v68, v24
	s_waitcnt lgkmcnt(1)
	v_fma_f32 v27, -v147, v83, v27
	v_fma_f32 v26, -v146, v82, v26
	v_fma_f32 v25, -v145, v81, v25
	v_fma_f32 v24, -v144, v80, v24
	s_waitcnt lgkmcnt(0)
	v_fmac_f32_e32 v27, 0x80000000, v153
	v_fmac_f32_e32 v26, 0x80000000, v152
	v_fmac_f32_e32 v25, 0x80000000, v151
	v_fma_f32 v24, -v150, v148, v24
	v_add_f32_e32 v24, v25, v24
	v_add_f32_e32 v25, v26, v27
	v_add_f32_e32 v149, v25, v24
	ds_read_b128 v[24:27], v92 offset:13824
	ds_read_b128 v[28:31], v92 offset:13840
	v_add_u32_e32 v85, v78, v97
	ds_read_b128 v[32:35], v92 offset:13856
	ds_read_b128 v[36:39], v92 offset:13872
	s_waitcnt lgkmcnt(3)
	v_fma_f32 v25, -v90, v25, 0
	s_waitcnt lgkmcnt(2)
	v_fma_f32 v25, -v95, v29, v25
	ds_read_u16 v29, v85
	ds_read_b128 v[40:43], v92 offset:13888
	v_mul_f32_e32 v24, v89, v24
	v_fma_f32 v27, -v93, v27, 0
	ds_read_b128 v[44:47], v92 offset:13904
	s_waitcnt lgkmcnt(2)
	v_lshlrev_b32_e32 v29, 16, v29
	v_fma_f32 v26, -v91, v26, 0
	v_fma_f32 v24, v76, v29, -v24
	v_fma_f32 v27, -v98, v31, v27
	ds_read_b128 v[48:51], v92 offset:13920
	v_fma_f32 v26, -v96, v30, v26
	v_fma_f32 v24, -v94, v28, v24
	v_fma_f32 v27, -v102, v35, v27
	ds_read_b128 v[52:55], v92 offset:13936
	v_fma_f32 v26, -v101, v34, v26
	v_fma_f32 v25, -v100, v33, v25
	v_fma_f32 v24, -v99, v32, v24
	v_fma_f32 v27, -v106, v39, v27
	ds_read_b128 v[56:59], v92 offset:13952
	v_fma_f32 v26, -v105, v38, v26
	v_fma_f32 v25, -v104, v37, v25
	v_fma_f32 v24, -v103, v36, v24
	s_waitcnt lgkmcnt(4)
	v_fma_f32 v27, -v110, v43, v27
	ds_read_b128 v[60:63], v92 offset:13968
	v_fma_f32 v26, -v109, v42, v26
	v_fma_f32 v25, -v108, v41, v25
	v_fma_f32 v24, -v107, v40, v24
	s_waitcnt lgkmcnt(4)
	v_fma_f32 v27, -v114, v47, v27
	ds_read_b128 v[64:67], v92 offset:13984
	v_fma_f32 v26, -v113, v46, v26
	v_fma_f32 v25, -v112, v45, v25
	v_fma_f32 v24, -v111, v44, v24
	s_waitcnt lgkmcnt(4)
	v_fma_f32 v27, -v118, v51, v27
	ds_read_b128 v[68:71], v92 offset:14000
	v_fma_f32 v26, -v117, v50, v26
	v_fma_f32 v25, -v116, v49, v25
	v_fma_f32 v24, -v115, v48, v24
	s_waitcnt lgkmcnt(4)
	v_fma_f32 v27, -v122, v55, v27
	ds_read_b128 v[72:75], v92 offset:14016
	v_fma_f32 v26, -v121, v54, v26
	v_fma_f32 v25, -v120, v53, v25
	v_fma_f32 v24, -v119, v52, v24
	s_waitcnt lgkmcnt(4)
	v_fma_f32 v27, -v126, v59, v27
	ds_read_b128 v[78:81], v92 offset:14032
	v_fma_f32 v26, -v125, v58, v26
	v_fma_f32 v25, -v124, v57, v25
	v_fma_f32 v24, -v123, v56, v24
	s_waitcnt lgkmcnt(4)
	v_fma_f32 v27, -v135, v63, v27
	v_fma_f32 v26, -v134, v62, v26
	v_fma_f32 v25, -v133, v61, v25
	v_fma_f32 v24, -v127, v60, v24
	s_waitcnt lgkmcnt(3)
	v_fma_f32 v27, -v139, v67, v27
	v_fma_f32 v26, -v138, v66, v26
	v_fma_f32 v25, -v137, v65, v25
	v_fma_f32 v24, -v136, v64, v24
	s_waitcnt lgkmcnt(2)
	v_fma_f32 v27, -v143, v71, v27
	v_fma_f32 v26, -v142, v70, v26
	v_fma_f32 v25, -v141, v69, v25
	v_fma_f32 v24, -v140, v68, v24
	s_waitcnt lgkmcnt(1)
	v_fma_f32 v27, -v147, v75, v27
	v_fma_f32 v26, -v146, v74, v26
	v_fma_f32 v25, -v145, v73, v25
	v_fma_f32 v24, -v144, v72, v24
	s_waitcnt lgkmcnt(0)
	v_fmac_f32_e32 v27, 0x80000000, v81
	v_fmac_f32_e32 v26, 0x80000000, v80
	v_fma_f32 v25, -v79, v149, v25
	v_fma_f32 v24, -v148, v78, v24
	v_add_f32_e32 v24, v25, v24
	v_add_f32_e32 v25, v26, v27
	v_add_f32_e32 v150, v25, v24
	ds_read_b128 v[24:27], v92 offset:14080
	ds_read_b128 v[28:31], v92 offset:14096
	v_add_u32_e32 v82, v85, v97
	ds_read_b128 v[32:35], v92 offset:14112
	ds_read_b128 v[36:39], v92 offset:14128
	s_waitcnt lgkmcnt(3)
	v_fma_f32 v25, -v90, v25, 0
	s_waitcnt lgkmcnt(2)
	v_fma_f32 v25, -v95, v29, v25
	ds_read_u16 v29, v82
	ds_read_b128 v[40:43], v92 offset:14144
	v_mul_f32_e32 v24, v89, v24
	v_fma_f32 v27, -v93, v27, 0
	ds_read_b128 v[44:47], v92 offset:14160
	s_waitcnt lgkmcnt(2)
	v_lshlrev_b32_e32 v29, 16, v29
	v_fma_f32 v26, -v91, v26, 0
	v_fma_f32 v24, v77, v29, -v24
	v_fma_f32 v27, -v98, v31, v27
	ds_read_b128 v[48:51], v92 offset:14176
	v_fma_f32 v26, -v96, v30, v26
	v_fma_f32 v24, -v94, v28, v24
	v_fma_f32 v27, -v102, v35, v27
	ds_read_b128 v[52:55], v92 offset:14192
	v_fma_f32 v26, -v101, v34, v26
	v_fma_f32 v25, -v100, v33, v25
	v_fma_f32 v24, -v99, v32, v24
	v_fma_f32 v27, -v106, v39, v27
	ds_read_b128 v[56:59], v92 offset:14208
	v_fma_f32 v26, -v105, v38, v26
	v_fma_f32 v25, -v104, v37, v25
	v_fma_f32 v24, -v103, v36, v24
	s_waitcnt lgkmcnt(4)
	v_fma_f32 v27, -v110, v43, v27
	ds_read_b128 v[60:63], v92 offset:14224
	v_fma_f32 v26, -v109, v42, v26
	v_fma_f32 v25, -v108, v41, v25
	v_fma_f32 v24, -v107, v40, v24
	s_waitcnt lgkmcnt(4)
	v_fma_f32 v27, -v114, v47, v27
	ds_read_b128 v[64:67], v92 offset:14240
	v_fma_f32 v26, -v113, v46, v26
	v_fma_f32 v25, -v112, v45, v25
	v_fma_f32 v24, -v111, v44, v24
	s_waitcnt lgkmcnt(4)
	v_fma_f32 v27, -v118, v51, v27
	ds_read_b128 v[68:71], v92 offset:14256
	v_fma_f32 v26, -v117, v50, v26
	v_fma_f32 v25, -v116, v49, v25
	v_fma_f32 v24, -v115, v48, v24
	s_waitcnt lgkmcnt(4)
	v_fma_f32 v27, -v122, v55, v27
	ds_read_b128 v[72:75], v92 offset:14272
	v_fma_f32 v26, -v121, v54, v26
	v_fma_f32 v25, -v120, v53, v25
	v_fma_f32 v24, -v119, v52, v24
	s_waitcnt lgkmcnt(4)
	v_fma_f32 v27, -v126, v59, v27
	ds_read_b128 v[78:81], v92 offset:14288
	v_fma_f32 v26, -v125, v58, v26
	v_fma_f32 v25, -v124, v57, v25
	v_fma_f32 v24, -v123, v56, v24
	s_waitcnt lgkmcnt(4)
	v_fma_f32 v27, -v135, v63, v27
	v_fma_f32 v26, -v134, v62, v26
	v_fma_f32 v25, -v133, v61, v25
	v_fma_f32 v24, -v127, v60, v24
	s_waitcnt lgkmcnt(3)
	v_fma_f32 v27, -v139, v67, v27
	v_fma_f32 v26, -v138, v66, v26
	v_fma_f32 v25, -v137, v65, v25
	v_fma_f32 v24, -v136, v64, v24
	ds_read_b128 v[28:31], v92 offset:14336
	s_waitcnt lgkmcnt(3)
	v_fma_f32 v27, -v143, v71, v27
	v_fma_f32 v26, -v142, v70, v26
	v_fma_f32 v25, -v141, v69, v25
	v_fma_f32 v24, -v140, v68, v24
	ds_read_b128 v[32:35], v92 offset:14352
	s_waitcnt lgkmcnt(3)
	v_fma_f32 v27, -v147, v75, v27
	v_fma_f32 v26, -v146, v74, v26
	v_fma_f32 v25, -v145, v73, v25
	v_fma_f32 v24, -v144, v72, v24
	ds_read_b128 v[36:39], v92 offset:14368
	s_waitcnt lgkmcnt(3)
	v_fmac_f32_e32 v27, 0x80000000, v81
	v_fma_f32 v26, -v80, v150, v26
	v_fma_f32 v25, -v149, v79, v25
	v_fma_f32 v24, -v148, v78, v24
	ds_read_b128 v[40:43], v92 offset:14384
	v_add_f32_e32 v24, v25, v24
	v_add_f32_e32 v25, v27, v26
	ds_read_b128 v[44:47], v92 offset:14400
	v_add_f32_e32 v151, v25, v24
	s_waitcnt lgkmcnt(4)
	v_fma_f32 v24, -v93, v31, 0
	ds_read_b128 v[48:51], v92 offset:14416
	s_waitcnt lgkmcnt(4)
	v_fma_f32 v24, -v98, v35, v24
	ds_read_b128 v[52:55], v92 offset:14432
	s_waitcnt lgkmcnt(4)
	v_fma_f32 v24, -v102, v39, v24
	ds_read_b128 v[56:59], v92 offset:14448
	s_waitcnt lgkmcnt(4)
	v_fma_f32 v24, -v106, v43, v24
	ds_read_b128 v[60:63], v92 offset:14464
	s_waitcnt lgkmcnt(4)
	v_fma_f32 v24, -v110, v47, v24
	ds_read_b128 v[64:67], v92 offset:14480
	s_waitcnt lgkmcnt(4)
	v_fma_f32 v24, -v114, v51, v24
	ds_read_b128 v[68:71], v92 offset:14496
	s_waitcnt lgkmcnt(4)
	v_fma_f32 v24, -v118, v55, v24
	ds_read_b128 v[72:75], v92 offset:14512
	s_waitcnt lgkmcnt(4)
	v_fma_f32 v24, -v122, v59, v24
	ds_read_b128 v[76:79], v92 offset:14528
	v_add_u32_e32 v85, v82, v97
	s_waitcnt lgkmcnt(4)
	v_fma_f32 v24, -v126, v63, v24
	ds_read_b128 v[80:83], v92 offset:14544
	s_waitcnt lgkmcnt(4)
	v_fma_f32 v24, -v135, v67, v24
	s_waitcnt lgkmcnt(3)
	v_fma_f32 v24, -v139, v71, v24
	s_waitcnt lgkmcnt(2)
	v_fma_f32 v24, -v143, v75, v24
	s_waitcnt lgkmcnt(1)
	v_fma_f32 v24, -v147, v79, v24
	s_waitcnt lgkmcnt(0)
	v_fma_f32 v31, -v83, v151, v24
	v_fma_f32 v24, -v91, v30, 0
	v_fma_f32 v24, -v96, v34, v24
	v_fma_f32 v24, -v101, v38, v24
	v_fma_f32 v24, -v105, v42, v24
	v_fma_f32 v24, -v109, v46, v24
	v_fma_f32 v24, -v113, v50, v24
	v_fma_f32 v24, -v117, v54, v24
	v_fma_f32 v24, -v121, v58, v24
	v_fma_f32 v24, -v125, v62, v24
	v_fma_f32 v24, -v134, v66, v24
	v_fma_f32 v24, -v138, v70, v24
	v_fma_f32 v24, -v142, v74, v24
	v_fma_f32 v24, -v146, v78, v24
	v_fma_f32 v30, -v150, v82, v24
	v_fma_f32 v24, -v90, v29, 0
	v_fma_f32 v24, -v95, v33, v24
	v_fma_f32 v24, -v100, v37, v24
	v_fma_f32 v24, -v104, v41, v24
	v_fma_f32 v24, -v108, v45, v24
	v_fma_f32 v24, -v112, v49, v24
	v_fma_f32 v24, -v116, v53, v24
	v_fma_f32 v24, -v120, v57, v24
	v_fma_f32 v24, -v124, v61, v24
	v_fma_f32 v24, -v133, v65, v24
	v_fma_f32 v24, -v137, v69, v24
	v_fma_f32 v24, -v141, v73, v24
	v_fma_f32 v24, -v145, v77, v24
	v_fma_f32 v29, -v149, v81, v24
	ds_read_b128 v[24:27], v84 offset:224
	ds_read_u16 v33, v85
	v_mul_f32_e32 v28, v89, v28
	v_add_u32_e32 v153, v85, v97
	ds_read_b128 v[154:157], v92 offset:14816
	ds_read_b128 v[158:161], v92 offset:15328
	s_waitcnt lgkmcnt(2)
	v_lshlrev_b32_e32 v33, 16, v33
	v_fma_f32 v24, v24, v33, -v28
	v_fma_f32 v24, -v94, v32, v24
	v_fma_f32 v24, -v99, v36, v24
	v_fma_f32 v24, -v103, v40, v24
	v_fma_f32 v24, -v107, v44, v24
	v_fma_f32 v24, -v111, v48, v24
	v_fma_f32 v24, -v115, v52, v24
	v_fma_f32 v24, -v119, v56, v24
	v_fma_f32 v24, -v123, v60, v24
	v_fma_f32 v24, -v127, v64, v24
	v_fma_f32 v24, -v136, v68, v24
	v_fma_f32 v24, -v140, v72, v24
	v_fma_f32 v24, -v144, v76, v24
	v_fma_f32 v24, -v148, v80, v24
	v_add_f32_e32 v24, v29, v24
	v_add_f32_e32 v28, v30, v31
	v_add_f32_e32 v152, v28, v24
	ds_read_b128 v[28:31], v92 offset:14592
	ds_read_b128 v[32:35], v92 offset:14608
	ds_read_b128 v[36:39], v92 offset:14624
	ds_read_b128 v[40:43], v92 offset:14640
	ds_read_b128 v[44:47], v92 offset:14656
	s_waitcnt lgkmcnt(4)
	v_fma_f32 v29, -v90, v29, 0
	s_waitcnt lgkmcnt(3)
	v_fma_f32 v29, -v95, v33, v29
	ds_read_u16 v33, v153
	v_mul_f32_e32 v28, v89, v28
	v_fma_f32 v31, -v93, v31, 0
	ds_read_b128 v[48:51], v92 offset:14672
	v_fma_f32 v30, -v91, v30, 0
	s_waitcnt lgkmcnt(1)
	v_lshlrev_b32_e32 v33, 16, v33
	v_fma_f32 v25, v25, v33, -v28
	v_fma_f32 v31, -v98, v35, v31
	ds_read_b128 v[52:55], v92 offset:14688
	v_fma_f32 v30, -v96, v34, v30
	v_fma_f32 v25, -v94, v32, v25
	v_fma_f32 v31, -v102, v39, v31
	ds_read_b128 v[56:59], v92 offset:14704
	v_fma_f32 v30, -v101, v38, v30
	v_fma_f32 v29, -v100, v37, v29
	v_fma_f32 v25, -v99, v36, v25
	v_fma_f32 v31, -v106, v43, v31
	ds_read_b128 v[60:63], v92 offset:14720
	v_fma_f32 v30, -v105, v42, v30
	v_fma_f32 v29, -v104, v41, v29
	v_fma_f32 v25, -v103, v40, v25
	v_fma_f32 v31, -v110, v47, v31
	ds_read_b128 v[64:67], v92 offset:14736
	v_fma_f32 v30, -v109, v46, v30
	v_fma_f32 v29, -v108, v45, v29
	v_fma_f32 v25, -v107, v44, v25
	s_waitcnt lgkmcnt(4)
	v_fma_f32 v31, -v114, v51, v31
	ds_read_b128 v[68:71], v92 offset:14752
	v_fma_f32 v30, -v113, v50, v30
	v_fma_f32 v29, -v112, v49, v29
	v_fma_f32 v25, -v111, v48, v25
	s_waitcnt lgkmcnt(4)
	v_fma_f32 v31, -v118, v55, v31
	ds_read_b128 v[72:75], v92 offset:14768
	v_fma_f32 v30, -v117, v54, v30
	v_fma_f32 v29, -v116, v53, v29
	v_fma_f32 v25, -v115, v52, v25
	s_waitcnt lgkmcnt(4)
	v_fma_f32 v31, -v122, v59, v31
	ds_read_b128 v[76:79], v92 offset:14784
	v_fma_f32 v30, -v121, v58, v30
	v_fma_f32 v29, -v120, v57, v29
	v_fma_f32 v25, -v119, v56, v25
	s_waitcnt lgkmcnt(4)
	v_fma_f32 v31, -v126, v63, v31
	ds_read_b128 v[80:83], v92 offset:14800
	v_fma_f32 v30, -v125, v62, v30
	v_fma_f32 v29, -v124, v61, v29
	v_fma_f32 v25, -v123, v60, v25
	s_waitcnt lgkmcnt(4)
	v_fma_f32 v31, -v135, v67, v31
	v_fma_f32 v30, -v134, v66, v30
	v_fma_f32 v29, -v133, v65, v29
	v_fma_f32 v25, -v127, v64, v25
	s_waitcnt lgkmcnt(3)
	v_fma_f32 v31, -v139, v71, v31
	v_fma_f32 v30, -v138, v70, v30
	v_fma_f32 v29, -v137, v69, v29
	v_fma_f32 v25, -v136, v68, v25
	s_waitcnt lgkmcnt(2)
	v_fma_f32 v31, -v143, v75, v31
	v_fma_f32 v30, -v142, v74, v30
	v_fma_f32 v29, -v141, v73, v29
	v_fma_f32 v25, -v140, v72, v25
	s_waitcnt lgkmcnt(1)
	v_fma_f32 v31, -v147, v79, v31
	v_fma_f32 v30, -v146, v78, v30
	v_fma_f32 v29, -v145, v77, v29
	v_fma_f32 v25, -v144, v76, v25
	s_waitcnt lgkmcnt(0)
	v_fma_f32 v31, -v151, v83, v31
	v_fma_f32 v30, -v150, v82, v30
	v_fma_f32 v29, -v149, v81, v29
	v_fma_f32 v25, -v148, v80, v25
	v_fmac_f32_e32 v31, 0x80000000, v157
	v_fmac_f32_e32 v30, 0x80000000, v156
	v_fmac_f32_e32 v29, 0x80000000, v155
	v_fma_f32 v25, -v154, v152, v25
	v_add_u32_e32 v24, v153, v97
	v_add_f32_e32 v25, v29, v25
	v_add_f32_e32 v28, v30, v31
	v_add_f32_e32 v153, v28, v25
	v_add_u32_e32 v25, v24, v97
	ds_read_b128 v[28:31], v92 offset:14848
	ds_read_u16 v24, v24
	ds_read_b128 v[32:35], v92 offset:14864
	ds_read_b128 v[36:39], v92 offset:14880
	ds_read_b128 v[40:43], v92 offset:14896
	ds_read_b128 v[44:47], v92 offset:14912
	s_waitcnt lgkmcnt(4)
	v_lshlrev_b32_e32 v24, 16, v24
	v_mul_f32_e32 v28, v89, v28
	v_fma_f32 v31, -v93, v31, 0
	ds_read_b128 v[48:51], v92 offset:14928
	v_fma_f32 v30, -v91, v30, 0
	v_fma_f32 v29, -v90, v29, 0
	v_fma_f32 v24, v26, v24, -v28
	s_waitcnt lgkmcnt(4)
	v_fma_f32 v31, -v98, v35, v31
	ds_read_b128 v[52:55], v92 offset:14944
	v_fma_f32 v30, -v96, v34, v30
	v_fma_f32 v29, -v95, v33, v29
	v_fma_f32 v24, -v94, v32, v24
	s_waitcnt lgkmcnt(4)
	v_fma_f32 v31, -v102, v39, v31
	ds_read_b128 v[56:59], v92 offset:14960
	v_fma_f32 v30, -v101, v38, v30
	v_fma_f32 v29, -v100, v37, v29
	v_fma_f32 v24, -v99, v36, v24
	s_waitcnt lgkmcnt(4)
	v_fma_f32 v31, -v106, v43, v31
	ds_read_b128 v[60:63], v92 offset:14976
	v_fma_f32 v30, -v105, v42, v30
	v_fma_f32 v29, -v104, v41, v29
	v_fma_f32 v24, -v103, v40, v24
	s_waitcnt lgkmcnt(4)
	v_fma_f32 v31, -v110, v47, v31
	ds_read_b128 v[64:67], v92 offset:14992
	v_fma_f32 v30, -v109, v46, v30
	v_fma_f32 v29, -v108, v45, v29
	v_fma_f32 v24, -v107, v44, v24
	s_waitcnt lgkmcnt(4)
	v_fma_f32 v31, -v114, v51, v31
	ds_read_b128 v[68:71], v92 offset:15008
	v_fma_f32 v30, -v113, v50, v30
	v_fma_f32 v29, -v112, v49, v29
	v_fma_f32 v24, -v111, v48, v24
	s_waitcnt lgkmcnt(4)
	v_fma_f32 v31, -v118, v55, v31
	ds_read_b128 v[72:75], v92 offset:15024
	v_fma_f32 v30, -v117, v54, v30
	v_fma_f32 v29, -v116, v53, v29
	v_fma_f32 v24, -v115, v52, v24
	s_waitcnt lgkmcnt(4)
	v_fma_f32 v31, -v122, v59, v31
	ds_read_b128 v[76:79], v92 offset:15040
	v_fma_f32 v30, -v121, v58, v30
	v_fma_f32 v29, -v120, v57, v29
	v_fma_f32 v24, -v119, v56, v24
	s_waitcnt lgkmcnt(4)
	v_fma_f32 v31, -v126, v63, v31
	ds_read_b128 v[80:83], v92 offset:15056
	v_fma_f32 v30, -v125, v62, v30
	v_fma_f32 v29, -v124, v61, v29
	v_fma_f32 v24, -v123, v60, v24
	s_waitcnt lgkmcnt(4)
	v_fma_f32 v31, -v135, v67, v31
	ds_read_b128 v[154:157], v92 offset:15072
	v_fma_f32 v30, -v134, v66, v30
	v_fma_f32 v29, -v133, v65, v29
	v_fma_f32 v24, -v127, v64, v24
	s_waitcnt lgkmcnt(4)
	v_fma_f32 v31, -v139, v71, v31
	v_fma_f32 v30, -v138, v70, v30
	v_fma_f32 v29, -v137, v69, v29
	v_fma_f32 v24, -v136, v68, v24
	s_waitcnt lgkmcnt(3)
	v_fma_f32 v31, -v143, v75, v31
	v_fma_f32 v30, -v142, v74, v30
	v_fma_f32 v29, -v141, v73, v29
	v_fma_f32 v24, -v140, v72, v24
	s_waitcnt lgkmcnt(2)
	v_fma_f32 v31, -v147, v79, v31
	v_fma_f32 v30, -v146, v78, v30
	v_fma_f32 v29, -v145, v77, v29
	v_fma_f32 v24, -v144, v76, v24
	s_waitcnt lgkmcnt(1)
	v_fma_f32 v31, -v151, v83, v31
	v_fma_f32 v30, -v150, v82, v30
	v_fma_f32 v29, -v149, v81, v29
	v_fma_f32 v24, -v148, v80, v24
	s_waitcnt lgkmcnt(0)
	v_fmac_f32_e32 v31, 0x80000000, v157
	v_fmac_f32_e32 v30, 0x80000000, v156
	v_fma_f32 v29, -v155, v153, v29
	v_fma_f32 v24, -v152, v154, v24
	v_add_f32_e32 v24, v29, v24
	v_add_f32_e32 v26, v30, v31
	v_add_u32_e32 v157, v25, v97
	ds_read_b128 v[28:31], v92 offset:15104
	ds_read_u16 v25, v25
	ds_read_b128 v[32:35], v92 offset:15120
	ds_read_b128 v[36:39], v92 offset:15136
	ds_read_b128 v[40:43], v92 offset:15152
	ds_read_b128 v[44:47], v92 offset:15168
	s_waitcnt lgkmcnt(4)
	v_lshlrev_b32_e32 v25, 16, v25
	v_mul_f32_e32 v28, v89, v28
	v_add_f32_e32 v154, v26, v24
	v_fma_f32 v24, -v93, v31, 0
	ds_read_b128 v[48:51], v92 offset:15184
	v_fma_f32 v26, -v91, v30, 0
	v_fma_f32 v29, -v90, v29, 0
	v_fma_f32 v25, v27, v25, -v28
	s_waitcnt lgkmcnt(4)
	v_fma_f32 v24, -v98, v35, v24
	ds_read_b128 v[52:55], v92 offset:15200
	v_fma_f32 v26, -v96, v34, v26
	v_fma_f32 v29, -v95, v33, v29
	v_fma_f32 v25, -v94, v32, v25
	s_waitcnt lgkmcnt(4)
	v_fma_f32 v24, -v102, v39, v24
	ds_read_b128 v[56:59], v92 offset:15216
	v_fma_f32 v26, -v101, v38, v26
	v_fma_f32 v29, -v100, v37, v29
	v_fma_f32 v25, -v99, v36, v25
	s_waitcnt lgkmcnt(4)
	v_fma_f32 v24, -v106, v43, v24
	ds_read_b128 v[60:63], v92 offset:15232
	v_fma_f32 v26, -v105, v42, v26
	v_fma_f32 v29, -v104, v41, v29
	v_fma_f32 v25, -v103, v40, v25
	s_waitcnt lgkmcnt(4)
	v_fma_f32 v24, -v110, v47, v24
	ds_read_b128 v[64:67], v92 offset:15248
	v_fma_f32 v26, -v109, v46, v26
	v_fma_f32 v29, -v108, v45, v29
	v_fma_f32 v25, -v107, v44, v25
	s_waitcnt lgkmcnt(4)
	v_fma_f32 v24, -v114, v51, v24
	ds_read_b128 v[68:71], v92 offset:15264
	v_fma_f32 v26, -v113, v50, v26
	v_fma_f32 v29, -v112, v49, v29
	v_fma_f32 v25, -v111, v48, v25
	s_waitcnt lgkmcnt(4)
	v_fma_f32 v24, -v118, v55, v24
	ds_read_b128 v[72:75], v92 offset:15280
	v_fma_f32 v26, -v117, v54, v26
	v_fma_f32 v29, -v116, v53, v29
	v_fma_f32 v25, -v115, v52, v25
	s_waitcnt lgkmcnt(4)
	v_fma_f32 v24, -v122, v59, v24
	ds_read_b128 v[76:79], v92 offset:15296
	v_fma_f32 v26, -v121, v58, v26
	v_fma_f32 v29, -v120, v57, v29
	v_fma_f32 v25, -v119, v56, v25
	s_waitcnt lgkmcnt(4)
	v_fma_f32 v24, -v126, v63, v24
	ds_read_b128 v[80:83], v92 offset:15312
	v_fma_f32 v26, -v125, v62, v26
	v_fma_f32 v29, -v124, v61, v29
	v_fma_f32 v25, -v123, v60, v25
	s_waitcnt lgkmcnt(4)
	v_fma_f32 v24, -v135, v67, v24
	v_fma_f32 v26, -v134, v66, v26
	v_fma_f32 v29, -v133, v65, v29
	v_fma_f32 v25, -v127, v64, v25
	s_waitcnt lgkmcnt(3)
	v_fma_f32 v24, -v139, v71, v24
	v_fma_f32 v26, -v138, v70, v26
	v_fma_f32 v29, -v137, v69, v29
	v_fma_f32 v25, -v136, v68, v25
	s_waitcnt lgkmcnt(2)
	v_fma_f32 v24, -v143, v75, v24
	v_fma_f32 v26, -v142, v74, v26
	v_fma_f32 v29, -v141, v73, v29
	v_fma_f32 v25, -v140, v72, v25
	s_waitcnt lgkmcnt(1)
	v_fma_f32 v24, -v147, v79, v24
	v_fma_f32 v26, -v146, v78, v26
	v_fma_f32 v29, -v145, v77, v29
	v_fma_f32 v25, -v144, v76, v25
	s_waitcnt lgkmcnt(0)
	v_fma_f32 v24, -v151, v83, v24
	v_fma_f32 v26, -v150, v82, v26
	v_fma_f32 v29, -v149, v81, v29
	v_fma_f32 v25, -v148, v80, v25
	v_fmac_f32_e32 v24, 0x80000000, v161
	v_fma_f32 v26, -v160, v154, v26
	v_fma_f32 v29, -v153, v159, v29
	v_fma_f32 v25, -v152, v158, v25
	v_add_f32_e32 v25, v29, v25
	v_add_f32_e32 v24, v24, v26
	v_add_f32_e32 v155, v24, v25
	ds_read_b128 v[24:27], v92 offset:15360
	ds_read_b128 v[28:31], v92 offset:15376
	ds_read_b128 v[32:35], v92 offset:15392
	ds_read_b128 v[36:39], v92 offset:15408
	ds_read_b128 v[40:43], v92 offset:15424
	s_waitcnt lgkmcnt(4)
	v_fma_f32 v27, -v93, v27, 0
	ds_read_b128 v[44:47], v92 offset:15440
	v_fma_f32 v26, -v91, v26, 0
	s_waitcnt lgkmcnt(4)
	v_fma_f32 v27, -v98, v31, v27
	ds_read_b128 v[48:51], v92 offset:15456
	v_fma_f32 v26, -v96, v30, v26
	s_waitcnt lgkmcnt(4)
	v_fma_f32 v27, -v102, v35, v27
	ds_read_b128 v[52:55], v92 offset:15472
	v_fma_f32 v26, -v101, v34, v26
	s_waitcnt lgkmcnt(4)
	v_fma_f32 v27, -v106, v39, v27
	ds_read_b128 v[56:59], v92 offset:15488
	v_fma_f32 v26, -v105, v38, v26
	s_waitcnt lgkmcnt(4)
	v_fma_f32 v27, -v110, v43, v27
	ds_read_b128 v[60:63], v92 offset:15504
	v_fma_f32 v26, -v109, v42, v26
	s_waitcnt lgkmcnt(4)
	v_fma_f32 v27, -v114, v47, v27
	ds_read_b128 v[64:67], v92 offset:15520
	v_fma_f32 v26, -v113, v46, v26
	s_waitcnt lgkmcnt(4)
	v_fma_f32 v27, -v118, v51, v27
	ds_read_b128 v[68:71], v92 offset:15536
	v_fma_f32 v26, -v117, v50, v26
	s_waitcnt lgkmcnt(4)
	v_fma_f32 v27, -v122, v55, v27
	ds_read_b128 v[72:75], v92 offset:15552
	v_fma_f32 v26, -v121, v54, v26
	s_waitcnt lgkmcnt(4)
	v_fma_f32 v27, -v126, v59, v27
	ds_read_b128 v[76:79], v92 offset:15568
	v_fma_f32 v26, -v125, v58, v26
	s_waitcnt lgkmcnt(4)
	v_fma_f32 v27, -v135, v63, v27
	ds_read_b128 v[80:83], v92 offset:15584
	v_fma_f32 v26, -v134, v62, v26
	s_waitcnt lgkmcnt(4)
	v_fma_f32 v27, -v139, v67, v27
	v_fma_f32 v26, -v138, v66, v26
	s_waitcnt lgkmcnt(3)
	v_fma_f32 v27, -v143, v71, v27
	v_fma_f32 v26, -v142, v70, v26
	s_waitcnt lgkmcnt(2)
	v_fma_f32 v27, -v147, v75, v27
	v_fma_f32 v26, -v146, v74, v26
	s_waitcnt lgkmcnt(1)
	v_fma_f32 v27, -v151, v79, v27
	v_fma_f32 v26, -v150, v78, v26
	v_fma_f32 v25, -v90, v25, 0
	s_waitcnt lgkmcnt(0)
	v_fma_f32 v27, -v83, v155, v27
	v_fma_f32 v26, -v154, v82, v26
	v_fma_f32 v25, -v95, v29, v25
	ds_read_b128 v[82:85], v84 offset:240
	ds_read_u16 v29, v157
	v_mul_f32_e32 v24, v89, v24
	v_fma_f32 v25, -v100, v33, v25
	v_fma_f32 v25, -v104, v37, v25
	v_fma_f32 v25, -v108, v41, v25
	s_waitcnt lgkmcnt(0)
	v_lshlrev_b32_e32 v29, 16, v29
	v_fma_f32 v24, v82, v29, -v24
	v_fma_f32 v24, -v94, v28, v24
	v_fma_f32 v24, -v99, v32, v24
	v_fma_f32 v24, -v103, v36, v24
	v_fma_f32 v24, -v107, v40, v24
	v_fma_f32 v25, -v112, v45, v25
	v_fma_f32 v24, -v111, v44, v24
	v_fma_f32 v25, -v116, v49, v25
	v_fma_f32 v24, -v115, v48, v24
	v_fma_f32 v25, -v120, v53, v25
	v_fma_f32 v24, -v119, v52, v24
	v_fma_f32 v25, -v124, v57, v25
	v_fma_f32 v24, -v123, v56, v24
	v_fma_f32 v25, -v133, v61, v25
	v_fma_f32 v24, -v127, v60, v24
	v_fma_f32 v25, -v137, v65, v25
	v_fma_f32 v24, -v136, v64, v24
	v_fma_f32 v25, -v141, v69, v25
	v_fma_f32 v24, -v140, v68, v24
	v_fma_f32 v25, -v145, v73, v25
	v_fma_f32 v24, -v144, v72, v24
	v_fma_f32 v25, -v149, v77, v25
	v_fma_f32 v24, -v148, v76, v24
	v_fma_f32 v25, -v153, v81, v25
	v_fma_f32 v24, -v152, v80, v24
	v_add_f32_e32 v24, v25, v24
	v_add_f32_e32 v25, v26, v27
	ds_read_b128 v[26:29], v92 offset:15616
	v_add_u32_e32 v156, v157, v97
	v_add_f32_e32 v24, v25, v24
	ds_read_b128 v[30:33], v92 offset:15632
	ds_read_b128 v[34:37], v92 offset:15648
	s_waitcnt lgkmcnt(2)
	v_fma_f32 v25, -v93, v29, 0
	ds_read_u16 v29, v156
	ds_read_b128 v[38:41], v92 offset:15664
	ds_read_b128 v[42:45], v92 offset:15680
	v_mul_f32_e32 v26, v89, v26
	ds_read_b128 v[46:49], v92 offset:15696
	s_waitcnt lgkmcnt(3)
	v_lshlrev_b32_e32 v29, 16, v29
	v_fma_f32 v28, -v91, v28, 0
	v_fma_f32 v27, -v90, v27, 0
	v_fma_f32 v26, v83, v29, -v26
	v_fma_f32 v25, -v98, v33, v25
	ds_read_b128 v[50:53], v92 offset:15712
	v_fma_f32 v28, -v96, v32, v28
	v_fma_f32 v27, -v95, v31, v27
	v_fma_f32 v26, -v94, v30, v26
	v_fma_f32 v25, -v102, v37, v25
	ds_read_b128 v[54:57], v92 offset:15728
	v_fma_f32 v28, -v101, v36, v28
	v_fma_f32 v27, -v100, v35, v27
	v_fma_f32 v26, -v99, v34, v26
	s_waitcnt lgkmcnt(4)
	v_fma_f32 v25, -v106, v41, v25
	ds_read_b128 v[58:61], v92 offset:15744
	v_fma_f32 v28, -v105, v40, v28
	v_fma_f32 v27, -v104, v39, v27
	v_fma_f32 v26, -v103, v38, v26
	s_waitcnt lgkmcnt(4)
	v_fma_f32 v25, -v110, v45, v25
	ds_read_b128 v[62:65], v92 offset:15760
	v_fma_f32 v28, -v109, v44, v28
	v_fma_f32 v27, -v108, v43, v27
	v_fma_f32 v26, -v107, v42, v26
	s_waitcnt lgkmcnt(4)
	v_fma_f32 v25, -v114, v49, v25
	ds_read_b128 v[66:69], v92 offset:15776
	v_fma_f32 v28, -v113, v48, v28
	v_fma_f32 v27, -v112, v47, v27
	v_fma_f32 v26, -v111, v46, v26
	s_waitcnt lgkmcnt(4)
	v_fma_f32 v25, -v118, v53, v25
	ds_read_b128 v[70:73], v92 offset:15792
	v_fma_f32 v28, -v117, v52, v28
	v_fma_f32 v27, -v116, v51, v27
	v_fma_f32 v26, -v115, v50, v26
	s_waitcnt lgkmcnt(4)
	v_fma_f32 v25, -v122, v57, v25
	ds_read_b128 v[74:77], v92 offset:15808
	v_fma_f32 v28, -v121, v56, v28
	v_fma_f32 v27, -v120, v55, v27
	v_fma_f32 v26, -v119, v54, v26
	s_waitcnt lgkmcnt(4)
	v_fma_f32 v25, -v126, v61, v25
	ds_read_b128 v[78:81], v92 offset:15824
	v_fma_f32 v28, -v125, v60, v28
	v_fma_f32 v27, -v124, v59, v27
	v_fma_f32 v26, -v123, v58, v26
	s_waitcnt lgkmcnt(4)
	v_fma_f32 v25, -v135, v65, v25
	ds_read_b128 v[158:161], v92 offset:15840
	ds_read_b128 v[162:165], v92 offset:15856
	v_fma_f32 v28, -v134, v64, v28
	v_fma_f32 v27, -v133, v63, v27
	v_fma_f32 v26, -v127, v62, v26
	s_waitcnt lgkmcnt(5)
	v_fma_f32 v25, -v139, v69, v25
	v_fma_f32 v28, -v138, v68, v28
	v_fma_f32 v27, -v137, v67, v27
	v_fma_f32 v26, -v136, v66, v26
	s_waitcnt lgkmcnt(4)
	v_fma_f32 v25, -v143, v73, v25
	v_fma_f32 v28, -v142, v72, v28
	v_fma_f32 v27, -v141, v71, v27
	v_fma_f32 v26, -v140, v70, v26
	s_waitcnt lgkmcnt(3)
	v_fma_f32 v25, -v147, v77, v25
	v_fma_f32 v28, -v146, v76, v28
	v_fma_f32 v27, -v145, v75, v27
	v_fma_f32 v26, -v144, v74, v26
	s_waitcnt lgkmcnt(2)
	v_fma_f32 v25, -v151, v81, v25
	v_fma_f32 v28, -v150, v80, v28
	v_fma_f32 v27, -v149, v79, v27
	v_fma_f32 v26, -v148, v78, v26
	s_waitcnt lgkmcnt(1)
	v_fma_f32 v25, -v155, v161, v25
	v_fma_f32 v28, -v154, v160, v28
	v_fma_f32 v27, -v153, v159, v27
	v_fma_f32 v26, -v152, v158, v26
	s_waitcnt lgkmcnt(0)
	v_fmac_f32_e32 v25, 0x80000000, v165
	v_fmac_f32_e32 v28, 0x80000000, v164
	v_fmac_f32_e32 v27, 0x80000000, v163
	v_fma_f32 v26, -v162, v24, v26
	v_add_f32_e32 v26, v27, v26
	v_add_f32_e32 v25, v28, v25
	v_add_f32_e32 v25, v25, v26
	ds_read_b128 v[26:29], v92 offset:15872
	ds_read_b128 v[30:33], v92 offset:15888
	v_add_u32_e32 v82, v156, v97
	ds_read_b128 v[34:37], v92 offset:15904
	ds_read_b128 v[38:41], v92 offset:15920
	s_waitcnt lgkmcnt(3)
	v_fma_f32 v27, -v90, v27, 0
	s_waitcnt lgkmcnt(2)
	v_fma_f32 v27, -v95, v31, v27
	ds_read_u16 v31, v82
	ds_read_b128 v[42:45], v92 offset:15936
	v_mul_f32_e32 v26, v89, v26
	v_fma_f32 v29, -v93, v29, 0
	ds_read_b128 v[46:49], v92 offset:15952
	s_waitcnt lgkmcnt(2)
	v_lshlrev_b32_e32 v31, 16, v31
	v_fma_f32 v28, -v91, v28, 0
	v_fma_f32 v26, v84, v31, -v26
	v_fma_f32 v29, -v98, v33, v29
	ds_read_b128 v[50:53], v92 offset:15968
	v_fma_f32 v28, -v96, v32, v28
	v_fma_f32 v26, -v94, v30, v26
	v_fma_f32 v29, -v102, v37, v29
	ds_read_b128 v[54:57], v92 offset:15984
	v_fma_f32 v28, -v101, v36, v28
	v_fma_f32 v27, -v100, v35, v27
	v_fma_f32 v26, -v99, v34, v26
	v_fma_f32 v29, -v106, v41, v29
	ds_read_b128 v[58:61], v92 offset:16000
	v_fma_f32 v28, -v105, v40, v28
	v_fma_f32 v27, -v104, v39, v27
	v_fma_f32 v26, -v103, v38, v26
	s_waitcnt lgkmcnt(4)
	v_fma_f32 v29, -v110, v45, v29
	ds_read_b128 v[62:65], v92 offset:16016
	v_fma_f32 v28, -v109, v44, v28
	v_fma_f32 v27, -v108, v43, v27
	v_fma_f32 v26, -v107, v42, v26
	s_waitcnt lgkmcnt(4)
	v_fma_f32 v29, -v114, v49, v29
	ds_read_b128 v[66:69], v92 offset:16032
	v_fma_f32 v28, -v113, v48, v28
	v_fma_f32 v27, -v112, v47, v27
	v_fma_f32 v26, -v111, v46, v26
	s_waitcnt lgkmcnt(4)
	v_fma_f32 v29, -v118, v53, v29
	ds_read_b128 v[70:73], v92 offset:16048
	v_fma_f32 v28, -v117, v52, v28
	v_fma_f32 v27, -v116, v51, v27
	v_fma_f32 v26, -v115, v50, v26
	s_waitcnt lgkmcnt(4)
	v_fma_f32 v29, -v122, v57, v29
	ds_read_b128 v[74:77], v92 offset:16064
	v_fma_f32 v28, -v121, v56, v28
	v_fma_f32 v27, -v120, v55, v27
	v_fma_f32 v26, -v119, v54, v26
	s_waitcnt lgkmcnt(4)
	v_fma_f32 v29, -v126, v61, v29
	ds_read_b128 v[78:81], v92 offset:16080
	v_fma_f32 v28, -v125, v60, v28
	v_fma_f32 v27, -v124, v59, v27
	v_fma_f32 v26, -v123, v58, v26
	s_waitcnt lgkmcnt(4)
	v_fma_f32 v29, -v135, v65, v29
	ds_read_b128 v[156:159], v92 offset:16096
	v_fma_f32 v28, -v134, v64, v28
	v_fma_f32 v27, -v133, v63, v27
	v_fma_f32 v26, -v127, v62, v26
	s_waitcnt lgkmcnt(4)
	v_fma_f32 v29, -v139, v69, v29
	ds_read_b128 v[160:163], v92 offset:16112
	v_fma_f32 v28, -v138, v68, v28
	v_fma_f32 v27, -v137, v67, v27
	v_fma_f32 v26, -v136, v66, v26
	s_waitcnt lgkmcnt(4)
	v_fma_f32 v29, -v143, v73, v29
	v_fma_f32 v28, -v142, v72, v28
	v_fma_f32 v27, -v141, v71, v27
	v_fma_f32 v26, -v140, v70, v26
	s_waitcnt lgkmcnt(3)
	v_fma_f32 v29, -v147, v77, v29
	v_fma_f32 v28, -v146, v76, v28
	v_fma_f32 v27, -v145, v75, v27
	v_fma_f32 v26, -v144, v74, v26
	s_waitcnt lgkmcnt(2)
	v_fma_f32 v29, -v151, v81, v29
	v_fma_f32 v28, -v150, v80, v28
	v_fma_f32 v27, -v149, v79, v27
	v_fma_f32 v26, -v148, v78, v26
	s_waitcnt lgkmcnt(1)
	v_fma_f32 v29, -v155, v159, v29
	v_fma_f32 v28, -v154, v158, v28
	v_fma_f32 v27, -v153, v157, v27
	v_fma_f32 v26, -v152, v156, v26
	s_waitcnt lgkmcnt(0)
	v_fmac_f32_e32 v29, 0x80000000, v163
	v_fmac_f32_e32 v28, 0x80000000, v162
	v_fma_f32 v27, -v161, v25, v27
	v_fma_f32 v26, -v24, v160, v26
	v_add_f32_e32 v26, v27, v26
	v_add_f32_e32 v27, v28, v29
	v_add_u32_e32 v83, v82, v97
	v_add_f32_e32 v82, v27, v26
	ds_read_b128 v[26:29], v92 offset:16128
	ds_read_b128 v[30:33], v92 offset:16144
	ds_read_b128 v[34:37], v92 offset:16160
	ds_read_b128 v[38:41], v92 offset:16176
	ds_read_b128 v[42:45], v92 offset:16192
	s_waitcnt lgkmcnt(4)
	v_fma_f32 v27, -v90, v27, 0
	s_waitcnt lgkmcnt(3)
	v_fma_f32 v27, -v95, v31, v27
	ds_read_u16 v31, v83
	v_mul_f32_e32 v26, v89, v26
	v_fma_f32 v29, -v93, v29, 0
	ds_read_b128 v[46:49], v92 offset:16208
	v_fma_f32 v28, -v91, v28, 0
	s_waitcnt lgkmcnt(1)
	v_lshlrev_b32_e32 v31, 16, v31
	v_fma_f32 v26, v85, v31, -v26
	v_fma_f32 v29, -v98, v33, v29
	ds_read_b128 v[50:53], v92 offset:16224
	v_fma_f32 v28, -v96, v32, v28
	v_fma_f32 v26, -v94, v30, v26
	v_fma_f32 v29, -v102, v37, v29
	ds_read_b128 v[54:57], v92 offset:16240
	v_fma_f32 v28, -v101, v36, v28
	v_fma_f32 v27, -v100, v35, v27
	v_fma_f32 v26, -v99, v34, v26
	v_fma_f32 v29, -v106, v41, v29
	ds_read_b128 v[58:61], v92 offset:16256
	v_fma_f32 v28, -v105, v40, v28
	v_fma_f32 v27, -v104, v39, v27
	v_fma_f32 v26, -v103, v38, v26
	v_fma_f32 v29, -v110, v45, v29
	ds_read_b128 v[62:65], v92 offset:16272
	v_fma_f32 v28, -v109, v44, v28
	v_fma_f32 v27, -v108, v43, v27
	v_fma_f32 v26, -v107, v42, v26
	s_waitcnt lgkmcnt(4)
	v_fma_f32 v29, -v114, v49, v29
	ds_read_b128 v[66:69], v92 offset:16288
	v_fma_f32 v28, -v113, v48, v28
	v_fma_f32 v27, -v112, v47, v27
	v_fma_f32 v26, -v111, v46, v26
	s_waitcnt lgkmcnt(4)
	v_fma_f32 v29, -v118, v53, v29
	ds_read_b128 v[70:73], v92 offset:16304
	v_fma_f32 v28, -v117, v52, v28
	v_fma_f32 v27, -v116, v51, v27
	v_fma_f32 v26, -v115, v50, v26
	s_waitcnt lgkmcnt(4)
	v_fma_f32 v29, -v122, v57, v29
	ds_read_b128 v[74:77], v92 offset:16320
	v_fma_f32 v28, -v121, v56, v28
	v_fma_f32 v27, -v120, v55, v27
	v_fma_f32 v26, -v119, v54, v26
	s_waitcnt lgkmcnt(4)
	v_fma_f32 v29, -v126, v61, v29
	ds_read_b128 v[78:81], v92 offset:16336
	v_fma_f32 v28, -v125, v60, v28
	v_fma_f32 v27, -v124, v59, v27
	v_fma_f32 v26, -v123, v58, v26
	s_waitcnt lgkmcnt(4)
	v_fma_f32 v29, -v135, v65, v29
	ds_read_b128 v[156:159], v92 offset:16352
	v_fma_f32 v28, -v134, v64, v28
	v_fma_f32 v27, -v133, v63, v27
	v_fma_f32 v26, -v127, v62, v26
	s_waitcnt lgkmcnt(4)
	v_fma_f32 v29, -v139, v69, v29
	ds_read_b128 v[160:163], v92 offset:16368
	v_fma_f32 v28, -v138, v68, v28
	v_fma_f32 v27, -v137, v67, v27
	v_fma_f32 v26, -v136, v66, v26
	s_waitcnt lgkmcnt(4)
	v_fma_f32 v29, -v143, v73, v29
	v_fma_f32 v28, -v142, v72, v28
	v_fma_f32 v27, -v141, v71, v27
	v_fma_f32 v26, -v140, v70, v26
	s_waitcnt lgkmcnt(3)
	v_fma_f32 v29, -v147, v77, v29
	v_fma_f32 v28, -v146, v76, v28
	v_fma_f32 v27, -v145, v75, v27
	v_fma_f32 v26, -v144, v74, v26
	s_waitcnt lgkmcnt(2)
	v_fma_f32 v29, -v151, v81, v29
	v_fma_f32 v28, -v150, v80, v28
	v_fma_f32 v27, -v149, v79, v27
	v_fma_f32 v26, -v148, v78, v26
	s_waitcnt lgkmcnt(1)
	v_fma_f32 v29, -v155, v159, v29
	v_fma_f32 v28, -v154, v158, v28
	v_fma_f32 v27, -v153, v157, v27
	v_fma_f32 v26, -v152, v156, v26
	s_waitcnt lgkmcnt(0)
	v_fmac_f32_e32 v29, 0x80000000, v163
	v_fma_f32 v28, -v162, v82, v28
	v_fma_f32 v27, -v25, v161, v27
	v_fma_f32 v26, -v24, v160, v26
	v_add_f32_e32 v26, v27, v26
	v_add_f32_e32 v27, v29, v28
	v_add_f32_e32 v30, v27, v26
	v_mov_b32_e32 v26, s53
	v_mov_b32_e32 v27, s55
	v_cndmask_b32_e64 v27, v26, v27, s[2:3]
	v_mov_b32_e32 v26, s52
	v_mov_b32_e32 v28, s54
	v_cndmask_b32_e64 v26, v26, v28, s[2:3]
	v_mov_b32_e32 v28, s7
	v_mov_b32_e32 v29, s1
	v_cndmask_b32_e32 v29, v28, v29, vcc
	v_mov_b32_e32 v28, s6
	v_mov_b32_e32 v31, s0
	v_cndmask_b32_e32 v28, v28, v31, vcc
	v_lshlrev_b64 v[28:29], 13, v[28:29]
	v_lshl_add_u64 v[26:27], v[26:27], 0, v[28:29]
	v_lshl_add_u64 v[26:27], v[26:27], 0, v[128:129]
	s_mov_b32 s98, 0x7060302
	s_mov_b32 s96, 0x55555555
	s_mov_b32 s97, 0x55555555
	v_and_b32_e32 v31, 1, v86
	v_mul_u32_u24_e32 v31, 0x7e, v31
	v_add_co_u32_e32 v26, vcc, v26, v31
	s_nop 0
	v_addc_co_u32_e32 v27, vcc, 0, v27, vcc
	v_bfe_u32 v28, v89, 16, 1
	v_bfe_u32 v29, v90, 16, 1
	v_add3_u32 v28, v89, v28, s42
	v_add3_u32 v29, v90, v29, s42
	s_nop 1
	v_mov_b32_dpp v31, v29 quad_perm:[1,0,3,2] row_mask:0xf bank_mask:0xf
	v_mov_b32_dpp v32, v28 quad_perm:[1,0,3,2] row_mask:0xf bank_mask:0xf
	v_cndmask_b32_e64 v28, v31, v28, s[96:97]
	v_cndmask_b32_e64 v29, v29, v32, s[96:97]
	v_perm_b32 v28, v29, v28, s98
	global_store_dword v[26:27], v28, off
	v_bfe_u32 v28, v91, 16, 1
	v_bfe_u32 v29, v93, 16, 1
	v_add3_u32 v28, v91, v28, s42
	v_add3_u32 v29, v93, v29, s42
	s_nop 1
	v_mov_b32_dpp v31, v29 quad_perm:[1,0,3,2] row_mask:0xf bank_mask:0xf
	v_mov_b32_dpp v32, v28 quad_perm:[1,0,3,2] row_mask:0xf bank_mask:0xf
	v_cndmask_b32_e64 v28, v31, v28, s[96:97]
	v_cndmask_b32_e64 v29, v29, v32, s[96:97]
	v_perm_b32 v28, v29, v28, s98
	global_store_dword v[26:27], v28, off offset:256
	v_bfe_u32 v28, v94, 16, 1
	v_bfe_u32 v29, v95, 16, 1
	v_add3_u32 v28, v94, v28, s42
	v_add3_u32 v29, v95, v29, s42
	s_nop 1
	v_mov_b32_dpp v31, v29 quad_perm:[1,0,3,2] row_mask:0xf bank_mask:0xf
	v_mov_b32_dpp v32, v28 quad_perm:[1,0,3,2] row_mask:0xf bank_mask:0xf
	v_cndmask_b32_e64 v28, v31, v28, s[96:97]
	v_cndmask_b32_e64 v29, v29, v32, s[96:97]
	v_perm_b32 v28, v29, v28, s98
	global_store_dword v[26:27], v28, off offset:512
	v_bfe_u32 v28, v96, 16, 1
	v_bfe_u32 v29, v98, 16, 1
	v_add3_u32 v28, v96, v28, s42
	v_add3_u32 v29, v98, v29, s42
	s_nop 1
	v_mov_b32_dpp v31, v29 quad_perm:[1,0,3,2] row_mask:0xf bank_mask:0xf
	v_mov_b32_dpp v32, v28 quad_perm:[1,0,3,2] row_mask:0xf bank_mask:0xf
	v_cndmask_b32_e64 v28, v31, v28, s[96:97]
	v_cndmask_b32_e64 v29, v29, v32, s[96:97]
	v_perm_b32 v28, v29, v28, s98
	global_store_dword v[26:27], v28, off offset:768
	v_bfe_u32 v28, v99, 16, 1
	v_bfe_u32 v29, v100, 16, 1
	v_add3_u32 v28, v99, v28, s42
	v_add3_u32 v29, v100, v29, s42
	s_nop 1
	v_mov_b32_dpp v31, v29 quad_perm:[1,0,3,2] row_mask:0xf bank_mask:0xf
	v_mov_b32_dpp v32, v28 quad_perm:[1,0,3,2] row_mask:0xf bank_mask:0xf
	v_cndmask_b32_e64 v28, v31, v28, s[96:97]
	v_cndmask_b32_e64 v29, v29, v32, s[96:97]
	v_perm_b32 v28, v29, v28, s98
	global_store_dword v[26:27], v28, off offset:1024
	v_bfe_u32 v28, v101, 16, 1
	v_bfe_u32 v29, v102, 16, 1
	v_add3_u32 v28, v101, v28, s42
	v_add3_u32 v29, v102, v29, s42
	s_nop 1
	v_mov_b32_dpp v31, v29 quad_perm:[1,0,3,2] row_mask:0xf bank_mask:0xf
	v_mov_b32_dpp v32, v28 quad_perm:[1,0,3,2] row_mask:0xf bank_mask:0xf
	v_cndmask_b32_e64 v28, v31, v28, s[96:97]
	v_cndmask_b32_e64 v29, v29, v32, s[96:97]
	v_perm_b32 v28, v29, v28, s98
	global_store_dword v[26:27], v28, off offset:1280
	v_bfe_u32 v28, v103, 16, 1
	v_bfe_u32 v29, v104, 16, 1
	v_add3_u32 v28, v103, v28, s42
	v_add3_u32 v29, v104, v29, s42
	s_nop 1
	v_mov_b32_dpp v31, v29 quad_perm:[1,0,3,2] row_mask:0xf bank_mask:0xf
	v_mov_b32_dpp v32, v28 quad_perm:[1,0,3,2] row_mask:0xf bank_mask:0xf
	v_cndmask_b32_e64 v28, v31, v28, s[96:97]
	v_cndmask_b32_e64 v29, v29, v32, s[96:97]
	v_perm_b32 v28, v29, v28, s98
	global_store_dword v[26:27], v28, off offset:1536
	v_bfe_u32 v28, v105, 16, 1
	v_bfe_u32 v29, v106, 16, 1
	v_add3_u32 v28, v105, v28, s42
	v_add3_u32 v29, v106, v29, s42
	s_nop 1
	v_mov_b32_dpp v31, v29 quad_perm:[1,0,3,2] row_mask:0xf bank_mask:0xf
	v_mov_b32_dpp v32, v28 quad_perm:[1,0,3,2] row_mask:0xf bank_mask:0xf
	v_cndmask_b32_e64 v28, v31, v28, s[96:97]
	v_cndmask_b32_e64 v29, v29, v32, s[96:97]
	v_perm_b32 v28, v29, v28, s98
	global_store_dword v[26:27], v28, off offset:1792
	v_bfe_u32 v28, v107, 16, 1
	v_bfe_u32 v29, v108, 16, 1
	v_add3_u32 v28, v107, v28, s42
	v_add3_u32 v29, v108, v29, s42
	s_nop 1
	v_mov_b32_dpp v31, v29 quad_perm:[1,0,3,2] row_mask:0xf bank_mask:0xf
	v_mov_b32_dpp v32, v28 quad_perm:[1,0,3,2] row_mask:0xf bank_mask:0xf
	v_cndmask_b32_e64 v28, v31, v28, s[96:97]
	v_cndmask_b32_e64 v29, v29, v32, s[96:97]
	v_perm_b32 v28, v29, v28, s98
	global_store_dword v[26:27], v28, off offset:2048
	v_bfe_u32 v28, v109, 16, 1
	v_bfe_u32 v29, v110, 16, 1
	v_add3_u32 v28, v109, v28, s42
	v_add3_u32 v29, v110, v29, s42
	s_nop 1
	v_mov_b32_dpp v31, v29 quad_perm:[1,0,3,2] row_mask:0xf bank_mask:0xf
	v_mov_b32_dpp v32, v28 quad_perm:[1,0,3,2] row_mask:0xf bank_mask:0xf
	v_cndmask_b32_e64 v28, v31, v28, s[96:97]
	v_cndmask_b32_e64 v29, v29, v32, s[96:97]
	v_perm_b32 v28, v29, v28, s98
	global_store_dword v[26:27], v28, off offset:2304
	v_bfe_u32 v28, v111, 16, 1
	v_bfe_u32 v29, v112, 16, 1
	v_add3_u32 v28, v111, v28, s42
	v_add3_u32 v29, v112, v29, s42
	s_nop 1
	v_mov_b32_dpp v31, v29 quad_perm:[1,0,3,2] row_mask:0xf bank_mask:0xf
	v_mov_b32_dpp v32, v28 quad_perm:[1,0,3,2] row_mask:0xf bank_mask:0xf
	v_cndmask_b32_e64 v28, v31, v28, s[96:97]
	v_cndmask_b32_e64 v29, v29, v32, s[96:97]
	v_perm_b32 v28, v29, v28, s98
	global_store_dword v[26:27], v28, off offset:2560
	v_bfe_u32 v28, v113, 16, 1
	v_bfe_u32 v29, v114, 16, 1
	v_add3_u32 v28, v113, v28, s42
	v_add3_u32 v29, v114, v29, s42
	s_nop 1
	v_mov_b32_dpp v31, v29 quad_perm:[1,0,3,2] row_mask:0xf bank_mask:0xf
	v_mov_b32_dpp v32, v28 quad_perm:[1,0,3,2] row_mask:0xf bank_mask:0xf
	v_cndmask_b32_e64 v28, v31, v28, s[96:97]
	v_cndmask_b32_e64 v29, v29, v32, s[96:97]
	v_perm_b32 v28, v29, v28, s98
	global_store_dword v[26:27], v28, off offset:2816
	v_bfe_u32 v28, v115, 16, 1
	v_bfe_u32 v29, v116, 16, 1
	v_add3_u32 v28, v115, v28, s42
	v_add3_u32 v29, v116, v29, s42
	s_nop 1
	v_mov_b32_dpp v31, v29 quad_perm:[1,0,3,2] row_mask:0xf bank_mask:0xf
	v_mov_b32_dpp v32, v28 quad_perm:[1,0,3,2] row_mask:0xf bank_mask:0xf
	v_cndmask_b32_e64 v28, v31, v28, s[96:97]
	v_cndmask_b32_e64 v29, v29, v32, s[96:97]
	v_perm_b32 v28, v29, v28, s98
	global_store_dword v[26:27], v28, off offset:3072
	v_bfe_u32 v28, v117, 16, 1
	v_bfe_u32 v29, v118, 16, 1
	v_add3_u32 v28, v117, v28, s42
	v_add3_u32 v29, v118, v29, s42
	s_nop 1
	v_mov_b32_dpp v31, v29 quad_perm:[1,0,3,2] row_mask:0xf bank_mask:0xf
	v_mov_b32_dpp v32, v28 quad_perm:[1,0,3,2] row_mask:0xf bank_mask:0xf
	v_cndmask_b32_e64 v28, v31, v28, s[96:97]
	v_cndmask_b32_e64 v29, v29, v32, s[96:97]
	v_perm_b32 v28, v29, v28, s98
	global_store_dword v[26:27], v28, off offset:3328
	v_bfe_u32 v28, v119, 16, 1
	v_bfe_u32 v29, v120, 16, 1
	v_add3_u32 v28, v119, v28, s42
	v_add3_u32 v29, v120, v29, s42
	s_nop 1
	v_mov_b32_dpp v31, v29 quad_perm:[1,0,3,2] row_mask:0xf bank_mask:0xf
	v_mov_b32_dpp v32, v28 quad_perm:[1,0,3,2] row_mask:0xf bank_mask:0xf
	v_cndmask_b32_e64 v28, v31, v28, s[96:97]
	v_cndmask_b32_e64 v29, v29, v32, s[96:97]
	v_perm_b32 v28, v29, v28, s98
	global_store_dword v[26:27], v28, off offset:3584
	v_bfe_u32 v28, v121, 16, 1
	v_bfe_u32 v29, v122, 16, 1
	v_add3_u32 v28, v121, v28, s42
	v_add3_u32 v29, v122, v29, s42
	s_nop 1
	v_mov_b32_dpp v31, v29 quad_perm:[1,0,3,2] row_mask:0xf bank_mask:0xf
	v_mov_b32_dpp v32, v28 quad_perm:[1,0,3,2] row_mask:0xf bank_mask:0xf
	v_cndmask_b32_e64 v28, v31, v28, s[96:97]
	v_cndmask_b32_e64 v29, v29, v32, s[96:97]
	v_perm_b32 v28, v29, v28, s98
	global_store_dword v[26:27], v28, off offset:3840
	s_movk_i32 s0, 0x1000
	v_add_co_u32_e32 v26, vcc, s0, v26
	s_nop 0
	v_addc_co_u32_e32 v27, vcc, 0, v27, vcc
	v_bfe_u32 v28, v123, 16, 1
	v_bfe_u32 v29, v124, 16, 1
	v_add3_u32 v28, v123, v28, s42
	v_add3_u32 v29, v124, v29, s42
	s_nop 1
	v_mov_b32_dpp v31, v29 quad_perm:[1,0,3,2] row_mask:0xf bank_mask:0xf
	v_mov_b32_dpp v32, v28 quad_perm:[1,0,3,2] row_mask:0xf bank_mask:0xf
	v_cndmask_b32_e64 v28, v31, v28, s[96:97]
	v_cndmask_b32_e64 v29, v29, v32, s[96:97]
	v_perm_b32 v28, v29, v28, s98
	global_store_dword v[26:27], v28, off
	v_bfe_u32 v28, v125, 16, 1
	v_bfe_u32 v29, v126, 16, 1
	v_add3_u32 v28, v125, v28, s42
	v_add3_u32 v29, v126, v29, s42
	s_nop 1
	v_mov_b32_dpp v31, v29 quad_perm:[1,0,3,2] row_mask:0xf bank_mask:0xf
	v_mov_b32_dpp v32, v28 quad_perm:[1,0,3,2] row_mask:0xf bank_mask:0xf
	v_cndmask_b32_e64 v28, v31, v28, s[96:97]
	v_cndmask_b32_e64 v29, v29, v32, s[96:97]
	v_perm_b32 v28, v29, v28, s98
	global_store_dword v[26:27], v28, off offset:256
	v_bfe_u32 v28, v127, 16, 1
	v_bfe_u32 v29, v133, 16, 1
	v_add3_u32 v28, v127, v28, s42
	v_add3_u32 v29, v133, v29, s42
	s_nop 1
	v_mov_b32_dpp v31, v29 quad_perm:[1,0,3,2] row_mask:0xf bank_mask:0xf
	v_mov_b32_dpp v32, v28 quad_perm:[1,0,3,2] row_mask:0xf bank_mask:0xf
	v_cndmask_b32_e64 v28, v31, v28, s[96:97]
	v_cndmask_b32_e64 v29, v29, v32, s[96:97]
	v_perm_b32 v28, v29, v28, s98
	global_store_dword v[26:27], v28, off offset:512
	v_bfe_u32 v28, v134, 16, 1
	v_bfe_u32 v29, v135, 16, 1
	v_add3_u32 v28, v134, v28, s42
	v_add3_u32 v29, v135, v29, s42
	s_nop 1
	v_mov_b32_dpp v31, v29 quad_perm:[1,0,3,2] row_mask:0xf bank_mask:0xf
	v_mov_b32_dpp v32, v28 quad_perm:[1,0,3,2] row_mask:0xf bank_mask:0xf
	v_cndmask_b32_e64 v28, v31, v28, s[96:97]
	v_cndmask_b32_e64 v29, v29, v32, s[96:97]
	v_perm_b32 v28, v29, v28, s98
	global_store_dword v[26:27], v28, off offset:768
	v_bfe_u32 v28, v136, 16, 1
	v_bfe_u32 v29, v137, 16, 1
	v_add3_u32 v28, v136, v28, s42
	v_add3_u32 v29, v137, v29, s42
	s_nop 1
	v_mov_b32_dpp v31, v29 quad_perm:[1,0,3,2] row_mask:0xf bank_mask:0xf
	v_mov_b32_dpp v32, v28 quad_perm:[1,0,3,2] row_mask:0xf bank_mask:0xf
	v_cndmask_b32_e64 v28, v31, v28, s[96:97]
	v_cndmask_b32_e64 v29, v29, v32, s[96:97]
	v_perm_b32 v28, v29, v28, s98
	global_store_dword v[26:27], v28, off offset:1024
	v_bfe_u32 v28, v138, 16, 1
	v_bfe_u32 v29, v139, 16, 1
	v_add3_u32 v28, v138, v28, s42
	v_add3_u32 v29, v139, v29, s42
	s_nop 1
	v_mov_b32_dpp v31, v29 quad_perm:[1,0,3,2] row_mask:0xf bank_mask:0xf
	v_mov_b32_dpp v32, v28 quad_perm:[1,0,3,2] row_mask:0xf bank_mask:0xf
	v_cndmask_b32_e64 v28, v31, v28, s[96:97]
	v_cndmask_b32_e64 v29, v29, v32, s[96:97]
	v_perm_b32 v28, v29, v28, s98
	global_store_dword v[26:27], v28, off offset:1280
	v_bfe_u32 v28, v140, 16, 1
	v_bfe_u32 v29, v141, 16, 1
	v_add3_u32 v28, v140, v28, s42
	v_add3_u32 v29, v141, v29, s42
	s_nop 1
	v_mov_b32_dpp v31, v29 quad_perm:[1,0,3,2] row_mask:0xf bank_mask:0xf
	v_mov_b32_dpp v32, v28 quad_perm:[1,0,3,2] row_mask:0xf bank_mask:0xf
	v_cndmask_b32_e64 v28, v31, v28, s[96:97]
	v_cndmask_b32_e64 v29, v29, v32, s[96:97]
	v_perm_b32 v28, v29, v28, s98
	global_store_dword v[26:27], v28, off offset:1536
	v_bfe_u32 v28, v142, 16, 1
	v_bfe_u32 v29, v143, 16, 1
	v_add3_u32 v28, v142, v28, s42
	v_add3_u32 v29, v143, v29, s42
	s_nop 1
	v_mov_b32_dpp v31, v29 quad_perm:[1,0,3,2] row_mask:0xf bank_mask:0xf
	v_mov_b32_dpp v32, v28 quad_perm:[1,0,3,2] row_mask:0xf bank_mask:0xf
	v_cndmask_b32_e64 v28, v31, v28, s[96:97]
	v_cndmask_b32_e64 v29, v29, v32, s[96:97]
	v_perm_b32 v28, v29, v28, s98
	global_store_dword v[26:27], v28, off offset:1792
	v_bfe_u32 v28, v144, 16, 1
	v_bfe_u32 v29, v145, 16, 1
	v_add3_u32 v28, v144, v28, s42
	v_add3_u32 v29, v145, v29, s42
	s_nop 1
	v_mov_b32_dpp v31, v29 quad_perm:[1,0,3,2] row_mask:0xf bank_mask:0xf
	v_mov_b32_dpp v32, v28 quad_perm:[1,0,3,2] row_mask:0xf bank_mask:0xf
	v_cndmask_b32_e64 v28, v31, v28, s[96:97]
	v_cndmask_b32_e64 v29, v29, v32, s[96:97]
	v_perm_b32 v28, v29, v28, s98
	global_store_dword v[26:27], v28, off offset:2048
	v_bfe_u32 v28, v146, 16, 1
	v_bfe_u32 v29, v147, 16, 1
	v_add3_u32 v28, v146, v28, s42
	v_add3_u32 v29, v147, v29, s42
	s_nop 1
	v_mov_b32_dpp v31, v29 quad_perm:[1,0,3,2] row_mask:0xf bank_mask:0xf
	v_mov_b32_dpp v32, v28 quad_perm:[1,0,3,2] row_mask:0xf bank_mask:0xf
	v_cndmask_b32_e64 v28, v31, v28, s[96:97]
	v_cndmask_b32_e64 v29, v29, v32, s[96:97]
	v_perm_b32 v28, v29, v28, s98
	global_store_dword v[26:27], v28, off offset:2304
	v_bfe_u32 v28, v148, 16, 1
	v_bfe_u32 v29, v149, 16, 1
	v_add3_u32 v28, v148, v28, s42
	v_add3_u32 v29, v149, v29, s42
	s_nop 1
	v_mov_b32_dpp v31, v29 quad_perm:[1,0,3,2] row_mask:0xf bank_mask:0xf
	v_mov_b32_dpp v32, v28 quad_perm:[1,0,3,2] row_mask:0xf bank_mask:0xf
	v_cndmask_b32_e64 v28, v31, v28, s[96:97]
	v_cndmask_b32_e64 v29, v29, v32, s[96:97]
	v_perm_b32 v28, v29, v28, s98
	global_store_dword v[26:27], v28, off offset:2560
	v_bfe_u32 v28, v150, 16, 1
	v_bfe_u32 v29, v151, 16, 1
	v_add3_u32 v28, v150, v28, s42
	v_add3_u32 v29, v151, v29, s42
	s_nop 1
	v_mov_b32_dpp v31, v29 quad_perm:[1,0,3,2] row_mask:0xf bank_mask:0xf
	v_mov_b32_dpp v32, v28 quad_perm:[1,0,3,2] row_mask:0xf bank_mask:0xf
	v_cndmask_b32_e64 v28, v31, v28, s[96:97]
	v_cndmask_b32_e64 v29, v29, v32, s[96:97]
	v_perm_b32 v28, v29, v28, s98
	global_store_dword v[26:27], v28, off offset:2816
	v_bfe_u32 v28, v152, 16, 1
	v_bfe_u32 v29, v153, 16, 1
	v_add3_u32 v28, v152, v28, s42
	v_add3_u32 v29, v153, v29, s42
	s_nop 1
	v_mov_b32_dpp v31, v29 quad_perm:[1,0,3,2] row_mask:0xf bank_mask:0xf
	v_mov_b32_dpp v32, v28 quad_perm:[1,0,3,2] row_mask:0xf bank_mask:0xf
	v_cndmask_b32_e64 v28, v31, v28, s[96:97]
	v_cndmask_b32_e64 v29, v29, v32, s[96:97]
	v_perm_b32 v28, v29, v28, s98
	global_store_dword v[26:27], v28, off offset:3072
	v_bfe_u32 v28, v154, 16, 1
	v_bfe_u32 v29, v155, 16, 1
	v_add3_u32 v28, v154, v28, s42
	v_add3_u32 v29, v155, v29, s42
	s_nop 1
	v_mov_b32_dpp v31, v29 quad_perm:[1,0,3,2] row_mask:0xf bank_mask:0xf
	v_mov_b32_dpp v32, v28 quad_perm:[1,0,3,2] row_mask:0xf bank_mask:0xf
	v_cndmask_b32_e64 v28, v31, v28, s[96:97]
	v_cndmask_b32_e64 v29, v29, v32, s[96:97]
	v_perm_b32 v28, v29, v28, s98
	global_store_dword v[26:27], v28, off offset:3328
	v_bfe_u32 v28, v24, 16, 1
	v_bfe_u32 v29, v25, 16, 1
	v_add3_u32 v28, v24, v28, s42
	v_add3_u32 v29, v25, v29, s42
	s_nop 1
	v_mov_b32_dpp v31, v29 quad_perm:[1,0,3,2] row_mask:0xf bank_mask:0xf
	v_mov_b32_dpp v32, v28 quad_perm:[1,0,3,2] row_mask:0xf bank_mask:0xf
	v_cndmask_b32_e64 v28, v31, v28, s[96:97]
	v_cndmask_b32_e64 v29, v29, v32, s[96:97]
	v_perm_b32 v28, v29, v28, s98
	global_store_dword v[26:27], v28, off offset:3584
	v_bfe_u32 v28, v82, 16, 1
	v_bfe_u32 v29, v30, 16, 1
	v_add3_u32 v28, v82, v28, s42
	v_add3_u32 v29, v30, v29, s42
	s_nop 1
	v_mov_b32_dpp v31, v29 quad_perm:[1,0,3,2] row_mask:0xf bank_mask:0xf
	v_mov_b32_dpp v32, v28 quad_perm:[1,0,3,2] row_mask:0xf bank_mask:0xf
	v_cndmask_b32_e64 v28, v31, v28, s[96:97]
	v_cndmask_b32_e64 v29, v29, v32, s[96:97]
	v_perm_b32 v28, v29, v28, s98
	global_store_dword v[26:27], v28, off offset:3840
	v_readlane_b32 s0, v252, 26
	s_add_i32 s12, s0, s12
	s_cmpk_lt_i32 s12, 0x880
	s_cbranch_scc0 .LBB0_1318
